# RG-LRU scan rewritten: gate matvecs as bf16 MFMA per 16 steps, gates through LDS to lane=channel scan
# speedup vs baseline: 1.2110x; 1.0414x over previous
; DI bf16_t f2bf(float x) { unsigned u = __float_as_uint(x); u += 0x7fffu + ((u >> 16) & 1u); return (bf16_t)(u >> 16); }
; template <bool PASS2>
; DI void lru_item(const Params& p, int l, int item, int lane, const bf16_t* xl, float* wxs) {
;   const int b = item / (8 * NCHL), blk = (item / NCHL) % 8, c = item % NCHL;
;   const int ch = blk * 64 + lane;
;   unsigned wpa[32], wpx[32];
;   {
;     const float* pa = p.in[I_LRU_W_A] + ((size_t)l * 8 + blk) * 4096;
;     const float* px = p.in[I_LRU_W_X] + ((size_t)l * 8 + blk) * 4096;
;     int lo_ = lane; asm volatile("" : "+v"(lo_));
; #pragma unroll
;     for (int m = 0; m < 32; m++) {
;       wpa[m] = (unsigned)f2bf(pa[(2 * m) * 64 + lo_]) | ((unsigned)f2bf(pa[(2 * m + 1) * 64 + lo_]) << 16);
;       wpx[m] = (unsigned)f2bf(px[(2 * m) * 64 + lo_]) | ((unsigned)f2bf(px[(2 * m + 1) * 64 + lo_]) << 16);
;       if ((m & 7) == 7) asm volatile("" ::: "memory");
;     }
;   }
;   const float* cw = p.in[I_LRU_CONV_W] + (size_t)l * 4 * 512;
;   const float cw0 = cw[ch], cw1 = cw[512 + ch], cw2 = cw[1024 + ch], cw3 = cw[1536 + ch];
;   const float cb = p.in[I_LRU_CONV_B][l * 512 + ch];
;   const float ba = p.in[I_LRU_B_A][l * 512 + ch], bx = p.in[I_LRU_B_X][l * 512 + ch];
; template <int Q>
; DI void run_phase(const Params& p, int l, bf16_t* sm) {
;     ...
;     for (int it = wave * gridDim.x + blockIdx.x; it < 16 * NCHL; it += gridDim.x * 4) lru_item<false>(p, l, __builtin_amdgcn_readfirstlane(it), lane, xlbuf, (float*)sm + wave * 4096);
.LBB0_513:
	s_or_b64 exec, exec, s[0:1]
	s_add_u32 s0, s60, 0x3158000
	s_addc_u32 s1, s61, 0
	v_writelane_b32 v254, s0, 61
	v_mov_b32_e32 v16, v210
	s_waitcnt lgkmcnt(0)
	v_mov_b32_e32 v0, v210
	v_writelane_b32 v254, s1, 62
	s_add_u32 s0, s60, 0x13558000
	s_addc_u32 s1, s61, 0
	v_writelane_b32 v254, s0, 63
	s_barrier
	s_nop 0
	v_writelane_b32 v255, s1, 0
	v_bfe_u32 v17, v0, 6, 2
	v_readlane_b32 s0, v252, 1
	v_and_b32_e32 v81, 63, v16
	v_readlane_b32 s1, v252, 2
	v_mul_lo_u32 v0, v17, s0
	v_add_u32_e32 v18, s33, v0
	s_movk_i32 s0, 0x800
	v_cmp_gt_i32_e32 vcc, s0, v18
	s_and_saveexec_b64 s[4:5], vcc
	s_cbranch_execz .LBB0_522
	v_readlane_b32 s14, v252, 3
	v_readlane_b32 s15, v252, 4
	v_readlane_b32 s13, v252, 1
	v_readfirstlane_b32 s12, v18
	s_sub_u32 s14, s14, 0x180
	s_subb_u32 s15, s15, 0
	s_lshl_b32 s13, s13, 2
	s_load_dwordx2 s[2:3], s[14:15], 0x170
	s_waitcnt lgkmcnt(0)
	s_add_u32 s6, s2, 0x13558000
	s_addc_u32 s7, s3, 0
.Llrua1_item:
	s_bfe_u32 s16, s12, 0x30007
	v_and_b32_e32 v78, 63, v210
	v_lshl_add_u32 v78, s16, 6, v78
	v_lshlrev_b32_e32 v72, 1, v78
	v_lshlrev_b32_e32 v79, 2, v78
	v_and_b32_e32 v80, 63, v210
	v_lshrrev_b32_e32 v146, 4, v80
	v_and_b32_e32 v80, 15, v80
	v_lshlrev_b32_e32 v76, 11, v146
	v_lshl_add_u32 v76, v80, 2, v76
	v_add_u32_e32 v77, 0x2000, v76
	s_load_dwordx4 s[16:19], s[14:15], 0x100
	s_waitcnt lgkmcnt(0)
	s_add_u32 s0, s16, 0x0
	s_addc_u32 s1, s17, 0
	global_load_dword v8, v79, s[0:1]
	global_load_dword v9, v79, s[0:1] offset:2048
	s_add_u32 s0, s0, 0x1000
	s_addc_u32 s1, s1, 0
	global_load_dword v10, v79, s[0:1]
	global_load_dword v11, v79, s[0:1] offset:2048
	s_add_u32 s0, s18, 0x0
	s_addc_u32 s1, s19, 0
	global_load_dword v12, v79, s[0:1]
	s_load_dwordx4 s[16:19], s[14:15], 0x110
	s_waitcnt lgkmcnt(0)
	s_add_u32 s0, s18, 0x0
	s_addc_u32 s1, s19, 0
	global_load_dword v13, v79, s[0:1]
	s_bfe_u32 s20, s12, 0x30007
	s_add_u32 s20, s20, 0
	s_lshl_b32 s20, s20, 14
	s_add_u32 s10, s16, s20
	s_addc_u32 s11, s17, 0
	s_load_dwordx4 s[16:19], s[14:15], 0x120
	s_mov_b32 s0, 0xffff0000
	s_movk_i32 s1, 0x7fff
	global_load_dword v20, v76, s[10:11] offset:0
	global_load_dword v21, v76, s[10:11] offset:256
	global_load_dword v22, v76, s[10:11] offset:512
	global_load_dword v23, v76, s[10:11] offset:768
	global_load_dword v24, v76, s[10:11] offset:1024
	global_load_dword v25, v76, s[10:11] offset:1280
	global_load_dword v26, v76, s[10:11] offset:1536
	global_load_dword v27, v76, s[10:11] offset:1792
	global_load_dword v28, v76, s[10:11] offset:64
	global_load_dword v29, v76, s[10:11] offset:320
	global_load_dword v30, v76, s[10:11] offset:576
	global_load_dword v31, v76, s[10:11] offset:832
	global_load_dword v32, v76, s[10:11] offset:1088
	global_load_dword v33, v76, s[10:11] offset:1344
	global_load_dword v34, v76, s[10:11] offset:1600
	global_load_dword v35, v76, s[10:11] offset:1856
	global_load_dword v36, v76, s[10:11] offset:128
	global_load_dword v37, v76, s[10:11] offset:384
	global_load_dword v38, v76, s[10:11] offset:640
	global_load_dword v39, v76, s[10:11] offset:896
	global_load_dword v40, v76, s[10:11] offset:1152
	global_load_dword v41, v76, s[10:11] offset:1408
	global_load_dword v42, v76, s[10:11] offset:1664
	global_load_dword v43, v76, s[10:11] offset:1920
	global_load_dword v44, v76, s[10:11] offset:192
	global_load_dword v45, v76, s[10:11] offset:448
	global_load_dword v46, v76, s[10:11] offset:704
	global_load_dword v47, v76, s[10:11] offset:960
	global_load_dword v48, v76, s[10:11] offset:1216
	global_load_dword v49, v76, s[10:11] offset:1472
	global_load_dword v50, v76, s[10:11] offset:1728
	global_load_dword v51, v76, s[10:11] offset:1984
	global_load_dword v52, v77, s[10:11] offset:0
	global_load_dword v53, v77, s[10:11] offset:256
	global_load_dword v54, v77, s[10:11] offset:512
	global_load_dword v55, v77, s[10:11] offset:768
	global_load_dword v56, v77, s[10:11] offset:1024
	global_load_dword v57, v77, s[10:11] offset:1280
	global_load_dword v58, v77, s[10:11] offset:1536
	global_load_dword v59, v77, s[10:11] offset:1792
	global_load_dword v60, v77, s[10:11] offset:64
	global_load_dword v61, v77, s[10:11] offset:320
	global_load_dword v62, v77, s[10:11] offset:576
	global_load_dword v63, v77, s[10:11] offset:832
	global_load_dword v64, v77, s[10:11] offset:1088
	global_load_dword v65, v77, s[10:11] offset:1344
	global_load_dword v66, v77, s[10:11] offset:1600
	global_load_dword v67, v77, s[10:11] offset:1856
	global_load_dword v0, v77, s[10:11] offset:128
	global_load_dword v1, v77, s[10:11] offset:384
	global_load_dword v2, v77, s[10:11] offset:640
	global_load_dword v3, v77, s[10:11] offset:896
	global_load_dword v4, v77, s[10:11] offset:1152
	global_load_dword v5, v77, s[10:11] offset:1408
	global_load_dword v6, v77, s[10:11] offset:1664
	global_load_dword v7, v77, s[10:11] offset:1920
	global_load_dword v19, v77, s[10:11] offset:192
	global_load_dword v68, v77, s[10:11] offset:448
	global_load_dword v69, v77, s[10:11] offset:704
	global_load_dword v70, v77, s[10:11] offset:960
	global_load_dword v71, v77, s[10:11] offset:1216
	global_load_dword v80, v77, s[10:11] offset:1472
	global_load_dword v146, v77, s[10:11] offset:1728
	global_load_dword v147, v77, s[10:11] offset:1984
	s_waitcnt vmcnt(0)
; DI bf16_t f2bf(float x) { unsigned u = __float_as_uint(x); u += 0x7fffu + ((u >> 16) & 1u); return (bf16_t)(u >> 16); }
; template <bool PASS2>
; DI void lru_item(const Params& p, int l, int item, int lane, const bf16_t* xl, float* wxs) {
;     ...
;   unsigned wpa[32], wpx[32];
;   {
;     const float* pa = p.in[I_LRU_W_A] + ((size_t)l * 8 + blk) * 4096;
;     const float* px = p.in[I_LRU_W_X] + ((size_t)l * 8 + blk) * 4096;
;     int lo_ = lane; asm volatile("" : "+v"(lo_));
; #pragma unroll
;     for (int m = 0; m < 32; m++) {
;       wpa[m] = (unsigned)f2bf(pa[(2 * m) * 64 + lo_]) | ((unsigned)f2bf(pa[(2 * m + 1) * 64 + lo_]) << 16);
;       wpx[m] = (unsigned)f2bf(px[(2 * m) * 64 + lo_]) | ((unsigned)f2bf(px[(2 * m + 1) * 64 + lo_]) << 16);
;       if ((m & 7) == 7) asm volatile("" ::: "memory");
;     }
;   }
	v_bfe_u32 v73, v20, 16, 1
	v_bfe_u32 v74, v21, 16, 1
	v_add3_u32 v20, v20, v73, s1
	v_add3_u32 v21, v21, v74, s1
	v_lshrrev_b32_e32 v20, 16, v20
	v_and_or_b32 v82, v21, s0, v20
	v_bfe_u32 v73, v22, 16, 1
	v_bfe_u32 v74, v23, 16, 1
	v_add3_u32 v22, v22, v73, s1
	v_add3_u32 v23, v23, v74, s1
	v_lshrrev_b32_e32 v22, 16, v22
	v_and_or_b32 v83, v23, s0, v22
	v_bfe_u32 v73, v24, 16, 1
	v_bfe_u32 v74, v25, 16, 1
	v_add3_u32 v24, v24, v73, s1
	v_add3_u32 v25, v25, v74, s1
	v_lshrrev_b32_e32 v24, 16, v24
	v_and_or_b32 v84, v25, s0, v24
	v_bfe_u32 v73, v26, 16, 1
	v_bfe_u32 v74, v27, 16, 1
	v_add3_u32 v26, v26, v73, s1
	v_add3_u32 v27, v27, v74, s1
	v_lshrrev_b32_e32 v26, 16, v26
	v_and_or_b32 v85, v27, s0, v26
	v_bfe_u32 v73, v28, 16, 1
	v_bfe_u32 v74, v29, 16, 1
	v_add3_u32 v28, v28, v73, s1
	v_add3_u32 v29, v29, v74, s1
	v_lshrrev_b32_e32 v28, 16, v28
	v_and_or_b32 v86, v29, s0, v28
	v_bfe_u32 v73, v30, 16, 1
	v_bfe_u32 v74, v31, 16, 1
	v_add3_u32 v30, v30, v73, s1
	v_add3_u32 v31, v31, v74, s1
	v_lshrrev_b32_e32 v30, 16, v30
	v_and_or_b32 v87, v31, s0, v30
	v_bfe_u32 v73, v32, 16, 1
	v_bfe_u32 v74, v33, 16, 1
	v_add3_u32 v32, v32, v73, s1
	v_add3_u32 v33, v33, v74, s1
	v_lshrrev_b32_e32 v32, 16, v32
	v_and_or_b32 v88, v33, s0, v32
	v_bfe_u32 v73, v34, 16, 1
	v_bfe_u32 v74, v35, 16, 1
	v_add3_u32 v34, v34, v73, s1
	v_add3_u32 v35, v35, v74, s1
	v_lshrrev_b32_e32 v34, 16, v34
	v_and_or_b32 v89, v35, s0, v34
	v_bfe_u32 v73, v36, 16, 1
	v_bfe_u32 v74, v37, 16, 1
	v_add3_u32 v36, v36, v73, s1
	v_add3_u32 v37, v37, v74, s1
	v_lshrrev_b32_e32 v36, 16, v36
	v_and_or_b32 v90, v37, s0, v36
	v_bfe_u32 v73, v38, 16, 1
	v_bfe_u32 v74, v39, 16, 1
	v_add3_u32 v38, v38, v73, s1
	v_add3_u32 v39, v39, v74, s1
	v_lshrrev_b32_e32 v38, 16, v38
	v_and_or_b32 v91, v39, s0, v38
	v_bfe_u32 v73, v40, 16, 1
	v_bfe_u32 v74, v41, 16, 1
	v_add3_u32 v40, v40, v73, s1
	v_add3_u32 v41, v41, v74, s1
	v_lshrrev_b32_e32 v40, 16, v40
	v_and_or_b32 v92, v41, s0, v40
	v_bfe_u32 v73, v42, 16, 1
	v_bfe_u32 v74, v43, 16, 1
	v_add3_u32 v42, v42, v73, s1
	v_add3_u32 v43, v43, v74, s1
	v_lshrrev_b32_e32 v42, 16, v42
	v_and_or_b32 v93, v43, s0, v42
	v_bfe_u32 v73, v44, 16, 1
	v_bfe_u32 v74, v45, 16, 1
	v_add3_u32 v44, v44, v73, s1
	v_add3_u32 v45, v45, v74, s1
	v_lshrrev_b32_e32 v44, 16, v44
	v_and_or_b32 v94, v45, s0, v44
	v_bfe_u32 v73, v46, 16, 1
	v_bfe_u32 v74, v47, 16, 1
	v_add3_u32 v46, v46, v73, s1
	v_add3_u32 v47, v47, v74, s1
	v_lshrrev_b32_e32 v46, 16, v46
	v_and_or_b32 v95, v47, s0, v46
	v_bfe_u32 v73, v48, 16, 1
	v_bfe_u32 v74, v49, 16, 1
	v_add3_u32 v48, v48, v73, s1
	v_add3_u32 v49, v49, v74, s1
	v_lshrrev_b32_e32 v48, 16, v48
	v_and_or_b32 v96, v49, s0, v48
	v_bfe_u32 v73, v50, 16, 1
	v_bfe_u32 v74, v51, 16, 1
	v_add3_u32 v50, v50, v73, s1
	v_add3_u32 v51, v51, v74, s1
	v_lshrrev_b32_e32 v50, 16, v50
	v_and_or_b32 v97, v51, s0, v50
	v_bfe_u32 v73, v52, 16, 1
	v_bfe_u32 v74, v53, 16, 1
	v_add3_u32 v52, v52, v73, s1
	v_add3_u32 v53, v53, v74, s1
	v_lshrrev_b32_e32 v52, 16, v52
	v_and_or_b32 v114, v53, s0, v52
	v_bfe_u32 v73, v54, 16, 1
	v_bfe_u32 v74, v55, 16, 1
	v_add3_u32 v54, v54, v73, s1
	v_add3_u32 v55, v55, v74, s1
	v_lshrrev_b32_e32 v54, 16, v54
	v_and_or_b32 v115, v55, s0, v54
	v_bfe_u32 v73, v56, 16, 1
	v_bfe_u32 v74, v57, 16, 1
	v_add3_u32 v56, v56, v73, s1
	v_add3_u32 v57, v57, v74, s1
	v_lshrrev_b32_e32 v56, 16, v56
	v_and_or_b32 v116, v57, s0, v56
	v_bfe_u32 v73, v58, 16, 1
	v_bfe_u32 v74, v59, 16, 1
	v_add3_u32 v58, v58, v73, s1
	v_add3_u32 v59, v59, v74, s1
	v_lshrrev_b32_e32 v58, 16, v58
	v_and_or_b32 v117, v59, s0, v58
	v_bfe_u32 v73, v60, 16, 1
	v_bfe_u32 v74, v61, 16, 1
	v_add3_u32 v60, v60, v73, s1
	v_add3_u32 v61, v61, v74, s1
	v_lshrrev_b32_e32 v60, 16, v60
	v_and_or_b32 v118, v61, s0, v60
	v_bfe_u32 v73, v62, 16, 1
	v_bfe_u32 v74, v63, 16, 1
	v_add3_u32 v62, v62, v73, s1
	v_add3_u32 v63, v63, v74, s1
	v_lshrrev_b32_e32 v62, 16, v62
	v_and_or_b32 v119, v63, s0, v62
	v_bfe_u32 v73, v64, 16, 1
	v_bfe_u32 v74, v65, 16, 1
	v_add3_u32 v64, v64, v73, s1
	v_add3_u32 v65, v65, v74, s1
	v_lshrrev_b32_e32 v64, 16, v64
	v_and_or_b32 v120, v65, s0, v64
	v_bfe_u32 v73, v66, 16, 1
	v_bfe_u32 v74, v67, 16, 1
	v_add3_u32 v66, v66, v73, s1
	v_add3_u32 v67, v67, v74, s1
	v_lshrrev_b32_e32 v66, 16, v66
	v_and_or_b32 v121, v67, s0, v66
	v_bfe_u32 v73, v0, 16, 1
	v_bfe_u32 v74, v1, 16, 1
	v_add3_u32 v0, v0, v73, s1
	v_add3_u32 v1, v1, v74, s1
	v_lshrrev_b32_e32 v0, 16, v0
	v_and_or_b32 v122, v1, s0, v0
	v_bfe_u32 v73, v2, 16, 1
	v_bfe_u32 v74, v3, 16, 1
	v_add3_u32 v2, v2, v73, s1
	v_add3_u32 v3, v3, v74, s1
	v_lshrrev_b32_e32 v2, 16, v2
	v_and_or_b32 v123, v3, s0, v2
	v_bfe_u32 v73, v4, 16, 1
	v_bfe_u32 v74, v5, 16, 1
	v_add3_u32 v4, v4, v73, s1
	v_add3_u32 v5, v5, v74, s1
	v_lshrrev_b32_e32 v4, 16, v4
	v_and_or_b32 v124, v5, s0, v4
	v_bfe_u32 v73, v6, 16, 1
	v_bfe_u32 v74, v7, 16, 1
	v_add3_u32 v6, v6, v73, s1
	v_add3_u32 v7, v7, v74, s1
	v_lshrrev_b32_e32 v6, 16, v6
	v_and_or_b32 v125, v7, s0, v6
	v_bfe_u32 v73, v19, 16, 1
	v_bfe_u32 v74, v68, 16, 1
	v_add3_u32 v19, v19, v73, s1
	v_add3_u32 v68, v68, v74, s1
	v_lshrrev_b32_e32 v19, 16, v19
	v_and_or_b32 v126, v68, s0, v19
	v_bfe_u32 v73, v69, 16, 1
	v_bfe_u32 v74, v70, 16, 1
	v_add3_u32 v69, v69, v73, s1
	v_add3_u32 v70, v70, v74, s1
	v_lshrrev_b32_e32 v69, 16, v69
	v_and_or_b32 v127, v70, s0, v69
	v_bfe_u32 v73, v71, 16, 1
	v_bfe_u32 v74, v80, 16, 1
	v_add3_u32 v71, v71, v73, s1
	v_add3_u32 v80, v80, v74, s1
	v_lshrrev_b32_e32 v71, 16, v71
	v_and_or_b32 v128, v80, s0, v71
	v_bfe_u32 v73, v146, 16, 1
	v_bfe_u32 v74, v147, 16, 1
	v_add3_u32 v146, v146, v73, s1
	v_add3_u32 v147, v147, v74, s1
	v_lshrrev_b32_e32 v146, 16, v146
	v_and_or_b32 v129, v147, s0, v146
	s_waitcnt lgkmcnt(0)
; DI bf16_t f2bf(float x) { unsigned u = __float_as_uint(x); u += 0x7fffu + ((u >> 16) & 1u); return (bf16_t)(u >> 16); }
; template <bool PASS2>
; DI void lru_item(const Params& p, int l, int item, int lane, const bf16_t* xl, float* wxs) {
;     ...
;   unsigned wpa[32], wpx[32];
;   {
;     const float* pa = p.in[I_LRU_W_A] + ((size_t)l * 8 + blk) * 4096;
;     const float* px = p.in[I_LRU_W_X] + ((size_t)l * 8 + blk) * 4096;
;     int lo_ = lane; asm volatile("" : "+v"(lo_));
; #pragma unroll
;     for (int m = 0; m < 32; m++) {
;       wpa[m] = (unsigned)f2bf(pa[(2 * m) * 64 + lo_]) | ((unsigned)f2bf(pa[(2 * m + 1) * 64 + lo_]) << 16);
;       wpx[m] = (unsigned)f2bf(px[(2 * m) * 64 + lo_]) | ((unsigned)f2bf(px[(2 * m + 1) * 64 + lo_]) << 16);
;       if ((m & 7) == 7) asm volatile("" ::: "memory");
;     }
;   }
	s_add_u32 s10, s16, s20
	s_addc_u32 s11, s17, 0
	global_load_dword v20, v76, s[10:11] offset:0
	global_load_dword v21, v76, s[10:11] offset:256
	global_load_dword v22, v76, s[10:11] offset:512
	global_load_dword v23, v76, s[10:11] offset:768
	global_load_dword v24, v76, s[10:11] offset:1024
	global_load_dword v25, v76, s[10:11] offset:1280
	global_load_dword v26, v76, s[10:11] offset:1536
	global_load_dword v27, v76, s[10:11] offset:1792
	global_load_dword v28, v76, s[10:11] offset:64
	global_load_dword v29, v76, s[10:11] offset:320
	global_load_dword v30, v76, s[10:11] offset:576
	global_load_dword v31, v76, s[10:11] offset:832
	global_load_dword v32, v76, s[10:11] offset:1088
	global_load_dword v33, v76, s[10:11] offset:1344
	global_load_dword v34, v76, s[10:11] offset:1600
	global_load_dword v35, v76, s[10:11] offset:1856
	global_load_dword v36, v76, s[10:11] offset:128
	global_load_dword v37, v76, s[10:11] offset:384
	global_load_dword v38, v76, s[10:11] offset:640
	global_load_dword v39, v76, s[10:11] offset:896
	global_load_dword v40, v76, s[10:11] offset:1152
	global_load_dword v41, v76, s[10:11] offset:1408
	global_load_dword v42, v76, s[10:11] offset:1664
	global_load_dword v43, v76, s[10:11] offset:1920
	global_load_dword v44, v76, s[10:11] offset:192
	global_load_dword v45, v76, s[10:11] offset:448
	global_load_dword v46, v76, s[10:11] offset:704
	global_load_dword v47, v76, s[10:11] offset:960
	global_load_dword v48, v76, s[10:11] offset:1216
	global_load_dword v49, v76, s[10:11] offset:1472
	global_load_dword v50, v76, s[10:11] offset:1728
	global_load_dword v51, v76, s[10:11] offset:1984
	global_load_dword v52, v77, s[10:11] offset:0
	global_load_dword v53, v77, s[10:11] offset:256
	global_load_dword v54, v77, s[10:11] offset:512
	global_load_dword v55, v77, s[10:11] offset:768
	global_load_dword v56, v77, s[10:11] offset:1024
	global_load_dword v57, v77, s[10:11] offset:1280
	global_load_dword v58, v77, s[10:11] offset:1536
	global_load_dword v59, v77, s[10:11] offset:1792
	global_load_dword v60, v77, s[10:11] offset:64
	global_load_dword v61, v77, s[10:11] offset:320
	global_load_dword v62, v77, s[10:11] offset:576
	global_load_dword v63, v77, s[10:11] offset:832
	global_load_dword v64, v77, s[10:11] offset:1088
	global_load_dword v65, v77, s[10:11] offset:1344
	global_load_dword v66, v77, s[10:11] offset:1600
	global_load_dword v67, v77, s[10:11] offset:1856
	global_load_dword v0, v77, s[10:11] offset:128
	global_load_dword v1, v77, s[10:11] offset:384
	global_load_dword v2, v77, s[10:11] offset:640
	global_load_dword v3, v77, s[10:11] offset:896
	global_load_dword v4, v77, s[10:11] offset:1152
	global_load_dword v5, v77, s[10:11] offset:1408
	global_load_dword v6, v77, s[10:11] offset:1664
	global_load_dword v7, v77, s[10:11] offset:1920
	global_load_dword v19, v77, s[10:11] offset:192
	global_load_dword v68, v77, s[10:11] offset:448
	global_load_dword v69, v77, s[10:11] offset:704
	global_load_dword v70, v77, s[10:11] offset:960
	global_load_dword v71, v77, s[10:11] offset:1216
	global_load_dword v80, v77, s[10:11] offset:1472
	global_load_dword v146, v77, s[10:11] offset:1728
	global_load_dword v147, v77, s[10:11] offset:1984
	s_waitcnt vmcnt(0)
	v_bfe_u32 v73, v20, 16, 1
	v_bfe_u32 v74, v21, 16, 1
	v_add3_u32 v20, v20, v73, s1
	v_add3_u32 v21, v21, v74, s1
	v_lshrrev_b32_e32 v20, 16, v20
	v_and_or_b32 v98, v21, s0, v20
	v_bfe_u32 v73, v22, 16, 1
	v_bfe_u32 v74, v23, 16, 1
	v_add3_u32 v22, v22, v73, s1
	v_add3_u32 v23, v23, v74, s1
	v_lshrrev_b32_e32 v22, 16, v22
	v_and_or_b32 v99, v23, s0, v22
	v_bfe_u32 v73, v24, 16, 1
	v_bfe_u32 v74, v25, 16, 1
	v_add3_u32 v24, v24, v73, s1
	v_add3_u32 v25, v25, v74, s1
	v_lshrrev_b32_e32 v24, 16, v24
	v_and_or_b32 v100, v25, s0, v24
	v_bfe_u32 v73, v26, 16, 1
	v_bfe_u32 v74, v27, 16, 1
	v_add3_u32 v26, v26, v73, s1
	v_add3_u32 v27, v27, v74, s1
	v_lshrrev_b32_e32 v26, 16, v26
	v_and_or_b32 v101, v27, s0, v26
	v_bfe_u32 v73, v28, 16, 1
	v_bfe_u32 v74, v29, 16, 1
	v_add3_u32 v28, v28, v73, s1
	v_add3_u32 v29, v29, v74, s1
	v_lshrrev_b32_e32 v28, 16, v28
	v_and_or_b32 v102, v29, s0, v28
	v_bfe_u32 v73, v30, 16, 1
	v_bfe_u32 v74, v31, 16, 1
	v_add3_u32 v30, v30, v73, s1
	v_add3_u32 v31, v31, v74, s1
	v_lshrrev_b32_e32 v30, 16, v30
	v_and_or_b32 v103, v31, s0, v30
	v_bfe_u32 v73, v32, 16, 1
	v_bfe_u32 v74, v33, 16, 1
	v_add3_u32 v32, v32, v73, s1
	v_add3_u32 v33, v33, v74, s1
	v_lshrrev_b32_e32 v32, 16, v32
	v_and_or_b32 v104, v33, s0, v32
	v_bfe_u32 v73, v34, 16, 1
	v_bfe_u32 v74, v35, 16, 1
	v_add3_u32 v34, v34, v73, s1
	v_add3_u32 v35, v35, v74, s1
	v_lshrrev_b32_e32 v34, 16, v34
	v_and_or_b32 v105, v35, s0, v34
	v_bfe_u32 v73, v36, 16, 1
	v_bfe_u32 v74, v37, 16, 1
	v_add3_u32 v36, v36, v73, s1
	v_add3_u32 v37, v37, v74, s1
	v_lshrrev_b32_e32 v36, 16, v36
	v_and_or_b32 v106, v37, s0, v36
	v_bfe_u32 v73, v38, 16, 1
	v_bfe_u32 v74, v39, 16, 1
	v_add3_u32 v38, v38, v73, s1
	v_add3_u32 v39, v39, v74, s1
	v_lshrrev_b32_e32 v38, 16, v38
	v_and_or_b32 v107, v39, s0, v38
	v_bfe_u32 v73, v40, 16, 1
	v_bfe_u32 v74, v41, 16, 1
	v_add3_u32 v40, v40, v73, s1
	v_add3_u32 v41, v41, v74, s1
	v_lshrrev_b32_e32 v40, 16, v40
	v_and_or_b32 v108, v41, s0, v40
	v_bfe_u32 v73, v42, 16, 1
	v_bfe_u32 v74, v43, 16, 1
	v_add3_u32 v42, v42, v73, s1
	v_add3_u32 v43, v43, v74, s1
	v_lshrrev_b32_e32 v42, 16, v42
	v_and_or_b32 v109, v43, s0, v42
	v_bfe_u32 v73, v44, 16, 1
	v_bfe_u32 v74, v45, 16, 1
	v_add3_u32 v44, v44, v73, s1
	v_add3_u32 v45, v45, v74, s1
	v_lshrrev_b32_e32 v44, 16, v44
	v_and_or_b32 v110, v45, s0, v44
	v_bfe_u32 v73, v46, 16, 1
	v_bfe_u32 v74, v47, 16, 1
	v_add3_u32 v46, v46, v73, s1
; DI float bf2f(bf16_t b) { return __uint_as_float(((unsigned)b) << 16); }
; DI float softplusf_(float z) { return fmaxf(z, 0.f) + __logf(1.f + __expf(-fabsf(z))); }
; template <bool PASS2>
; DI void lru_item(const Params& p, int l, int item, int lane, const bf16_t* xl, float* wxs) {
;     ...
;   const float* cw = p.in[I_LRU_CONV_W] + (size_t)l * 4 * 512;
;   const float cw0 = cw[ch], cw1 = cw[512 + ch], cw2 = cw[1024 + ch], cw3 = cw[1536 + ch];
;   const float cb = p.in[I_LRU_CONV_B][l * 512 + ch];
;   const float ba = p.in[I_LRU_B_A][l * 512 + ch], bx = p.in[I_LRU_B_X][l * 512 + ch];
;   const float sp = softplusf_(-p.in[I_LRU_LAM][l * 512 + ch]);
;   const size_t tok0 = (size_t)b * SEQ + (size_t)c * LCL;
;   float x1 = 0.f, x2 = 0.f, x3 = 0.f;
;   if (c > 0) {
;     x1 = bf2f(xl[(tok0 - 1) * 512 + ch]); x2 = bf2f(xl[(tok0 - 2) * 512 + ch]); x3 = bf2f(xl[(tok0 - 3) * 512 + ch]);
;   }
;   float* st = p.lrust + ((size_t)(b * 512 + ch) * NCHL + c) * 2;
;   float hs = PASS2 ? st[1] : 0.f;
;   float aprod = 1.f;
;   float xn = bf2f(xl[tok0 * 512 + ch]);
	v_add3_u32 v47, v47, v74, s1
	v_lshrrev_b32_e32 v46, 16, v46
	v_and_or_b32 v111, v47, s0, v46
	v_bfe_u32 v73, v48, 16, 1
	v_bfe_u32 v74, v49, 16, 1
	v_add3_u32 v48, v48, v73, s1
	v_add3_u32 v49, v49, v74, s1
	v_lshrrev_b32_e32 v48, 16, v48
	v_and_or_b32 v112, v49, s0, v48
	v_bfe_u32 v73, v50, 16, 1
	v_bfe_u32 v74, v51, 16, 1
	v_add3_u32 v50, v50, v73, s1
	v_add3_u32 v51, v51, v74, s1
	v_lshrrev_b32_e32 v50, 16, v50
	v_and_or_b32 v113, v51, s0, v50
	v_bfe_u32 v73, v52, 16, 1
	v_bfe_u32 v74, v53, 16, 1
	v_add3_u32 v52, v52, v73, s1
	v_add3_u32 v53, v53, v74, s1
	v_lshrrev_b32_e32 v52, 16, v52
	v_and_or_b32 v130, v53, s0, v52
	v_bfe_u32 v73, v54, 16, 1
	v_bfe_u32 v74, v55, 16, 1
	v_add3_u32 v54, v54, v73, s1
	v_add3_u32 v55, v55, v74, s1
	v_lshrrev_b32_e32 v54, 16, v54
	v_and_or_b32 v131, v55, s0, v54
	v_bfe_u32 v73, v56, 16, 1
	v_bfe_u32 v74, v57, 16, 1
	v_add3_u32 v56, v56, v73, s1
	v_add3_u32 v57, v57, v74, s1
	v_lshrrev_b32_e32 v56, 16, v56
	v_and_or_b32 v132, v57, s0, v56
	v_bfe_u32 v73, v58, 16, 1
	v_bfe_u32 v74, v59, 16, 1
	v_add3_u32 v58, v58, v73, s1
	v_add3_u32 v59, v59, v74, s1
	v_lshrrev_b32_e32 v58, 16, v58
	v_and_or_b32 v133, v59, s0, v58
	v_bfe_u32 v73, v60, 16, 1
	v_bfe_u32 v74, v61, 16, 1
	v_add3_u32 v60, v60, v73, s1
	v_add3_u32 v61, v61, v74, s1
	v_lshrrev_b32_e32 v60, 16, v60
	v_and_or_b32 v134, v61, s0, v60
	v_bfe_u32 v73, v62, 16, 1
	v_bfe_u32 v74, v63, 16, 1
	v_add3_u32 v62, v62, v73, s1
	v_add3_u32 v63, v63, v74, s1
	v_lshrrev_b32_e32 v62, 16, v62
	v_and_or_b32 v135, v63, s0, v62
	v_bfe_u32 v73, v64, 16, 1
	v_bfe_u32 v74, v65, 16, 1
	v_add3_u32 v64, v64, v73, s1
	v_add3_u32 v65, v65, v74, s1
	v_lshrrev_b32_e32 v64, 16, v64
	v_and_or_b32 v136, v65, s0, v64
	v_bfe_u32 v73, v66, 16, 1
	v_bfe_u32 v74, v67, 16, 1
	v_add3_u32 v66, v66, v73, s1
	v_add3_u32 v67, v67, v74, s1
	v_lshrrev_b32_e32 v66, 16, v66
	v_and_or_b32 v137, v67, s0, v66
	v_bfe_u32 v73, v0, 16, 1
	v_bfe_u32 v74, v1, 16, 1
	v_add3_u32 v0, v0, v73, s1
	v_add3_u32 v1, v1, v74, s1
	v_lshrrev_b32_e32 v0, 16, v0
	v_and_or_b32 v138, v1, s0, v0
	v_bfe_u32 v73, v2, 16, 1
	v_bfe_u32 v74, v3, 16, 1
	v_add3_u32 v2, v2, v73, s1
	v_add3_u32 v3, v3, v74, s1
	v_lshrrev_b32_e32 v2, 16, v2
	v_and_or_b32 v139, v3, s0, v2
	v_bfe_u32 v73, v4, 16, 1
	v_bfe_u32 v74, v5, 16, 1
	v_add3_u32 v4, v4, v73, s1
	v_add3_u32 v5, v5, v74, s1
	v_lshrrev_b32_e32 v4, 16, v4
	v_and_or_b32 v140, v5, s0, v4
	v_bfe_u32 v73, v6, 16, 1
	v_bfe_u32 v74, v7, 16, 1
	v_add3_u32 v6, v6, v73, s1
	v_add3_u32 v7, v7, v74, s1
	v_lshrrev_b32_e32 v6, 16, v6
	v_and_or_b32 v141, v7, s0, v6
	v_bfe_u32 v73, v19, 16, 1
	v_bfe_u32 v74, v68, 16, 1
	v_add3_u32 v19, v19, v73, s1
	v_add3_u32 v68, v68, v74, s1
	v_lshrrev_b32_e32 v19, 16, v19
	v_and_or_b32 v142, v68, s0, v19
	v_bfe_u32 v73, v69, 16, 1
	v_bfe_u32 v74, v70, 16, 1
	v_add3_u32 v69, v69, v73, s1
	v_add3_u32 v70, v70, v74, s1
	v_lshrrev_b32_e32 v69, 16, v69
	v_and_or_b32 v143, v70, s0, v69
	v_bfe_u32 v73, v71, 16, 1
	v_bfe_u32 v74, v80, 16, 1
	v_add3_u32 v71, v71, v73, s1
	v_add3_u32 v80, v80, v74, s1
	v_lshrrev_b32_e32 v71, 16, v71
	v_and_or_b32 v144, v80, s0, v71
	v_bfe_u32 v73, v146, 16, 1
	v_bfe_u32 v74, v147, 16, 1
	v_add3_u32 v146, v146, v73, s1
	v_add3_u32 v147, v147, v74, s1
	v_lshrrev_b32_e32 v146, 16, v146
	v_and_or_b32 v145, v147, s0, v146
	s_add_u32 s0, s18, 0x0
	s_addc_u32 s1, s19, 0
	global_load_dword v14, v79, s[0:1]
	s_load_dwordx2 s[16:17], s[14:15], 0x130
	s_waitcnt lgkmcnt(0)
	s_add_u32 s0, s16, 0x0
	s_addc_u32 s1, s17, 0
	global_load_dword v15, v79, s[0:1]
	v_and_b32_e32 v80, 63, v210
	v_lshrrev_b32_e32 v146, 6, v210
	v_and_b32_e32 v146, 3, v146
	v_mul_u32_u24_e32 v146, 0x2200, v146
	v_lshl_add_u32 v74, v80, 1, v146
	v_and_b32_e32 v147, 15, v80
	v_lshrrev_b32_e32 v79, 4, v80
	v_mul_u32_u24_e32 v75, 0x90, v147
	v_lshl_add_u32 v75, v79, 4, v75
	v_add_u32_e32 v75, v146, v75
	v_add_u32_e32 v146, 0x8800, v146
	v_mul_u32_u24_e32 v76, 0x210, v79
	v_add_u32_e32 v76, v76, v147
	v_lshl_add_u32 v76, v76, 2, v146
	v_lshl_add_u32 v77, v80, 2, v146
	s_lshr_b32 s19, s12, 10
	s_and_b32 s17, s12, 127
	s_lshl_b32 s18, s19, 14
	s_lshl_b32 s20, s17, 7
	s_add_u32 s18, s18, s20
	s_lshl_b32 s20, s18, 10
	v_add_u32_e32 v73, s20, v72
	v_mov_b32_e32 v69, 0
	v_mov_b32_e32 v70, 0
	v_mov_b32_e32 v71, 0
	v_mov_b32_e32 v19, 0
	v_mov_b32_e32 v68, 1.0
	s_cmp_eq_u32 s17, 0
	s_cbranch_scc1 .Llrua1_nohist
	global_load_ushort v69, v73, s[6:7] offset:-1024
	global_load_ushort v70, v73, s[6:7] offset:-2048
	global_load_ushort v71, v73, s[6:7] offset:-3072
.Llrua1_nohist:
	global_load_ushort v20, v73, s[6:7] offset:0
	global_load_ushort v21, v73, s[6:7] offset:1024
	global_load_ushort v22, v73, s[6:7] offset:2048
	global_load_ushort v23, v73, s[6:7] offset:3072
	v_add_u32_e32 v73, 0x1000, v73
	global_load_ushort v24, v73, s[6:7] offset:0
	global_load_ushort v25, v73, s[6:7] offset:1024
	global_load_ushort v26, v73, s[6:7] offset:2048
	global_load_ushort v27, v73, s[6:7] offset:3072
	v_add_u32_e32 v73, 0x1000, v73
	global_load_ushort v28, v73, s[6:7] offset:0
	global_load_ushort v29, v73, s[6:7] offset:1024
	global_load_ushort v30, v73, s[6:7] offset:2048
	global_load_ushort v31, v73, s[6:7] offset:3072
	v_add_u32_e32 v73, 0x1000, v73
	global_load_ushort v32, v73, s[6:7] offset:0
	global_load_ushort v33, v73, s[6:7] offset:1024
	global_load_ushort v34, v73, s[6:7] offset:2048
	global_load_ushort v35, v73, s[6:7] offset:3072
	v_add_u32_e32 v73, 0x1000, v73
	s_waitcnt vmcnt(0)
	v_lshlrev_b32_e32 v69, 16, v69
	v_lshlrev_b32_e32 v70, 16, v70
	v_lshlrev_b32_e32 v71, 16, v71
	v_and_b32_e32 v146, 0x7fffffff, v15
	v_mul_f32_e32 v146, 0xbfb8aa3b, v146
	v_exp_f32_e32 v146, v146
	v_max_f32_e64 v80, -v15, 0
	v_add_f32_e32 v146, 1.0, v146
	v_log_f32_e32 v146, v146
	s_nop 0
	v_mul_f32_e32 v146, 0x3f317218, v146
	v_add_f32_e32 v146, v80, v146
	v_mul_f32_e32 v15, 0xc138aa3b, v146
	s_mov_b32 s20, 0
	s_movk_i32 s1, 0x7fff
; DI bf16_t f2bf(float x) { unsigned u = __float_as_uint(x); u += 0x7fffu + ((u >> 16) & 1u); return (bf16_t)(u >> 16); }
; DI float bf2f(bf16_t b) { return __uint_as_float(((unsigned)b) << 16); }
; template <bool PASS2>
; DI void lru_item(const Params& p, int l, int item, int lane, const bf16_t* xl, float* wxs) {
;     ...
; #pragma unroll 1
;   for (int t = 0; t < LCL; t++) {
;     const float x0 = xn;
;     if (t + 1 < LCL) xn = bf2f(xl[(tok0 + t + 1) * 512 + ch]);
;     const float xc = cw3 * x0 + cw2 * x1 + cw1 * x2 + cw0 * x3 + cb;
;     x3 = x2; x2 = x1; x1 = x0;
;     float ra0 = ba, ra1 = 0.f, rx0 = bx, rx1 = 0.f;
;     const unsigned xb16 = (unsigned)f2bf(xc);
;     const unsigned xnb = (unsigned)__shfl_xor((int)xb16, 1);
;     const unsigned xpk = xb16 | (xnb << 16);
; #pragma unroll
;     for (int m = 0; m < 32; m += 2) {
;       const bf2_t xa = __builtin_bit_cast(bf2_t, (unsigned)__builtin_amdgcn_readlane((int)xpk, 2 * m));
;       const bf2_t xb = __builtin_bit_cast(bf2_t, (unsigned)__builtin_amdgcn_readlane((int)xpk, 2 * m + 2));
;       ra0 = __builtin_amdgcn_fdot2_f32_bf16(xa, __builtin_bit_cast(bf2_t, wpa[m]), ra0, false);
;       rx0 = __builtin_amdgcn_fdot2_f32_bf16(xa, __builtin_bit_cast(bf2_t, wpx[m]), rx0, false);
;       ra1 = __builtin_amdgcn_fdot2_f32_bf16(xb, __builtin_bit_cast(bf2_t, wpa[m + 1]), ra1, false);
;       rx1 = __builtin_amdgcn_fdot2_f32_bf16(xb, __builtin_bit_cast(bf2_t, wpx[m + 1]), rx1, false);
;     }
.Llrua1_loop:
	v_lshlrev_b32_e32 v20, 16, v20
	v_fma_f32 v52, v8, v71, v12
	v_fmac_f32_e32 v52, v9, v70
	v_fmac_f32_e32 v52, v10, v69
	v_fmac_f32_e32 v52, v11, v20
	v_bfe_u32 v78, v52, 16, 1
	v_add3_u32 v78, v52, v78, s1
	ds_write_b16_d16_hi v74, v78 offset:0
	v_lshlrev_b32_e32 v21, 16, v21
	v_fma_f32 v53, v8, v70, v12
	v_fmac_f32_e32 v53, v9, v69
	v_fmac_f32_e32 v53, v10, v20
	v_fmac_f32_e32 v53, v11, v21
	v_bfe_u32 v79, v53, 16, 1
	v_add3_u32 v79, v53, v79, s1
	ds_write_b16_d16_hi v74, v79 offset:144
	v_lshlrev_b32_e32 v22, 16, v22
	v_fma_f32 v54, v8, v69, v12
	v_fmac_f32_e32 v54, v9, v20
	v_fmac_f32_e32 v54, v10, v21
	v_fmac_f32_e32 v54, v11, v22
	v_bfe_u32 v78, v54, 16, 1
	v_add3_u32 v78, v54, v78, s1
	ds_write_b16_d16_hi v74, v78 offset:288
	v_lshlrev_b32_e32 v23, 16, v23
	v_fma_f32 v55, v8, v20, v12
	v_fmac_f32_e32 v55, v9, v21
	v_fmac_f32_e32 v55, v10, v22
	v_fmac_f32_e32 v55, v11, v23
	v_bfe_u32 v79, v55, 16, 1
	v_add3_u32 v79, v55, v79, s1
	ds_write_b16_d16_hi v74, v79 offset:432
	v_lshlrev_b32_e32 v24, 16, v24
	v_fma_f32 v56, v8, v21, v12
	v_fmac_f32_e32 v56, v9, v22
	v_fmac_f32_e32 v56, v10, v23
	v_fmac_f32_e32 v56, v11, v24
	v_bfe_u32 v78, v56, 16, 1
	v_add3_u32 v78, v56, v78, s1
	ds_write_b16_d16_hi v74, v78 offset:576
	v_lshlrev_b32_e32 v25, 16, v25
	v_fma_f32 v57, v8, v22, v12
	v_fmac_f32_e32 v57, v9, v23
	v_fmac_f32_e32 v57, v10, v24
	v_fmac_f32_e32 v57, v11, v25
	v_bfe_u32 v79, v57, 16, 1
	v_add3_u32 v79, v57, v79, s1
	ds_write_b16_d16_hi v74, v79 offset:720
	v_lshlrev_b32_e32 v26, 16, v26
	v_fma_f32 v58, v8, v23, v12
	v_fmac_f32_e32 v58, v9, v24
	v_fmac_f32_e32 v58, v10, v25
	v_fmac_f32_e32 v58, v11, v26
	v_bfe_u32 v78, v58, 16, 1
	v_add3_u32 v78, v58, v78, s1
	ds_write_b16_d16_hi v74, v78 offset:864
	v_lshlrev_b32_e32 v27, 16, v27
	v_fma_f32 v59, v8, v24, v12
	v_fmac_f32_e32 v59, v9, v25
	v_fmac_f32_e32 v59, v10, v26
	v_fmac_f32_e32 v59, v11, v27
	v_bfe_u32 v79, v59, 16, 1
	v_add3_u32 v79, v59, v79, s1
	ds_write_b16_d16_hi v74, v79 offset:1008
	v_lshlrev_b32_e32 v28, 16, v28
	v_fma_f32 v60, v8, v25, v12
	v_fmac_f32_e32 v60, v9, v26
	v_fmac_f32_e32 v60, v10, v27
	v_fmac_f32_e32 v60, v11, v28
	v_bfe_u32 v78, v60, 16, 1
	v_add3_u32 v78, v60, v78, s1
	ds_write_b16_d16_hi v74, v78 offset:1152
	v_lshlrev_b32_e32 v29, 16, v29
	v_fma_f32 v61, v8, v26, v12
	v_fmac_f32_e32 v61, v9, v27
	v_fmac_f32_e32 v61, v10, v28
	v_fmac_f32_e32 v61, v11, v29
	v_bfe_u32 v79, v61, 16, 1
	v_add3_u32 v79, v61, v79, s1
	ds_write_b16_d16_hi v74, v79 offset:1296
	v_lshlrev_b32_e32 v30, 16, v30
	v_fma_f32 v62, v8, v27, v12
	v_fmac_f32_e32 v62, v9, v28
	v_fmac_f32_e32 v62, v10, v29
	v_fmac_f32_e32 v62, v11, v30
	v_bfe_u32 v78, v62, 16, 1
	v_add3_u32 v78, v62, v78, s1
	ds_write_b16_d16_hi v74, v78 offset:1440
	v_lshlrev_b32_e32 v31, 16, v31
	v_fma_f32 v63, v8, v28, v12
	v_fmac_f32_e32 v63, v9, v29
	v_fmac_f32_e32 v63, v10, v30
	v_fmac_f32_e32 v63, v11, v31
	v_bfe_u32 v79, v63, 16, 1
	v_add3_u32 v79, v63, v79, s1
	ds_write_b16_d16_hi v74, v79 offset:1584
	v_lshlrev_b32_e32 v32, 16, v32
	v_fma_f32 v64, v8, v29, v12
	v_fmac_f32_e32 v64, v9, v30
	v_fmac_f32_e32 v64, v10, v31
	v_fmac_f32_e32 v64, v11, v32
	v_bfe_u32 v78, v64, 16, 1
	v_add3_u32 v78, v64, v78, s1
	ds_write_b16_d16_hi v74, v78 offset:1728
	v_lshlrev_b32_e32 v33, 16, v33
	v_fma_f32 v65, v8, v30, v12
	v_fmac_f32_e32 v65, v9, v31
	v_fmac_f32_e32 v65, v10, v32
	v_fmac_f32_e32 v65, v11, v33
	v_bfe_u32 v79, v65, 16, 1
	v_add3_u32 v79, v65, v79, s1
	ds_write_b16_d16_hi v74, v79 offset:1872
	v_lshlrev_b32_e32 v34, 16, v34
	v_fma_f32 v66, v8, v31, v12
	v_fmac_f32_e32 v66, v9, v32
	v_fmac_f32_e32 v66, v10, v33
	v_fmac_f32_e32 v66, v11, v34
	v_bfe_u32 v78, v66, 16, 1
	v_add3_u32 v78, v66, v78, s1
	ds_write_b16_d16_hi v74, v78 offset:2016
	v_lshlrev_b32_e32 v35, 16, v35
	v_fma_f32 v67, v8, v32, v12
	v_fmac_f32_e32 v67, v9, v33
	v_fmac_f32_e32 v67, v10, v34
	v_fmac_f32_e32 v67, v11, v35
	v_bfe_u32 v79, v67, 16, 1
	v_add3_u32 v79, v67, v79, s1
	ds_write_b16_d16_hi v74, v79 offset:2160
	v_mov_b32_e32 v71, v33
	v_mov_b32_e32 v70, v34
	v_mov_b32_e32 v69, v35
	ds_read_b128 v[0:3], v75
	ds_read_b128 v[4:7], v75 offset:64
	s_waitcnt lgkmcnt(0)
	v_mfma_f32_16x16x32_bf16 v[20:23], v[0:3], v[82:85], 0
	v_mfma_f32_16x16x32_bf16 v[24:27], v[0:3], v[86:89], 0
	v_mfma_f32_16x16x32_bf16 v[28:31], v[0:3], v[90:93], 0
	v_mfma_f32_16x16x32_bf16 v[32:35], v[0:3], v[94:97], 0
	v_mfma_f32_16x16x32_bf16 v[36:39], v[0:3], v[98:101], 0
	v_mfma_f32_16x16x32_bf16 v[40:43], v[0:3], v[102:105], 0
	v_mfma_f32_16x16x32_bf16 v[44:47], v[0:3], v[106:109], 0
	v_mfma_f32_16x16x32_bf16 v[48:51], v[0:3], v[110:113], 0
	v_mfma_f32_16x16x32_bf16 v[20:23], v[4:7], v[114:117], v[20:23]
	v_mfma_f32_16x16x32_bf16 v[24:27], v[4:7], v[118:121], v[24:27]
	v_mfma_f32_16x16x32_bf16 v[28:31], v[4:7], v[122:125], v[28:31]
	v_mfma_f32_16x16x32_bf16 v[32:35], v[4:7], v[126:129], v[32:35]
	v_mfma_f32_16x16x32_bf16 v[36:39], v[4:7], v[130:133], v[36:39]
	v_mfma_f32_16x16x32_bf16 v[40:43], v[4:7], v[134:137], v[40:43]
	v_mfma_f32_16x16x32_bf16 v[44:47], v[4:7], v[138:141], v[44:47]
	v_mfma_f32_16x16x32_bf16 v[48:51], v[4:7], v[142:145], v[48:51]
	s_nop 7
	ds_write_b32 v76, v20 offset:0
	ds_write_b32 v76, v21 offset:528
	ds_write_b32 v76, v22 offset:1056
	ds_write_b32 v76, v23 offset:1584
	ds_write_b32 v76, v24 offset:64
	ds_write_b32 v76, v25 offset:592
	ds_write_b32 v76, v26 offset:1120
	ds_write_b32 v76, v27 offset:1648
	ds_write_b32 v76, v28 offset:128
	ds_write_b32 v76, v29 offset:656
	ds_write_b32 v76, v30 offset:1184
	ds_write_b32 v76, v31 offset:1712
	ds_write_b32 v76, v32 offset:192
	ds_write_b32 v76, v33 offset:720
	ds_write_b32 v76, v34 offset:1248
	ds_write_b32 v76, v35 offset:1776
	ds_write_b32 v76, v36 offset:256
	ds_write_b32 v76, v37 offset:784
	ds_write_b32 v76, v38 offset:1312
	ds_write_b32 v76, v39 offset:1840
	ds_write_b32 v76, v40 offset:320
	ds_write_b32 v76, v41 offset:848
	ds_write_b32 v76, v42 offset:1376
	ds_write_b32 v76, v43 offset:1904
	ds_write_b32 v76, v44 offset:384
	ds_write_b32 v76, v45 offset:912
	ds_write_b32 v76, v46 offset:1440
	ds_write_b32 v76, v47 offset:1968
	ds_write_b32 v76, v48 offset:448
	ds_write_b32 v76, v49 offset:976
	ds_write_b32 v76, v50 offset:1504
	ds_write_b32 v76, v51 offset:2032
	s_cmp_lt_u32 s20, 7
	s_cbranch_scc0 .Llrua1_noload
; DI bf16_t f2bf(float x) { unsigned u = __float_as_uint(x); u += 0x7fffu + ((u >> 16) & 1u); return (bf16_t)(u >> 16); }
; DI float sigmoidf_(float x) { return __builtin_amdgcn_rcpf(1.f + __expf(-x)); }
; template <bool PASS2>
; DI void lru_item(const Params& p, int l, int item, int lane, const bf16_t* xl, float* wxs) {
;     ...
;     const float rg = sigmoidf_(ra0 + ra1), ig = sigmoidf_(rx0 + rx1);
;     const float la = -8.f * rg * sp;
;     const float a = __expf(la);
;     const float inp = sqrtf(fmaxf(1.f - a * a, 0.f)) * (ig * xc);
;     hs = a * hs + inp;
;     if (PASS2) p.yd[(tok0 + t) * 512 + ch] = f2bf(hs);
;     else aprod *= a;
	global_load_ushort v20, v73, s[6:7] offset:0
	global_load_ushort v21, v73, s[6:7] offset:1024
	global_load_ushort v22, v73, s[6:7] offset:2048
	global_load_ushort v23, v73, s[6:7] offset:3072
	v_add_u32_e32 v73, 0x1000, v73
	global_load_ushort v24, v73, s[6:7] offset:0
	global_load_ushort v25, v73, s[6:7] offset:1024
	global_load_ushort v26, v73, s[6:7] offset:2048
	global_load_ushort v27, v73, s[6:7] offset:3072
	v_add_u32_e32 v73, 0x1000, v73
	global_load_ushort v28, v73, s[6:7] offset:0
	global_load_ushort v29, v73, s[6:7] offset:1024
	global_load_ushort v30, v73, s[6:7] offset:2048
	global_load_ushort v31, v73, s[6:7] offset:3072
	v_add_u32_e32 v73, 0x1000, v73
	global_load_ushort v32, v73, s[6:7] offset:0
	global_load_ushort v33, v73, s[6:7] offset:1024
	global_load_ushort v34, v73, s[6:7] offset:2048
	global_load_ushort v35, v73, s[6:7] offset:3072
	v_add_u32_e32 v73, 0x1000, v73
.Llrua1_noload:
	ds_read_b32 v0, v77 offset:0
	ds_read_b32 v1, v77 offset:256
	ds_read_b32 v2, v77 offset:528
	ds_read_b32 v3, v77 offset:784
	ds_read_b32 v4, v77 offset:1056
	ds_read_b32 v5, v77 offset:1312
	ds_read_b32 v6, v77 offset:1584
	ds_read_b32 v7, v77 offset:1840
	s_waitcnt lgkmcnt(0)
	v_add_f32_e32 v0, v0, v13
	v_add_f32_e32 v1, v1, v14
	v_mul_f32_e32 v0, 0xbfb8aa3b, v0
	v_mul_f32_e32 v1, 0xbfb8aa3b, v1
	v_exp_f32_e32 v0, v0
	v_exp_f32_e32 v1, v1
	v_add_f32_e32 v0, 1.0, v0
	v_add_f32_e32 v1, 1.0, v1
	v_rcp_f32_e32 v0, v0
	v_rcp_f32_e32 v1, v1
	v_mul_f32_e32 v80, v0, v15
	v_exp_f32_e32 v80, v80
	v_mul_f32_e32 v147, v1, v52
	v_fma_f32 v146, -v80, v80, 1.0
	v_max_f32_e32 v146, 0, v146
	v_sqrt_f32_e32 v146, v146
	v_mul_f32_e32 v68, v68, v80
	v_mul_f32_e32 v147, v146, v147
	v_fma_f32 v19, v80, v19, v147
	v_add_f32_e32 v2, v2, v13
	v_add_f32_e32 v3, v3, v14
	v_mul_f32_e32 v2, 0xbfb8aa3b, v2
	v_mul_f32_e32 v3, 0xbfb8aa3b, v3
	v_exp_f32_e32 v2, v2
	v_exp_f32_e32 v3, v3
	v_add_f32_e32 v2, 1.0, v2
	v_add_f32_e32 v3, 1.0, v3
	v_rcp_f32_e32 v2, v2
	v_rcp_f32_e32 v3, v3
	v_mul_f32_e32 v80, v2, v15
	v_exp_f32_e32 v80, v80
	v_mul_f32_e32 v147, v3, v53
	v_fma_f32 v146, -v80, v80, 1.0
	v_max_f32_e32 v146, 0, v146
	v_sqrt_f32_e32 v146, v146
	v_mul_f32_e32 v68, v68, v80
	v_mul_f32_e32 v147, v146, v147
	v_fma_f32 v19, v80, v19, v147
	v_add_f32_e32 v4, v4, v13
	v_add_f32_e32 v5, v5, v14
	v_mul_f32_e32 v4, 0xbfb8aa3b, v4
	v_mul_f32_e32 v5, 0xbfb8aa3b, v5
	v_exp_f32_e32 v4, v4
	v_exp_f32_e32 v5, v5
	v_add_f32_e32 v4, 1.0, v4
	v_add_f32_e32 v5, 1.0, v5
	v_rcp_f32_e32 v4, v4
	v_rcp_f32_e32 v5, v5
	v_mul_f32_e32 v80, v4, v15
	v_exp_f32_e32 v80, v80
	v_mul_f32_e32 v147, v5, v54
	v_fma_f32 v146, -v80, v80, 1.0
	v_max_f32_e32 v146, 0, v146
	v_sqrt_f32_e32 v146, v146
	v_mul_f32_e32 v68, v68, v80
	v_mul_f32_e32 v147, v146, v147
	v_fma_f32 v19, v80, v19, v147
	v_add_f32_e32 v6, v6, v13
	v_add_f32_e32 v7, v7, v14
	v_mul_f32_e32 v6, 0xbfb8aa3b, v6
	v_mul_f32_e32 v7, 0xbfb8aa3b, v7
	v_exp_f32_e32 v6, v6
	v_exp_f32_e32 v7, v7
	v_add_f32_e32 v6, 1.0, v6
	v_add_f32_e32 v7, 1.0, v7
	v_rcp_f32_e32 v6, v6
	v_rcp_f32_e32 v7, v7
	v_mul_f32_e32 v80, v6, v15
	v_exp_f32_e32 v80, v80
	v_mul_f32_e32 v147, v7, v55
	v_fma_f32 v146, -v80, v80, 1.0
	v_max_f32_e32 v146, 0, v146
	v_sqrt_f32_e32 v146, v146
	v_mul_f32_e32 v68, v68, v80
	v_mul_f32_e32 v147, v146, v147
	v_fma_f32 v19, v80, v19, v147
	ds_read_b32 v0, v77 offset:2112
	ds_read_b32 v1, v77 offset:2368
	ds_read_b32 v2, v77 offset:2640
	ds_read_b32 v3, v77 offset:2896
	ds_read_b32 v4, v77 offset:3168
	ds_read_b32 v5, v77 offset:3424
	ds_read_b32 v6, v77 offset:3696
	ds_read_b32 v7, v77 offset:3952
	s_waitcnt lgkmcnt(0)
	v_add_f32_e32 v0, v0, v13
	v_add_f32_e32 v1, v1, v14
	v_mul_f32_e32 v0, 0xbfb8aa3b, v0
	v_mul_f32_e32 v1, 0xbfb8aa3b, v1
	v_exp_f32_e32 v0, v0
	v_exp_f32_e32 v1, v1
	v_add_f32_e32 v0, 1.0, v0
	v_add_f32_e32 v1, 1.0, v1
	v_rcp_f32_e32 v0, v0
	v_rcp_f32_e32 v1, v1
	v_mul_f32_e32 v80, v0, v15
	v_exp_f32_e32 v80, v80
	v_mul_f32_e32 v147, v1, v56
	v_fma_f32 v146, -v80, v80, 1.0
	v_max_f32_e32 v146, 0, v146
	v_sqrt_f32_e32 v146, v146
	v_mul_f32_e32 v68, v68, v80
	v_mul_f32_e32 v147, v146, v147
	v_fma_f32 v19, v80, v19, v147
	v_add_f32_e32 v2, v2, v13
	v_add_f32_e32 v3, v3, v14
	v_mul_f32_e32 v2, 0xbfb8aa3b, v2
	v_mul_f32_e32 v3, 0xbfb8aa3b, v3
	v_exp_f32_e32 v2, v2
	v_exp_f32_e32 v3, v3
	v_add_f32_e32 v2, 1.0, v2
	v_add_f32_e32 v3, 1.0, v3
	v_rcp_f32_e32 v2, v2
	v_rcp_f32_e32 v3, v3
	v_mul_f32_e32 v80, v2, v15
	v_exp_f32_e32 v80, v80
	v_mul_f32_e32 v147, v3, v57
	v_fma_f32 v146, -v80, v80, 1.0
	v_max_f32_e32 v146, 0, v146
	v_sqrt_f32_e32 v146, v146
	v_mul_f32_e32 v68, v68, v80
	v_mul_f32_e32 v147, v146, v147
	v_fma_f32 v19, v80, v19, v147
	v_add_f32_e32 v4, v4, v13
	v_add_f32_e32 v5, v5, v14
	v_mul_f32_e32 v4, 0xbfb8aa3b, v4
	v_mul_f32_e32 v5, 0xbfb8aa3b, v5
	v_exp_f32_e32 v4, v4
	v_exp_f32_e32 v5, v5
	v_add_f32_e32 v4, 1.0, v4
	v_add_f32_e32 v5, 1.0, v5
	v_rcp_f32_e32 v4, v4
	v_rcp_f32_e32 v5, v5
	v_mul_f32_e32 v80, v4, v15
	v_exp_f32_e32 v80, v80
	v_mul_f32_e32 v147, v5, v58
	v_fma_f32 v146, -v80, v80, 1.0
	v_max_f32_e32 v146, 0, v146
	v_sqrt_f32_e32 v146, v146
	v_mul_f32_e32 v68, v68, v80
	v_mul_f32_e32 v147, v146, v147
	v_fma_f32 v19, v80, v19, v147
	v_add_f32_e32 v6, v6, v13
	v_add_f32_e32 v7, v7, v14
	v_mul_f32_e32 v6, 0xbfb8aa3b, v6
	v_mul_f32_e32 v7, 0xbfb8aa3b, v7
	v_exp_f32_e32 v6, v6
	v_exp_f32_e32 v7, v7
	v_add_f32_e32 v6, 1.0, v6
	v_add_f32_e32 v7, 1.0, v7
	v_rcp_f32_e32 v6, v6
	v_rcp_f32_e32 v7, v7
	v_mul_f32_e32 v80, v6, v15
	v_exp_f32_e32 v80, v80
	v_mul_f32_e32 v147, v7, v59
	v_fma_f32 v146, -v80, v80, 1.0
	v_max_f32_e32 v146, 0, v146
	v_sqrt_f32_e32 v146, v146
	v_mul_f32_e32 v68, v68, v80
	v_mul_f32_e32 v147, v146, v147
	v_fma_f32 v19, v80, v19, v147
	ds_read_b32 v0, v77 offset:4224
	ds_read_b32 v1, v77 offset:4480
	ds_read_b32 v2, v77 offset:4752
	ds_read_b32 v3, v77 offset:5008
	ds_read_b32 v4, v77 offset:5280
	ds_read_b32 v5, v77 offset:5536
	ds_read_b32 v6, v77 offset:5808
	ds_read_b32 v7, v77 offset:6064
	s_waitcnt lgkmcnt(0)
; DI bf16_t f2bf(float x) { unsigned u = __float_as_uint(x); u += 0x7fffu + ((u >> 16) & 1u); return (bf16_t)(u >> 16); }
; DI float sigmoidf_(float x) { return __builtin_amdgcn_rcpf(1.f + __expf(-x)); }
; template <bool PASS2>
; DI void lru_item(const Params& p, int l, int item, int lane, const bf16_t* xl, float* wxs) {
;     ...
;     const float rg = sigmoidf_(ra0 + ra1), ig = sigmoidf_(rx0 + rx1);
;     const float la = -8.f * rg * sp;
;     const float a = __expf(la);
;     const float inp = sqrtf(fmaxf(1.f - a * a, 0.f)) * (ig * xc);
;     hs = a * hs + inp;
;     if (PASS2) p.yd[(tok0 + t) * 512 + ch] = f2bf(hs);
;     else aprod *= a;
;   }
;   if (!PASS2) { st[0] = aprod; st[1] = hs; }
; template <int Q>
; DI void run_phase(const Params& p, int l, bf16_t* sm) {
;     ...
;     for (int it = wave * gridDim.x + blockIdx.x; it < 16 * NCHL; it += gridDim.x * 4) lru_item<false>(p, l, __builtin_amdgcn_readfirstlane(it), lane, xlbuf, (float*)sm + wave * 4096);
	v_add_f32_e32 v0, v0, v13
	v_add_f32_e32 v1, v1, v14
	v_mul_f32_e32 v0, 0xbfb8aa3b, v0
	v_mul_f32_e32 v1, 0xbfb8aa3b, v1
	v_exp_f32_e32 v0, v0
	v_exp_f32_e32 v1, v1
	v_add_f32_e32 v0, 1.0, v0
	v_add_f32_e32 v1, 1.0, v1
	v_rcp_f32_e32 v0, v0
	v_rcp_f32_e32 v1, v1
	v_mul_f32_e32 v80, v0, v15
	v_exp_f32_e32 v80, v80
	v_mul_f32_e32 v147, v1, v60
	v_fma_f32 v146, -v80, v80, 1.0
	v_max_f32_e32 v146, 0, v146
	v_sqrt_f32_e32 v146, v146
	v_mul_f32_e32 v68, v68, v80
	v_mul_f32_e32 v147, v146, v147
	v_fma_f32 v19, v80, v19, v147
	v_add_f32_e32 v2, v2, v13
	v_add_f32_e32 v3, v3, v14
	v_mul_f32_e32 v2, 0xbfb8aa3b, v2
	v_mul_f32_e32 v3, 0xbfb8aa3b, v3
	v_exp_f32_e32 v2, v2
	v_exp_f32_e32 v3, v3
	v_add_f32_e32 v2, 1.0, v2
	v_add_f32_e32 v3, 1.0, v3
	v_rcp_f32_e32 v2, v2
	v_rcp_f32_e32 v3, v3
	v_mul_f32_e32 v80, v2, v15
	v_exp_f32_e32 v80, v80
	v_mul_f32_e32 v147, v3, v61
	v_fma_f32 v146, -v80, v80, 1.0
	v_max_f32_e32 v146, 0, v146
	v_sqrt_f32_e32 v146, v146
	v_mul_f32_e32 v68, v68, v80
	v_mul_f32_e32 v147, v146, v147
	v_fma_f32 v19, v80, v19, v147
	v_add_f32_e32 v4, v4, v13
	v_add_f32_e32 v5, v5, v14
	v_mul_f32_e32 v4, 0xbfb8aa3b, v4
	v_mul_f32_e32 v5, 0xbfb8aa3b, v5
	v_exp_f32_e32 v4, v4
	v_exp_f32_e32 v5, v5
	v_add_f32_e32 v4, 1.0, v4
	v_add_f32_e32 v5, 1.0, v5
	v_rcp_f32_e32 v4, v4
	v_rcp_f32_e32 v5, v5
	v_mul_f32_e32 v80, v4, v15
	v_exp_f32_e32 v80, v80
	v_mul_f32_e32 v147, v5, v62
	v_fma_f32 v146, -v80, v80, 1.0
	v_max_f32_e32 v146, 0, v146
	v_sqrt_f32_e32 v146, v146
	v_mul_f32_e32 v68, v68, v80
	v_mul_f32_e32 v147, v146, v147
	v_fma_f32 v19, v80, v19, v147
	v_add_f32_e32 v6, v6, v13
	v_add_f32_e32 v7, v7, v14
	v_mul_f32_e32 v6, 0xbfb8aa3b, v6
	v_mul_f32_e32 v7, 0xbfb8aa3b, v7
	v_exp_f32_e32 v6, v6
	v_exp_f32_e32 v7, v7
	v_add_f32_e32 v6, 1.0, v6
	v_add_f32_e32 v7, 1.0, v7
	v_rcp_f32_e32 v6, v6
	v_rcp_f32_e32 v7, v7
	v_mul_f32_e32 v80, v6, v15
	v_exp_f32_e32 v80, v80
	v_mul_f32_e32 v147, v7, v63
	v_fma_f32 v146, -v80, v80, 1.0
	v_max_f32_e32 v146, 0, v146
	v_sqrt_f32_e32 v146, v146
	v_mul_f32_e32 v68, v68, v80
	v_mul_f32_e32 v147, v146, v147
	v_fma_f32 v19, v80, v19, v147
	ds_read_b32 v0, v77 offset:6336
	ds_read_b32 v1, v77 offset:6592
	ds_read_b32 v2, v77 offset:6864
	ds_read_b32 v3, v77 offset:7120
	ds_read_b32 v4, v77 offset:7392
	ds_read_b32 v5, v77 offset:7648
	ds_read_b32 v6, v77 offset:7920
	ds_read_b32 v7, v77 offset:8176
	s_waitcnt lgkmcnt(0)
	v_add_f32_e32 v0, v0, v13
	v_add_f32_e32 v1, v1, v14
	v_mul_f32_e32 v0, 0xbfb8aa3b, v0
	v_mul_f32_e32 v1, 0xbfb8aa3b, v1
	v_exp_f32_e32 v0, v0
	v_exp_f32_e32 v1, v1
	v_add_f32_e32 v0, 1.0, v0
	v_add_f32_e32 v1, 1.0, v1
	v_rcp_f32_e32 v0, v0
	v_rcp_f32_e32 v1, v1
	v_mul_f32_e32 v80, v0, v15
	v_exp_f32_e32 v80, v80
	v_mul_f32_e32 v147, v1, v64
	v_fma_f32 v146, -v80, v80, 1.0
	v_max_f32_e32 v146, 0, v146
	v_sqrt_f32_e32 v146, v146
	v_mul_f32_e32 v68, v68, v80
	v_mul_f32_e32 v147, v146, v147
	v_fma_f32 v19, v80, v19, v147
	v_add_f32_e32 v2, v2, v13
	v_add_f32_e32 v3, v3, v14
	v_mul_f32_e32 v2, 0xbfb8aa3b, v2
	v_mul_f32_e32 v3, 0xbfb8aa3b, v3
	v_exp_f32_e32 v2, v2
	v_exp_f32_e32 v3, v3
	v_add_f32_e32 v2, 1.0, v2
	v_add_f32_e32 v3, 1.0, v3
	v_rcp_f32_e32 v2, v2
	v_rcp_f32_e32 v3, v3
	v_mul_f32_e32 v80, v2, v15
	v_exp_f32_e32 v80, v80
	v_mul_f32_e32 v147, v3, v65
	v_fma_f32 v146, -v80, v80, 1.0
	v_max_f32_e32 v146, 0, v146
	v_sqrt_f32_e32 v146, v146
	v_mul_f32_e32 v68, v68, v80
	v_mul_f32_e32 v147, v146, v147
	v_fma_f32 v19, v80, v19, v147
	v_add_f32_e32 v4, v4, v13
	v_add_f32_e32 v5, v5, v14
	v_mul_f32_e32 v4, 0xbfb8aa3b, v4
	v_mul_f32_e32 v5, 0xbfb8aa3b, v5
	v_exp_f32_e32 v4, v4
	v_exp_f32_e32 v5, v5
	v_add_f32_e32 v4, 1.0, v4
	v_add_f32_e32 v5, 1.0, v5
	v_rcp_f32_e32 v4, v4
	v_rcp_f32_e32 v5, v5
	v_mul_f32_e32 v80, v4, v15
	v_exp_f32_e32 v80, v80
	v_mul_f32_e32 v147, v5, v66
	v_fma_f32 v146, -v80, v80, 1.0
	v_max_f32_e32 v146, 0, v146
	v_sqrt_f32_e32 v146, v146
	v_mul_f32_e32 v68, v68, v80
	v_mul_f32_e32 v147, v146, v147
	v_fma_f32 v19, v80, v19, v147
	v_add_f32_e32 v6, v6, v13
	v_add_f32_e32 v7, v7, v14
	v_mul_f32_e32 v6, 0xbfb8aa3b, v6
	v_mul_f32_e32 v7, 0xbfb8aa3b, v7
	v_exp_f32_e32 v6, v6
	v_exp_f32_e32 v7, v7
	v_add_f32_e32 v6, 1.0, v6
	v_add_f32_e32 v7, 1.0, v7
	v_rcp_f32_e32 v6, v6
	v_rcp_f32_e32 v7, v7
	v_mul_f32_e32 v80, v6, v15
	v_exp_f32_e32 v80, v80
	v_mul_f32_e32 v147, v7, v67
	v_fma_f32 v146, -v80, v80, 1.0
	v_max_f32_e32 v146, 0, v146
	v_sqrt_f32_e32 v146, v146
	v_mul_f32_e32 v68, v68, v80
	v_mul_f32_e32 v147, v146, v147
	v_fma_f32 v19, v80, v19, v147
	s_add_u32 s20, s20, 1
	s_waitcnt vmcnt(0)
	s_cmp_lt_u32 s20, 8
	s_cbranch_scc1 .Llrua1_loop
	v_and_b32_e32 v78, 63, v210
	s_bfe_u32 s16, s12, 0x30007
	v_lshl_add_u32 v78, s16, 6, v78
	v_lshl_add_u32 v78, s19, 9, v78
	v_lshlrev_b32_e32 v78, 7, v78
	v_add_u32_e32 v78, s17, v78
	v_lshlrev_b32_e32 v78, 3, v78
	s_add_u32 s0, s2, 0x3158000
	s_addc_u32 s1, s3, 0
	global_store_dword v78, v68, s[0:1]
	global_store_dword v78, v19, s[0:1] offset:4
	s_waitcnt vmcnt(0)
	s_add_u32 s12, s12, s13
	s_cmpk_lt_i32 s12, 0x800
	s_cbranch_scc1 .Llrua1_item

; DI bf16_t f2bf(float x) { unsigned u = __float_as_uint(x); u += 0x7fffu + ((u >> 16) & 1u); return (bf16_t)(u >> 16); }
; template <bool PASS2>
; DI void lru_item(const Params& p, int l, int item, int lane, const bf16_t* xl, float* wxs) {
;   const int b = item / (8 * NCHL), blk = (item / NCHL) % 8, c = item % NCHL;
;   const int ch = blk * 64 + lane;
;   unsigned wpa[32], wpx[32];
;   {
;     const float* pa = p.in[I_LRU_W_A] + ((size_t)l * 8 + blk) * 4096;
;     const float* px = p.in[I_LRU_W_X] + ((size_t)l * 8 + blk) * 4096;
;     int lo_ = lane; asm volatile("" : "+v"(lo_));
; #pragma unroll
;     for (int m = 0; m < 32; m++) {
;       wpa[m] = (unsigned)f2bf(pa[(2 * m) * 64 + lo_]) | ((unsigned)f2bf(pa[(2 * m + 1) * 64 + lo_]) << 16);
;       wpx[m] = (unsigned)f2bf(px[(2 * m) * 64 + lo_]) | ((unsigned)f2bf(px[(2 * m + 1) * 64 + lo_]) << 16);
;       if ((m & 7) == 7) asm volatile("" ::: "memory");
;     }
;   }
;   const float* cw = p.in[I_LRU_CONV_W] + (size_t)l * 4 * 512;
;   const float cw0 = cw[ch], cw1 = cw[512 + ch], cw2 = cw[1024 + ch], cw3 = cw[1536 + ch];
;   const float cb = p.in[I_LRU_CONV_B][l * 512 + ch];
;   const float ba = p.in[I_LRU_B_A][l * 512 + ch], bx = p.in[I_LRU_B_X][l * 512 + ch];
; template <int Q>
; DI void run_phase(const Params& p, int l, bf16_t* sm) {
;     ...
;     for (int it = wave * gridDim.x + blockIdx.x; it < 16 * NCHL; it += gridDim.x * 4) lru_item<true>(p, l, __builtin_amdgcn_readfirstlane(it), lane, xlbuf, (float*)sm + wave * 4096);
.LBB0_646:
	s_or_b64 exec, exec, s[0:1]
	s_add_u32 s0, s60, 0xf558000
	s_addc_u32 s1, s61, 0
	v_writelane_b32 v255, s0, 6
	v_mov_b32_e32 v21, v210
	s_waitcnt lgkmcnt(0)
	v_mov_b32_e32 v0, v210
	v_writelane_b32 v255, s1, 7
	s_barrier
	v_readlane_b32 s0, v252, 1
	v_bfe_u32 v20, v0, 6, 2
	v_and_b32_e32 v113, 63, v21
	v_mul_lo_u32 v0, v20, s0
	v_add_u32_e32 v22, s33, v0
	s_movk_i32 s0, 0x800
	v_cmp_gt_i32_e32 vcc, s0, v22
	v_readlane_b32 s1, v252, 2
	s_and_saveexec_b64 s[4:5], vcc
	s_cbranch_execz .LBB0_656
	v_readlane_b32 s14, v252, 3
	v_readlane_b32 s15, v252, 4
	v_readlane_b32 s13, v252, 1
	v_readfirstlane_b32 s12, v22
	s_sub_u32 s14, s14, 0x180
	s_subb_u32 s15, s15, 0
	s_lshl_b32 s13, s13, 2
	s_load_dwordx2 s[2:3], s[14:15], 0x170
	s_waitcnt lgkmcnt(0)
	s_add_u32 s6, s2, 0x13558000
	s_addc_u32 s7, s3, 0
.Llrua2_item:
	s_bfe_u32 s16, s12, 0x30007
	v_and_b32_e32 v110, 63, v210
	v_lshl_add_u32 v110, s16, 6, v110
	v_lshlrev_b32_e32 v104, 1, v110
	v_lshlrev_b32_e32 v111, 2, v110
	v_and_b32_e32 v112, 63, v210
	v_lshrrev_b32_e32 v146, 4, v112
	v_and_b32_e32 v112, 15, v112
	v_lshlrev_b32_e32 v108, 11, v146
	v_lshl_add_u32 v108, v112, 2, v108
	v_add_u32_e32 v109, 0x2000, v108
	s_load_dwordx4 s[16:19], s[14:15], 0x100
	s_waitcnt lgkmcnt(0)
	s_add_u32 s0, s16, 0x0
	s_addc_u32 s1, s17, 0
	global_load_dword v8, v111, s[0:1]
	global_load_dword v9, v111, s[0:1] offset:2048
	s_add_u32 s0, s0, 0x1000
	s_addc_u32 s1, s1, 0
	global_load_dword v10, v111, s[0:1]
	global_load_dword v11, v111, s[0:1] offset:2048
	s_add_u32 s0, s18, 0x0
	s_addc_u32 s1, s19, 0
	global_load_dword v12, v111, s[0:1]
	s_load_dwordx4 s[16:19], s[14:15], 0x110
	s_waitcnt lgkmcnt(0)
	s_add_u32 s0, s18, 0x0
	s_addc_u32 s1, s19, 0
	global_load_dword v13, v111, s[0:1]
	s_bfe_u32 s20, s12, 0x30007
	s_add_u32 s20, s20, 0
	s_lshl_b32 s20, s20, 14
	s_add_u32 s10, s16, s20
	s_addc_u32 s11, s17, 0
	s_load_dwordx4 s[16:19], s[14:15], 0x120
	s_mov_b32 s0, 0xffff0000
	s_movk_i32 s1, 0x7fff
	global_load_dword v114, v108, s[10:11] offset:0
	global_load_dword v115, v108, s[10:11] offset:256
	global_load_dword v116, v108, s[10:11] offset:512
	global_load_dword v117, v108, s[10:11] offset:768
	global_load_dword v118, v108, s[10:11] offset:1024
	global_load_dword v119, v108, s[10:11] offset:1280
	global_load_dword v120, v108, s[10:11] offset:1536
	global_load_dword v121, v108, s[10:11] offset:1792
	global_load_dword v122, v108, s[10:11] offset:64
	global_load_dword v123, v108, s[10:11] offset:320
	global_load_dword v124, v108, s[10:11] offset:576
	global_load_dword v125, v108, s[10:11] offset:832
	global_load_dword v126, v108, s[10:11] offset:1088
	global_load_dword v127, v108, s[10:11] offset:1344
	global_load_dword v128, v108, s[10:11] offset:1600
	global_load_dword v129, v108, s[10:11] offset:1856
	global_load_dword v130, v108, s[10:11] offset:128
	global_load_dword v131, v108, s[10:11] offset:384
	global_load_dword v132, v108, s[10:11] offset:640
	global_load_dword v133, v108, s[10:11] offset:896
	global_load_dword v134, v108, s[10:11] offset:1152
	global_load_dword v135, v108, s[10:11] offset:1408
	global_load_dword v136, v108, s[10:11] offset:1664
	global_load_dword v137, v108, s[10:11] offset:1920
	global_load_dword v138, v108, s[10:11] offset:192
	global_load_dword v139, v108, s[10:11] offset:448
	global_load_dword v140, v108, s[10:11] offset:704
	global_load_dword v141, v108, s[10:11] offset:960
	global_load_dword v142, v108, s[10:11] offset:1216
	global_load_dword v143, v108, s[10:11] offset:1472
	global_load_dword v144, v108, s[10:11] offset:1728
	global_load_dword v145, v108, s[10:11] offset:1984
	global_load_dword v88, v109, s[10:11] offset:0
	global_load_dword v89, v109, s[10:11] offset:256
	global_load_dword v90, v109, s[10:11] offset:512
	global_load_dword v91, v109, s[10:11] offset:768
	global_load_dword v92, v109, s[10:11] offset:1024
	global_load_dword v93, v109, s[10:11] offset:1280
	global_load_dword v94, v109, s[10:11] offset:1536
	global_load_dword v95, v109, s[10:11] offset:1792
	global_load_dword v96, v109, s[10:11] offset:64
	global_load_dword v97, v109, s[10:11] offset:320
	global_load_dword v98, v109, s[10:11] offset:576
	global_load_dword v99, v109, s[10:11] offset:832
	global_load_dword v100, v109, s[10:11] offset:1088
	global_load_dword v101, v109, s[10:11] offset:1344
	global_load_dword v102, v109, s[10:11] offset:1600
	global_load_dword v103, v109, s[10:11] offset:1856
	global_load_dword v0, v109, s[10:11] offset:128
	global_load_dword v1, v109, s[10:11] offset:384
	global_load_dword v2, v109, s[10:11] offset:640
	global_load_dword v3, v109, s[10:11] offset:896
	global_load_dword v4, v109, s[10:11] offset:1152
	global_load_dword v5, v109, s[10:11] offset:1408
	global_load_dword v6, v109, s[10:11] offset:1664
	global_load_dword v7, v109, s[10:11] offset:1920
	global_load_dword v16, v109, s[10:11] offset:192
	global_load_dword v17, v109, s[10:11] offset:448
	global_load_dword v18, v109, s[10:11] offset:704
	global_load_dword v19, v109, s[10:11] offset:960
	global_load_dword v23, v109, s[10:11] offset:1216
	global_load_dword v112, v109, s[10:11] offset:1472
	global_load_dword v146, v109, s[10:11] offset:1728
	global_load_dword v147, v109, s[10:11] offset:1984
	s_waitcnt vmcnt(0)
; DI bf16_t f2bf(float x) { unsigned u = __float_as_uint(x); u += 0x7fffu + ((u >> 16) & 1u); return (bf16_t)(u >> 16); }
; template <bool PASS2>
; DI void lru_item(const Params& p, int l, int item, int lane, const bf16_t* xl, float* wxs) {
;     ...
;   unsigned wpa[32], wpx[32];
;   {
;     const float* pa = p.in[I_LRU_W_A] + ((size_t)l * 8 + blk) * 4096;
;     const float* px = p.in[I_LRU_W_X] + ((size_t)l * 8 + blk) * 4096;
;     int lo_ = lane; asm volatile("" : "+v"(lo_));
; #pragma unroll
;     for (int m = 0; m < 32; m++) {
;       wpa[m] = (unsigned)f2bf(pa[(2 * m) * 64 + lo_]) | ((unsigned)f2bf(pa[(2 * m + 1) * 64 + lo_]) << 16);
;       wpx[m] = (unsigned)f2bf(px[(2 * m) * 64 + lo_]) | ((unsigned)f2bf(px[(2 * m + 1) * 64 + lo_]) << 16);
;       if ((m & 7) == 7) asm volatile("" ::: "memory");
;     }
;   }
	v_bfe_u32 v105, v114, 16, 1
	v_bfe_u32 v106, v115, 16, 1
	v_add3_u32 v114, v114, v105, s1
	v_add3_u32 v115, v115, v106, s1
	v_lshrrev_b32_e32 v114, 16, v114
	v_and_or_b32 v24, v115, s0, v114
	v_bfe_u32 v105, v116, 16, 1
	v_bfe_u32 v106, v117, 16, 1
	v_add3_u32 v116, v116, v105, s1
	v_add3_u32 v117, v117, v106, s1
	v_lshrrev_b32_e32 v116, 16, v116
	v_and_or_b32 v25, v117, s0, v116
	v_bfe_u32 v105, v118, 16, 1
	v_bfe_u32 v106, v119, 16, 1
	v_add3_u32 v118, v118, v105, s1
	v_add3_u32 v119, v119, v106, s1
	v_lshrrev_b32_e32 v118, 16, v118
	v_and_or_b32 v26, v119, s0, v118
	v_bfe_u32 v105, v120, 16, 1
	v_bfe_u32 v106, v121, 16, 1
	v_add3_u32 v120, v120, v105, s1
	v_add3_u32 v121, v121, v106, s1
	v_lshrrev_b32_e32 v120, 16, v120
	v_and_or_b32 v27, v121, s0, v120
	v_bfe_u32 v105, v122, 16, 1
	v_bfe_u32 v106, v123, 16, 1
	v_add3_u32 v122, v122, v105, s1
	v_add3_u32 v123, v123, v106, s1
	v_lshrrev_b32_e32 v122, 16, v122
	v_and_or_b32 v28, v123, s0, v122
	v_bfe_u32 v105, v124, 16, 1
	v_bfe_u32 v106, v125, 16, 1
	v_add3_u32 v124, v124, v105, s1
	v_add3_u32 v125, v125, v106, s1
	v_lshrrev_b32_e32 v124, 16, v124
	v_and_or_b32 v29, v125, s0, v124
	v_bfe_u32 v105, v126, 16, 1
	v_bfe_u32 v106, v127, 16, 1
	v_add3_u32 v126, v126, v105, s1
	v_add3_u32 v127, v127, v106, s1
	v_lshrrev_b32_e32 v126, 16, v126
	v_and_or_b32 v30, v127, s0, v126
	v_bfe_u32 v105, v128, 16, 1
	v_bfe_u32 v106, v129, 16, 1
	v_add3_u32 v128, v128, v105, s1
	v_add3_u32 v129, v129, v106, s1
	v_lshrrev_b32_e32 v128, 16, v128
	v_and_or_b32 v31, v129, s0, v128
	v_bfe_u32 v105, v130, 16, 1
	v_bfe_u32 v106, v131, 16, 1
	v_add3_u32 v130, v130, v105, s1
	v_add3_u32 v131, v131, v106, s1
	v_lshrrev_b32_e32 v130, 16, v130
	v_and_or_b32 v32, v131, s0, v130
	v_bfe_u32 v105, v132, 16, 1
	v_bfe_u32 v106, v133, 16, 1
	v_add3_u32 v132, v132, v105, s1
	v_add3_u32 v133, v133, v106, s1
	v_lshrrev_b32_e32 v132, 16, v132
	v_and_or_b32 v33, v133, s0, v132
	v_bfe_u32 v105, v134, 16, 1
	v_bfe_u32 v106, v135, 16, 1
	v_add3_u32 v134, v134, v105, s1
	v_add3_u32 v135, v135, v106, s1
	v_lshrrev_b32_e32 v134, 16, v134
	v_and_or_b32 v34, v135, s0, v134
	v_bfe_u32 v105, v136, 16, 1
	v_bfe_u32 v106, v137, 16, 1
	v_add3_u32 v136, v136, v105, s1
	v_add3_u32 v137, v137, v106, s1
	v_lshrrev_b32_e32 v136, 16, v136
	v_and_or_b32 v35, v137, s0, v136
	v_bfe_u32 v105, v138, 16, 1
	v_bfe_u32 v106, v139, 16, 1
	v_add3_u32 v138, v138, v105, s1
	v_add3_u32 v139, v139, v106, s1
	v_lshrrev_b32_e32 v138, 16, v138
	v_and_or_b32 v36, v139, s0, v138
	v_bfe_u32 v105, v140, 16, 1
	v_bfe_u32 v106, v141, 16, 1
	v_add3_u32 v140, v140, v105, s1
	v_add3_u32 v141, v141, v106, s1
	v_lshrrev_b32_e32 v140, 16, v140
	v_and_or_b32 v37, v141, s0, v140
	v_bfe_u32 v105, v142, 16, 1
	v_bfe_u32 v106, v143, 16, 1
	v_add3_u32 v142, v142, v105, s1
	v_add3_u32 v143, v143, v106, s1
	v_lshrrev_b32_e32 v142, 16, v142
	v_and_or_b32 v38, v143, s0, v142
	v_bfe_u32 v105, v144, 16, 1
	v_bfe_u32 v106, v145, 16, 1
	v_add3_u32 v144, v144, v105, s1
	v_add3_u32 v145, v145, v106, s1
	v_lshrrev_b32_e32 v144, 16, v144
	v_and_or_b32 v39, v145, s0, v144
	v_bfe_u32 v105, v88, 16, 1
	v_bfe_u32 v106, v89, 16, 1
	v_add3_u32 v88, v88, v105, s1
	v_add3_u32 v89, v89, v106, s1
	v_lshrrev_b32_e32 v88, 16, v88
	v_and_or_b32 v56, v89, s0, v88
	v_bfe_u32 v105, v90, 16, 1
	v_bfe_u32 v106, v91, 16, 1
	v_add3_u32 v90, v90, v105, s1
	v_add3_u32 v91, v91, v106, s1
	v_lshrrev_b32_e32 v90, 16, v90
	v_and_or_b32 v57, v91, s0, v90
	v_bfe_u32 v105, v92, 16, 1
	v_bfe_u32 v106, v93, 16, 1
	v_add3_u32 v92, v92, v105, s1
	v_add3_u32 v93, v93, v106, s1
	v_lshrrev_b32_e32 v92, 16, v92
	v_and_or_b32 v58, v93, s0, v92
	v_bfe_u32 v105, v94, 16, 1
	v_bfe_u32 v106, v95, 16, 1
	v_add3_u32 v94, v94, v105, s1
	v_add3_u32 v95, v95, v106, s1
	v_lshrrev_b32_e32 v94, 16, v94
	v_and_or_b32 v59, v95, s0, v94
	v_bfe_u32 v105, v96, 16, 1
	v_bfe_u32 v106, v97, 16, 1
	v_add3_u32 v96, v96, v105, s1
	v_add3_u32 v97, v97, v106, s1
	v_lshrrev_b32_e32 v96, 16, v96
	v_and_or_b32 v60, v97, s0, v96
	v_bfe_u32 v105, v98, 16, 1
	v_bfe_u32 v106, v99, 16, 1
	v_add3_u32 v98, v98, v105, s1
	v_add3_u32 v99, v99, v106, s1
	v_lshrrev_b32_e32 v98, 16, v98
	v_and_or_b32 v61, v99, s0, v98
	v_bfe_u32 v105, v100, 16, 1
	v_bfe_u32 v106, v101, 16, 1
	v_add3_u32 v100, v100, v105, s1
	v_add3_u32 v101, v101, v106, s1
	v_lshrrev_b32_e32 v100, 16, v100
	v_and_or_b32 v62, v101, s0, v100
	v_bfe_u32 v105, v102, 16, 1
	v_bfe_u32 v106, v103, 16, 1
	v_add3_u32 v102, v102, v105, s1
	v_add3_u32 v103, v103, v106, s1
	v_lshrrev_b32_e32 v102, 16, v102
	v_and_or_b32 v63, v103, s0, v102
	v_bfe_u32 v105, v0, 16, 1
	v_bfe_u32 v106, v1, 16, 1
	v_add3_u32 v0, v0, v105, s1
	v_add3_u32 v1, v1, v106, s1
	v_lshrrev_b32_e32 v0, 16, v0
	v_and_or_b32 v64, v1, s0, v0
	v_bfe_u32 v105, v2, 16, 1
	v_bfe_u32 v106, v3, 16, 1
	v_add3_u32 v2, v2, v105, s1
	v_add3_u32 v3, v3, v106, s1
	v_lshrrev_b32_e32 v2, 16, v2
	v_and_or_b32 v65, v3, s0, v2
	v_bfe_u32 v105, v4, 16, 1
	v_bfe_u32 v106, v5, 16, 1
	v_add3_u32 v4, v4, v105, s1
	v_add3_u32 v5, v5, v106, s1
	v_lshrrev_b32_e32 v4, 16, v4
	v_and_or_b32 v66, v5, s0, v4
	v_bfe_u32 v105, v6, 16, 1
	v_bfe_u32 v106, v7, 16, 1
	v_add3_u32 v6, v6, v105, s1
	v_add3_u32 v7, v7, v106, s1
	v_lshrrev_b32_e32 v6, 16, v6
	v_and_or_b32 v67, v7, s0, v6
	v_bfe_u32 v105, v16, 16, 1
	v_bfe_u32 v106, v17, 16, 1
	v_add3_u32 v16, v16, v105, s1
	v_add3_u32 v17, v17, v106, s1
	v_lshrrev_b32_e32 v16, 16, v16
	v_and_or_b32 v68, v17, s0, v16
	v_bfe_u32 v105, v18, 16, 1
	v_bfe_u32 v106, v19, 16, 1
	v_add3_u32 v18, v18, v105, s1
	v_add3_u32 v19, v19, v106, s1
	v_lshrrev_b32_e32 v18, 16, v18
	v_and_or_b32 v69, v19, s0, v18
	v_bfe_u32 v105, v23, 16, 1
	v_bfe_u32 v106, v112, 16, 1
	v_add3_u32 v23, v23, v105, s1
	v_add3_u32 v112, v112, v106, s1
	v_lshrrev_b32_e32 v23, 16, v23
	v_and_or_b32 v70, v112, s0, v23
	v_bfe_u32 v105, v146, 16, 1
	v_bfe_u32 v106, v147, 16, 1
	v_add3_u32 v146, v146, v105, s1
	v_add3_u32 v147, v147, v106, s1
	v_lshrrev_b32_e32 v146, 16, v146
	v_and_or_b32 v71, v147, s0, v146
	s_waitcnt lgkmcnt(0)
; DI bf16_t f2bf(float x) { unsigned u = __float_as_uint(x); u += 0x7fffu + ((u >> 16) & 1u); return (bf16_t)(u >> 16); }
; template <bool PASS2>
; DI void lru_item(const Params& p, int l, int item, int lane, const bf16_t* xl, float* wxs) {
;     ...
;   unsigned wpa[32], wpx[32];
;   {
;     const float* pa = p.in[I_LRU_W_A] + ((size_t)l * 8 + blk) * 4096;
;     const float* px = p.in[I_LRU_W_X] + ((size_t)l * 8 + blk) * 4096;
;     int lo_ = lane; asm volatile("" : "+v"(lo_));
; #pragma unroll
;     for (int m = 0; m < 32; m++) {
;       wpa[m] = (unsigned)f2bf(pa[(2 * m) * 64 + lo_]) | ((unsigned)f2bf(pa[(2 * m + 1) * 64 + lo_]) << 16);
;       wpx[m] = (unsigned)f2bf(px[(2 * m) * 64 + lo_]) | ((unsigned)f2bf(px[(2 * m + 1) * 64 + lo_]) << 16);
;       if ((m & 7) == 7) asm volatile("" ::: "memory");
;     }
;   }
	s_add_u32 s10, s16, s20
	s_addc_u32 s11, s17, 0
	global_load_dword v114, v108, s[10:11] offset:0
	global_load_dword v115, v108, s[10:11] offset:256
	global_load_dword v116, v108, s[10:11] offset:512
	global_load_dword v117, v108, s[10:11] offset:768
	global_load_dword v118, v108, s[10:11] offset:1024
	global_load_dword v119, v108, s[10:11] offset:1280
	global_load_dword v120, v108, s[10:11] offset:1536
	global_load_dword v121, v108, s[10:11] offset:1792
	global_load_dword v122, v108, s[10:11] offset:64
	global_load_dword v123, v108, s[10:11] offset:320
	global_load_dword v124, v108, s[10:11] offset:576
	global_load_dword v125, v108, s[10:11] offset:832
	global_load_dword v126, v108, s[10:11] offset:1088
	global_load_dword v127, v108, s[10:11] offset:1344
	global_load_dword v128, v108, s[10:11] offset:1600
	global_load_dword v129, v108, s[10:11] offset:1856
	global_load_dword v130, v108, s[10:11] offset:128
	global_load_dword v131, v108, s[10:11] offset:384
	global_load_dword v132, v108, s[10:11] offset:640
	global_load_dword v133, v108, s[10:11] offset:896
	global_load_dword v134, v108, s[10:11] offset:1152
	global_load_dword v135, v108, s[10:11] offset:1408
	global_load_dword v136, v108, s[10:11] offset:1664
	global_load_dword v137, v108, s[10:11] offset:1920
	global_load_dword v138, v108, s[10:11] offset:192
	global_load_dword v139, v108, s[10:11] offset:448
	global_load_dword v140, v108, s[10:11] offset:704
	global_load_dword v141, v108, s[10:11] offset:960
	global_load_dword v142, v108, s[10:11] offset:1216
	global_load_dword v143, v108, s[10:11] offset:1472
	global_load_dword v144, v108, s[10:11] offset:1728
	global_load_dword v145, v108, s[10:11] offset:1984
	global_load_dword v88, v109, s[10:11] offset:0
	global_load_dword v89, v109, s[10:11] offset:256
	global_load_dword v90, v109, s[10:11] offset:512
	global_load_dword v91, v109, s[10:11] offset:768
	global_load_dword v92, v109, s[10:11] offset:1024
	global_load_dword v93, v109, s[10:11] offset:1280
	global_load_dword v94, v109, s[10:11] offset:1536
	global_load_dword v95, v109, s[10:11] offset:1792
	global_load_dword v96, v109, s[10:11] offset:64
	global_load_dword v97, v109, s[10:11] offset:320
	global_load_dword v98, v109, s[10:11] offset:576
	global_load_dword v99, v109, s[10:11] offset:832
	global_load_dword v100, v109, s[10:11] offset:1088
	global_load_dword v101, v109, s[10:11] offset:1344
	global_load_dword v102, v109, s[10:11] offset:1600
	global_load_dword v103, v109, s[10:11] offset:1856
	global_load_dword v0, v109, s[10:11] offset:128
	global_load_dword v1, v109, s[10:11] offset:384
	global_load_dword v2, v109, s[10:11] offset:640
	global_load_dword v3, v109, s[10:11] offset:896
	global_load_dword v4, v109, s[10:11] offset:1152
	global_load_dword v5, v109, s[10:11] offset:1408
	global_load_dword v6, v109, s[10:11] offset:1664
	global_load_dword v7, v109, s[10:11] offset:1920
	global_load_dword v16, v109, s[10:11] offset:192
	global_load_dword v17, v109, s[10:11] offset:448
	global_load_dword v18, v109, s[10:11] offset:704
	global_load_dword v19, v109, s[10:11] offset:960
	global_load_dword v23, v109, s[10:11] offset:1216
	global_load_dword v112, v109, s[10:11] offset:1472
	global_load_dword v146, v109, s[10:11] offset:1728
	global_load_dword v147, v109, s[10:11] offset:1984
	s_waitcnt vmcnt(0)
	v_bfe_u32 v105, v114, 16, 1
	v_bfe_u32 v106, v115, 16, 1
	v_add3_u32 v114, v114, v105, s1
	v_add3_u32 v115, v115, v106, s1
	v_lshrrev_b32_e32 v114, 16, v114
	v_and_or_b32 v40, v115, s0, v114
	v_bfe_u32 v105, v116, 16, 1
	v_bfe_u32 v106, v117, 16, 1
	v_add3_u32 v116, v116, v105, s1
	v_add3_u32 v117, v117, v106, s1
	v_lshrrev_b32_e32 v116, 16, v116
	v_and_or_b32 v41, v117, s0, v116
	v_bfe_u32 v105, v118, 16, 1
	v_bfe_u32 v106, v119, 16, 1
	v_add3_u32 v118, v118, v105, s1
	v_add3_u32 v119, v119, v106, s1
	v_lshrrev_b32_e32 v118, 16, v118
	v_and_or_b32 v42, v119, s0, v118
	v_bfe_u32 v105, v120, 16, 1
	v_bfe_u32 v106, v121, 16, 1
	v_add3_u32 v120, v120, v105, s1
	v_add3_u32 v121, v121, v106, s1
	v_lshrrev_b32_e32 v120, 16, v120
	v_and_or_b32 v43, v121, s0, v120
	v_bfe_u32 v105, v122, 16, 1
	v_bfe_u32 v106, v123, 16, 1
	v_add3_u32 v122, v122, v105, s1
	v_add3_u32 v123, v123, v106, s1
	v_lshrrev_b32_e32 v122, 16, v122
	v_and_or_b32 v44, v123, s0, v122
	v_bfe_u32 v105, v124, 16, 1
	v_bfe_u32 v106, v125, 16, 1
	v_add3_u32 v124, v124, v105, s1
	v_add3_u32 v125, v125, v106, s1
	v_lshrrev_b32_e32 v124, 16, v124
	v_and_or_b32 v45, v125, s0, v124
	v_bfe_u32 v105, v126, 16, 1
	v_bfe_u32 v106, v127, 16, 1
	v_add3_u32 v126, v126, v105, s1
	v_add3_u32 v127, v127, v106, s1
	v_lshrrev_b32_e32 v126, 16, v126
	v_and_or_b32 v46, v127, s0, v126
	v_bfe_u32 v105, v128, 16, 1
	v_bfe_u32 v106, v129, 16, 1
	v_add3_u32 v128, v128, v105, s1
	v_add3_u32 v129, v129, v106, s1
	v_lshrrev_b32_e32 v128, 16, v128
	v_and_or_b32 v47, v129, s0, v128
	v_bfe_u32 v105, v130, 16, 1
	v_bfe_u32 v106, v131, 16, 1
	v_add3_u32 v130, v130, v105, s1
	v_add3_u32 v131, v131, v106, s1
	v_lshrrev_b32_e32 v130, 16, v130
	v_and_or_b32 v48, v131, s0, v130
	v_bfe_u32 v105, v132, 16, 1
	v_bfe_u32 v106, v133, 16, 1
	v_add3_u32 v132, v132, v105, s1
	v_add3_u32 v133, v133, v106, s1
	v_lshrrev_b32_e32 v132, 16, v132
	v_and_or_b32 v49, v133, s0, v132
	v_bfe_u32 v105, v134, 16, 1
	v_bfe_u32 v106, v135, 16, 1
	v_add3_u32 v134, v134, v105, s1
	v_add3_u32 v135, v135, v106, s1
	v_lshrrev_b32_e32 v134, 16, v134
	v_and_or_b32 v50, v135, s0, v134
	v_bfe_u32 v105, v136, 16, 1
	v_bfe_u32 v106, v137, 16, 1
	v_add3_u32 v136, v136, v105, s1
	v_add3_u32 v137, v137, v106, s1
	v_lshrrev_b32_e32 v136, 16, v136
	v_and_or_b32 v51, v137, s0, v136
; DI bf16_t f2bf(float x) { unsigned u = __float_as_uint(x); u += 0x7fffu + ((u >> 16) & 1u); return (bf16_t)(u >> 16); }
; DI float bf2f(bf16_t b) { return __uint_as_float(((unsigned)b) << 16); }
; DI float softplusf_(float z) { return fmaxf(z, 0.f) + __logf(1.f + __expf(-fabsf(z))); }
; template <bool PASS2>
; DI void lru_item(const Params& p, int l, int item, int lane, const bf16_t* xl, float* wxs) {
;     ...
;   unsigned wpa[32], wpx[32];
;   {
;     const float* pa = p.in[I_LRU_W_A] + ((size_t)l * 8 + blk) * 4096;
;     const float* px = p.in[I_LRU_W_X] + ((size_t)l * 8 + blk) * 4096;
;     int lo_ = lane; asm volatile("" : "+v"(lo_));
; #pragma unroll
;     for (int m = 0; m < 32; m++) {
;       wpa[m] = (unsigned)f2bf(pa[(2 * m) * 64 + lo_]) | ((unsigned)f2bf(pa[(2 * m + 1) * 64 + lo_]) << 16);
;       wpx[m] = (unsigned)f2bf(px[(2 * m) * 64 + lo_]) | ((unsigned)f2bf(px[(2 * m + 1) * 64 + lo_]) << 16);
;       if ((m & 7) == 7) asm volatile("" ::: "memory");
;     }
;   }
;   const float* cw = p.in[I_LRU_CONV_W] + (size_t)l * 4 * 512;
;   const float cw0 = cw[ch], cw1 = cw[512 + ch], cw2 = cw[1024 + ch], cw3 = cw[1536 + ch];
;   const float cb = p.in[I_LRU_CONV_B][l * 512 + ch];
;   const float ba = p.in[I_LRU_B_A][l * 512 + ch], bx = p.in[I_LRU_B_X][l * 512 + ch];
;   const float sp = softplusf_(-p.in[I_LRU_LAM][l * 512 + ch]);
;   const size_t tok0 = (size_t)b * SEQ + (size_t)c * LCL;
;   float x1 = 0.f, x2 = 0.f, x3 = 0.f;
;   if (c > 0) {
;     x1 = bf2f(xl[(tok0 - 1) * 512 + ch]); x2 = bf2f(xl[(tok0 - 2) * 512 + ch]); x3 = bf2f(xl[(tok0 - 3) * 512 + ch]);
;   }
;   float* st = p.lrust + ((size_t)(b * 512 + ch) * NCHL + c) * 2;
;   float hs = PASS2 ? st[1] : 0.f;
	v_bfe_u32 v105, v138, 16, 1
	v_bfe_u32 v106, v139, 16, 1
	v_add3_u32 v138, v138, v105, s1
	v_add3_u32 v139, v139, v106, s1
	v_lshrrev_b32_e32 v138, 16, v138
	v_and_or_b32 v52, v139, s0, v138
	v_bfe_u32 v105, v140, 16, 1
	v_bfe_u32 v106, v141, 16, 1
	v_add3_u32 v140, v140, v105, s1
	v_add3_u32 v141, v141, v106, s1
	v_lshrrev_b32_e32 v140, 16, v140
	v_and_or_b32 v53, v141, s0, v140
	v_bfe_u32 v105, v142, 16, 1
	v_bfe_u32 v106, v143, 16, 1
	v_add3_u32 v142, v142, v105, s1
	v_add3_u32 v143, v143, v106, s1
	v_lshrrev_b32_e32 v142, 16, v142
	v_and_or_b32 v54, v143, s0, v142
	v_bfe_u32 v105, v144, 16, 1
	v_bfe_u32 v106, v145, 16, 1
	v_add3_u32 v144, v144, v105, s1
	v_add3_u32 v145, v145, v106, s1
	v_lshrrev_b32_e32 v144, 16, v144
	v_and_or_b32 v55, v145, s0, v144
	v_bfe_u32 v105, v88, 16, 1
	v_bfe_u32 v106, v89, 16, 1
	v_add3_u32 v88, v88, v105, s1
	v_add3_u32 v89, v89, v106, s1
	v_lshrrev_b32_e32 v88, 16, v88
	v_and_or_b32 v72, v89, s0, v88
	v_bfe_u32 v105, v90, 16, 1
	v_bfe_u32 v106, v91, 16, 1
	v_add3_u32 v90, v90, v105, s1
	v_add3_u32 v91, v91, v106, s1
	v_lshrrev_b32_e32 v90, 16, v90
	v_and_or_b32 v73, v91, s0, v90
	v_bfe_u32 v105, v92, 16, 1
	v_bfe_u32 v106, v93, 16, 1
	v_add3_u32 v92, v92, v105, s1
	v_add3_u32 v93, v93, v106, s1
	v_lshrrev_b32_e32 v92, 16, v92
	v_and_or_b32 v74, v93, s0, v92
	v_bfe_u32 v105, v94, 16, 1
	v_bfe_u32 v106, v95, 16, 1
	v_add3_u32 v94, v94, v105, s1
	v_add3_u32 v95, v95, v106, s1
	v_lshrrev_b32_e32 v94, 16, v94
	v_and_or_b32 v75, v95, s0, v94
	v_bfe_u32 v105, v96, 16, 1
	v_bfe_u32 v106, v97, 16, 1
	v_add3_u32 v96, v96, v105, s1
	v_add3_u32 v97, v97, v106, s1
	v_lshrrev_b32_e32 v96, 16, v96
	v_and_or_b32 v76, v97, s0, v96
	v_bfe_u32 v105, v98, 16, 1
	v_bfe_u32 v106, v99, 16, 1
	v_add3_u32 v98, v98, v105, s1
	v_add3_u32 v99, v99, v106, s1
	v_lshrrev_b32_e32 v98, 16, v98
	v_and_or_b32 v77, v99, s0, v98
	v_bfe_u32 v105, v100, 16, 1
	v_bfe_u32 v106, v101, 16, 1
	v_add3_u32 v100, v100, v105, s1
	v_add3_u32 v101, v101, v106, s1
	v_lshrrev_b32_e32 v100, 16, v100
	v_and_or_b32 v78, v101, s0, v100
	v_bfe_u32 v105, v102, 16, 1
	v_bfe_u32 v106, v103, 16, 1
	v_add3_u32 v102, v102, v105, s1
	v_add3_u32 v103, v103, v106, s1
	v_lshrrev_b32_e32 v102, 16, v102
	v_and_or_b32 v79, v103, s0, v102
	v_bfe_u32 v105, v0, 16, 1
	v_bfe_u32 v106, v1, 16, 1
	v_add3_u32 v0, v0, v105, s1
	v_add3_u32 v1, v1, v106, s1
	v_lshrrev_b32_e32 v0, 16, v0
	v_and_or_b32 v80, v1, s0, v0
	v_bfe_u32 v105, v2, 16, 1
	v_bfe_u32 v106, v3, 16, 1
	v_add3_u32 v2, v2, v105, s1
	v_add3_u32 v3, v3, v106, s1
	v_lshrrev_b32_e32 v2, 16, v2
	v_and_or_b32 v81, v3, s0, v2
	v_bfe_u32 v105, v4, 16, 1
	v_bfe_u32 v106, v5, 16, 1
	v_add3_u32 v4, v4, v105, s1
	v_add3_u32 v5, v5, v106, s1
	v_lshrrev_b32_e32 v4, 16, v4
	v_and_or_b32 v82, v5, s0, v4
	v_bfe_u32 v105, v6, 16, 1
	v_bfe_u32 v106, v7, 16, 1
	v_add3_u32 v6, v6, v105, s1
	v_add3_u32 v7, v7, v106, s1
	v_lshrrev_b32_e32 v6, 16, v6
	v_and_or_b32 v83, v7, s0, v6
	v_bfe_u32 v105, v16, 16, 1
	v_bfe_u32 v106, v17, 16, 1
	v_add3_u32 v16, v16, v105, s1
	v_add3_u32 v17, v17, v106, s1
	v_lshrrev_b32_e32 v16, 16, v16
	v_and_or_b32 v84, v17, s0, v16
	v_bfe_u32 v105, v18, 16, 1
	v_bfe_u32 v106, v19, 16, 1
	v_add3_u32 v18, v18, v105, s1
	v_add3_u32 v19, v19, v106, s1
	v_lshrrev_b32_e32 v18, 16, v18
	v_and_or_b32 v85, v19, s0, v18
	v_bfe_u32 v105, v23, 16, 1
	v_bfe_u32 v106, v112, 16, 1
	v_add3_u32 v23, v23, v105, s1
	v_add3_u32 v112, v112, v106, s1
	v_lshrrev_b32_e32 v23, 16, v23
	v_and_or_b32 v86, v112, s0, v23
	v_bfe_u32 v105, v146, 16, 1
	v_bfe_u32 v106, v147, 16, 1
	v_add3_u32 v146, v146, v105, s1
	v_add3_u32 v147, v147, v106, s1
	v_lshrrev_b32_e32 v146, 16, v146
	v_and_or_b32 v87, v147, s0, v146
	s_add_u32 s0, s18, 0x0
	s_addc_u32 s1, s19, 0
	global_load_dword v14, v111, s[0:1]
	s_load_dwordx2 s[16:17], s[14:15], 0x130
	s_waitcnt lgkmcnt(0)
	s_add_u32 s0, s16, 0x0
	s_addc_u32 s1, s17, 0
	global_load_dword v15, v111, s[0:1]
	v_and_b32_e32 v112, 63, v210
	v_lshrrev_b32_e32 v146, 6, v210
	v_and_b32_e32 v146, 3, v146
	v_mul_u32_u24_e32 v146, 0x2200, v146
	v_lshl_add_u32 v106, v112, 1, v146
	v_and_b32_e32 v147, 15, v112
	v_lshrrev_b32_e32 v111, 4, v112
	v_mul_u32_u24_e32 v107, 0x90, v147
	v_lshl_add_u32 v107, v111, 4, v107
	v_add_u32_e32 v107, v146, v107
	v_add_u32_e32 v146, 0x8800, v146
	v_mul_u32_u24_e32 v108, 0x210, v111
	v_add_u32_e32 v108, v108, v147
	v_lshl_add_u32 v108, v108, 2, v146
	v_lshl_add_u32 v109, v112, 2, v146
	s_lshr_b32 s19, s12, 10
	s_and_b32 s17, s12, 127
	s_lshl_b32 s18, s19, 14
	s_lshl_b32 s20, s17, 7
	s_add_u32 s18, s18, s20
	s_lshl_b32 s20, s18, 10
	v_add_u32_e32 v105, s20, v104
	v_mov_b32_e32 v18, 0
	v_mov_b32_e32 v19, 0
	v_mov_b32_e32 v23, 0
	v_mov_b32_e32 v16, 0
	v_mov_b32_e32 v17, v105
	v_lshl_add_u32 v110, s19, 9, v110
	v_lshlrev_b32_e32 v110, 7, v110
	v_add_u32_e32 v110, s17, v110
	v_lshlrev_b32_e32 v110, 3, v110
	s_add_u32 s0, s2, 0x3158000
	s_addc_u32 s1, s3, 0
	global_load_dword v16, v110, s[0:1] offset:4
	s_add_u32 s10, s2, 0xf558000
	s_addc_u32 s11, s3, 0
	s_cmp_eq_u32 s17, 0
	s_cbranch_scc1 .Llrua2_nohist
	global_load_ushort v18, v105, s[6:7] offset:-1024
	global_load_ushort v19, v105, s[6:7] offset:-2048
	global_load_ushort v23, v105, s[6:7] offset:-3072
; DI bf16_t f2bf(float x) { unsigned u = __float_as_uint(x); u += 0x7fffu + ((u >> 16) & 1u); return (bf16_t)(u >> 16); }
; DI float bf2f(bf16_t b) { return __uint_as_float(((unsigned)b) << 16); }
; DI float softplusf_(float z) { return fmaxf(z, 0.f) + __logf(1.f + __expf(-fabsf(z))); }
; template <bool PASS2>
; DI void lru_item(const Params& p, int l, int item, int lane, const bf16_t* xl, float* wxs) {
;     ...
;   const float sp = softplusf_(-p.in[I_LRU_LAM][l * 512 + ch]);
;   const size_t tok0 = (size_t)b * SEQ + (size_t)c * LCL;
;   float x1 = 0.f, x2 = 0.f, x3 = 0.f;
;   if (c > 0) {
;     x1 = bf2f(xl[(tok0 - 1) * 512 + ch]); x2 = bf2f(xl[(tok0 - 2) * 512 + ch]); x3 = bf2f(xl[(tok0 - 3) * 512 + ch]);
;   }
;   float* st = p.lrust + ((size_t)(b * 512 + ch) * NCHL + c) * 2;
;   float hs = PASS2 ? st[1] : 0.f;
;   float aprod = 1.f;
;   float xn = bf2f(xl[tok0 * 512 + ch]);
; #pragma unroll 1
;   for (int t = 0; t < LCL; t++) {
;     const float x0 = xn;
;     if (t + 1 < LCL) xn = bf2f(xl[(tok0 + t + 1) * 512 + ch]);
;     const float xc = cw3 * x0 + cw2 * x1 + cw1 * x2 + cw0 * x3 + cb;
;     x3 = x2; x2 = x1; x1 = x0;
;     float ra0 = ba, ra1 = 0.f, rx0 = bx, rx1 = 0.f;
;     const unsigned xb16 = (unsigned)f2bf(xc);
;     const unsigned xnb = (unsigned)__shfl_xor((int)xb16, 1);
;     const unsigned xpk = xb16 | (xnb << 16);
.Llrua2_nohist:
	global_load_ushort v114, v105, s[6:7] offset:0
	global_load_ushort v115, v105, s[6:7] offset:1024
	global_load_ushort v116, v105, s[6:7] offset:2048
	global_load_ushort v117, v105, s[6:7] offset:3072
	v_add_u32_e32 v105, 0x1000, v105
	global_load_ushort v118, v105, s[6:7] offset:0
	global_load_ushort v119, v105, s[6:7] offset:1024
	global_load_ushort v120, v105, s[6:7] offset:2048
	global_load_ushort v121, v105, s[6:7] offset:3072
	v_add_u32_e32 v105, 0x1000, v105
	global_load_ushort v122, v105, s[6:7] offset:0
	global_load_ushort v123, v105, s[6:7] offset:1024
	global_load_ushort v124, v105, s[6:7] offset:2048
	global_load_ushort v125, v105, s[6:7] offset:3072
	v_add_u32_e32 v105, 0x1000, v105
	global_load_ushort v126, v105, s[6:7] offset:0
	global_load_ushort v127, v105, s[6:7] offset:1024
	global_load_ushort v128, v105, s[6:7] offset:2048
	global_load_ushort v129, v105, s[6:7] offset:3072
	v_add_u32_e32 v105, 0x1000, v105
	s_waitcnt vmcnt(0)
	v_lshlrev_b32_e32 v18, 16, v18
	v_lshlrev_b32_e32 v19, 16, v19
	v_lshlrev_b32_e32 v23, 16, v23
	v_and_b32_e32 v146, 0x7fffffff, v15
	v_mul_f32_e32 v146, 0xbfb8aa3b, v146
	v_exp_f32_e32 v146, v146
	v_max_f32_e64 v112, -v15, 0
	v_add_f32_e32 v146, 1.0, v146
	v_log_f32_e32 v146, v146
	s_nop 0
	v_mul_f32_e32 v146, 0x3f317218, v146
	v_add_f32_e32 v146, v112, v146
	v_mul_f32_e32 v15, 0xc138aa3b, v146
	s_mov_b32 s20, 0
	s_movk_i32 s1, 0x7fff
.Llrua2_loop:
	v_lshlrev_b32_e32 v114, 16, v114
	v_fma_f32 v88, v8, v23, v12
	v_fmac_f32_e32 v88, v9, v19
	v_fmac_f32_e32 v88, v10, v18
	v_fmac_f32_e32 v88, v11, v114
	v_bfe_u32 v110, v88, 16, 1
	v_add3_u32 v110, v88, v110, s1
	ds_write_b16_d16_hi v106, v110 offset:0
	v_lshlrev_b32_e32 v115, 16, v115
	v_fma_f32 v89, v8, v19, v12
	v_fmac_f32_e32 v89, v9, v18
	v_fmac_f32_e32 v89, v10, v114
	v_fmac_f32_e32 v89, v11, v115
	v_bfe_u32 v111, v89, 16, 1
	v_add3_u32 v111, v89, v111, s1
	ds_write_b16_d16_hi v106, v111 offset:144
	v_lshlrev_b32_e32 v116, 16, v116
	v_fma_f32 v90, v8, v18, v12
	v_fmac_f32_e32 v90, v9, v114
	v_fmac_f32_e32 v90, v10, v115
	v_fmac_f32_e32 v90, v11, v116
	v_bfe_u32 v110, v90, 16, 1
	v_add3_u32 v110, v90, v110, s1
	ds_write_b16_d16_hi v106, v110 offset:288
	v_lshlrev_b32_e32 v117, 16, v117
	v_fma_f32 v91, v8, v114, v12
	v_fmac_f32_e32 v91, v9, v115
	v_fmac_f32_e32 v91, v10, v116
	v_fmac_f32_e32 v91, v11, v117
	v_bfe_u32 v111, v91, 16, 1
	v_add3_u32 v111, v91, v111, s1
	ds_write_b16_d16_hi v106, v111 offset:432
	v_lshlrev_b32_e32 v118, 16, v118
	v_fma_f32 v92, v8, v115, v12
	v_fmac_f32_e32 v92, v9, v116
	v_fmac_f32_e32 v92, v10, v117
	v_fmac_f32_e32 v92, v11, v118
	v_bfe_u32 v110, v92, 16, 1
	v_add3_u32 v110, v92, v110, s1
	ds_write_b16_d16_hi v106, v110 offset:576
	v_lshlrev_b32_e32 v119, 16, v119
	v_fma_f32 v93, v8, v116, v12
	v_fmac_f32_e32 v93, v9, v117
	v_fmac_f32_e32 v93, v10, v118
	v_fmac_f32_e32 v93, v11, v119
	v_bfe_u32 v111, v93, 16, 1
	v_add3_u32 v111, v93, v111, s1
	ds_write_b16_d16_hi v106, v111 offset:720
	v_lshlrev_b32_e32 v120, 16, v120
	v_fma_f32 v94, v8, v117, v12
	v_fmac_f32_e32 v94, v9, v118
	v_fmac_f32_e32 v94, v10, v119
	v_fmac_f32_e32 v94, v11, v120
	v_bfe_u32 v110, v94, 16, 1
	v_add3_u32 v110, v94, v110, s1
	ds_write_b16_d16_hi v106, v110 offset:864
	v_lshlrev_b32_e32 v121, 16, v121
	v_fma_f32 v95, v8, v118, v12
	v_fmac_f32_e32 v95, v9, v119
	v_fmac_f32_e32 v95, v10, v120
	v_fmac_f32_e32 v95, v11, v121
	v_bfe_u32 v111, v95, 16, 1
	v_add3_u32 v111, v95, v111, s1
	ds_write_b16_d16_hi v106, v111 offset:1008
	v_lshlrev_b32_e32 v122, 16, v122
	v_fma_f32 v96, v8, v119, v12
	v_fmac_f32_e32 v96, v9, v120
	v_fmac_f32_e32 v96, v10, v121
	v_fmac_f32_e32 v96, v11, v122
	v_bfe_u32 v110, v96, 16, 1
	v_add3_u32 v110, v96, v110, s1
	ds_write_b16_d16_hi v106, v110 offset:1152
	v_lshlrev_b32_e32 v123, 16, v123
	v_fma_f32 v97, v8, v120, v12
	v_fmac_f32_e32 v97, v9, v121
	v_fmac_f32_e32 v97, v10, v122
	v_fmac_f32_e32 v97, v11, v123
	v_bfe_u32 v111, v97, 16, 1
	v_add3_u32 v111, v97, v111, s1
	ds_write_b16_d16_hi v106, v111 offset:1296
	v_lshlrev_b32_e32 v124, 16, v124
	v_fma_f32 v98, v8, v121, v12
	v_fmac_f32_e32 v98, v9, v122
	v_fmac_f32_e32 v98, v10, v123
	v_fmac_f32_e32 v98, v11, v124
	v_bfe_u32 v110, v98, 16, 1
	v_add3_u32 v110, v98, v110, s1
	ds_write_b16_d16_hi v106, v110 offset:1440
	v_lshlrev_b32_e32 v125, 16, v125
	v_fma_f32 v99, v8, v122, v12
	v_fmac_f32_e32 v99, v9, v123
	v_fmac_f32_e32 v99, v10, v124
	v_fmac_f32_e32 v99, v11, v125
	v_bfe_u32 v111, v99, 16, 1
	v_add3_u32 v111, v99, v111, s1
	ds_write_b16_d16_hi v106, v111 offset:1584
	v_lshlrev_b32_e32 v126, 16, v126
	v_fma_f32 v100, v8, v123, v12
	v_fmac_f32_e32 v100, v9, v124
	v_fmac_f32_e32 v100, v10, v125
	v_fmac_f32_e32 v100, v11, v126
	v_bfe_u32 v110, v100, 16, 1
	v_add3_u32 v110, v100, v110, s1
	ds_write_b16_d16_hi v106, v110 offset:1728
	v_lshlrev_b32_e32 v127, 16, v127
	v_fma_f32 v101, v8, v124, v12
	v_fmac_f32_e32 v101, v9, v125
	v_fmac_f32_e32 v101, v10, v126
	v_fmac_f32_e32 v101, v11, v127
	v_bfe_u32 v111, v101, 16, 1
	v_add3_u32 v111, v101, v111, s1
	ds_write_b16_d16_hi v106, v111 offset:1872
	v_lshlrev_b32_e32 v128, 16, v128
	v_fma_f32 v102, v8, v125, v12
	v_fmac_f32_e32 v102, v9, v126
	v_fmac_f32_e32 v102, v10, v127
	v_fmac_f32_e32 v102, v11, v128
	v_bfe_u32 v110, v102, 16, 1
	v_add3_u32 v110, v102, v110, s1
	ds_write_b16_d16_hi v106, v110 offset:2016
	v_lshlrev_b32_e32 v129, 16, v129
	v_fma_f32 v103, v8, v126, v12
	v_fmac_f32_e32 v103, v9, v127
	v_fmac_f32_e32 v103, v10, v128
	v_fmac_f32_e32 v103, v11, v129
	v_bfe_u32 v111, v103, 16, 1
	v_add3_u32 v111, v103, v111, s1
	ds_write_b16_d16_hi v106, v111 offset:2160
	v_mov_b32_e32 v23, v127
	v_mov_b32_e32 v19, v128
	v_mov_b32_e32 v18, v129
	ds_read_b128 v[0:3], v107
	ds_read_b128 v[4:7], v107 offset:64
	s_waitcnt lgkmcnt(0)
; DI bf16_t f2bf(float x) { unsigned u = __float_as_uint(x); u += 0x7fffu + ((u >> 16) & 1u); return (bf16_t)(u >> 16); }
; DI float bf2f(bf16_t b) { return __uint_as_float(((unsigned)b) << 16); }
; DI float sigmoidf_(float x) { return __builtin_amdgcn_rcpf(1.f + __expf(-x)); }
; template <bool PASS2>
; DI void lru_item(const Params& p, int l, int item, int lane, const bf16_t* xl, float* wxs) {
;     ...
;   for (int t = 0; t < LCL; t++) {
;     const float x0 = xn;
;     if (t + 1 < LCL) xn = bf2f(xl[(tok0 + t + 1) * 512 + ch]);
;     const float xc = cw3 * x0 + cw2 * x1 + cw1 * x2 + cw0 * x3 + cb;
;     x3 = x2; x2 = x1; x1 = x0;
;     float ra0 = ba, ra1 = 0.f, rx0 = bx, rx1 = 0.f;
;     const unsigned xb16 = (unsigned)f2bf(xc);
;     const unsigned xnb = (unsigned)__shfl_xor((int)xb16, 1);
;     const unsigned xpk = xb16 | (xnb << 16);
; #pragma unroll
;     for (int m = 0; m < 32; m += 2) {
;       const bf2_t xa = __builtin_bit_cast(bf2_t, (unsigned)__builtin_amdgcn_readlane((int)xpk, 2 * m));
;       const bf2_t xb = __builtin_bit_cast(bf2_t, (unsigned)__builtin_amdgcn_readlane((int)xpk, 2 * m + 2));
;       ra0 = __builtin_amdgcn_fdot2_f32_bf16(xa, __builtin_bit_cast(bf2_t, wpa[m]), ra0, false);
;       rx0 = __builtin_amdgcn_fdot2_f32_bf16(xa, __builtin_bit_cast(bf2_t, wpx[m]), rx0, false);
;       ra1 = __builtin_amdgcn_fdot2_f32_bf16(xb, __builtin_bit_cast(bf2_t, wpa[m + 1]), ra1, false);
;       rx1 = __builtin_amdgcn_fdot2_f32_bf16(xb, __builtin_bit_cast(bf2_t, wpx[m + 1]), rx1, false);
;     }
;     const float rg = sigmoidf_(ra0 + ra1), ig = sigmoidf_(rx0 + rx1);
;     const float la = -8.f * rg * sp;
;     const float a = __expf(la);
;     const float inp = sqrtf(fmaxf(1.f - a * a, 0.f)) * (ig * xc);
;     hs = a * hs + inp;
;     if (PASS2) p.yd[(tok0 + t) * 512 + ch] = f2bf(hs);
;     else aprod *= a;
;   }
	v_mfma_f32_16x16x32_bf16 v[114:117], v[0:3], v[24:27], 0
	v_mfma_f32_16x16x32_bf16 v[118:121], v[0:3], v[28:31], 0
	v_mfma_f32_16x16x32_bf16 v[122:125], v[0:3], v[32:35], 0
	v_mfma_f32_16x16x32_bf16 v[126:129], v[0:3], v[36:39], 0
	v_mfma_f32_16x16x32_bf16 v[130:133], v[0:3], v[40:43], 0
	v_mfma_f32_16x16x32_bf16 v[134:137], v[0:3], v[44:47], 0
	v_mfma_f32_16x16x32_bf16 v[138:141], v[0:3], v[48:51], 0
	v_mfma_f32_16x16x32_bf16 v[142:145], v[0:3], v[52:55], 0
	v_mfma_f32_16x16x32_bf16 v[114:117], v[4:7], v[56:59], v[114:117]
	v_mfma_f32_16x16x32_bf16 v[118:121], v[4:7], v[60:63], v[118:121]
	v_mfma_f32_16x16x32_bf16 v[122:125], v[4:7], v[64:67], v[122:125]
	v_mfma_f32_16x16x32_bf16 v[126:129], v[4:7], v[68:71], v[126:129]
	v_mfma_f32_16x16x32_bf16 v[130:133], v[4:7], v[72:75], v[130:133]
	v_mfma_f32_16x16x32_bf16 v[134:137], v[4:7], v[76:79], v[134:137]
	v_mfma_f32_16x16x32_bf16 v[138:141], v[4:7], v[80:83], v[138:141]
	v_mfma_f32_16x16x32_bf16 v[142:145], v[4:7], v[84:87], v[142:145]
	s_nop 7
	ds_write_b32 v108, v114 offset:0
	ds_write_b32 v108, v115 offset:528
	ds_write_b32 v108, v116 offset:1056
	ds_write_b32 v108, v117 offset:1584
	ds_write_b32 v108, v118 offset:64
	ds_write_b32 v108, v119 offset:592
	ds_write_b32 v108, v120 offset:1120
	ds_write_b32 v108, v121 offset:1648
	ds_write_b32 v108, v122 offset:128
	ds_write_b32 v108, v123 offset:656
	ds_write_b32 v108, v124 offset:1184
	ds_write_b32 v108, v125 offset:1712
	ds_write_b32 v108, v126 offset:192
	ds_write_b32 v108, v127 offset:720
	ds_write_b32 v108, v128 offset:1248
	ds_write_b32 v108, v129 offset:1776
	ds_write_b32 v108, v130 offset:256
	ds_write_b32 v108, v131 offset:784
	ds_write_b32 v108, v132 offset:1312
	ds_write_b32 v108, v133 offset:1840
	ds_write_b32 v108, v134 offset:320
	ds_write_b32 v108, v135 offset:848
	ds_write_b32 v108, v136 offset:1376
	ds_write_b32 v108, v137 offset:1904
	ds_write_b32 v108, v138 offset:384
	ds_write_b32 v108, v139 offset:912
	ds_write_b32 v108, v140 offset:1440
	ds_write_b32 v108, v141 offset:1968
	ds_write_b32 v108, v142 offset:448
	ds_write_b32 v108, v143 offset:976
	ds_write_b32 v108, v144 offset:1504
	ds_write_b32 v108, v145 offset:2032
	s_cmp_lt_u32 s20, 7
	s_cbranch_scc0 .Llrua2_noload
	global_load_ushort v114, v105, s[6:7] offset:0
	global_load_ushort v115, v105, s[6:7] offset:1024
	global_load_ushort v116, v105, s[6:7] offset:2048
	global_load_ushort v117, v105, s[6:7] offset:3072
	v_add_u32_e32 v105, 0x1000, v105
	global_load_ushort v118, v105, s[6:7] offset:0
	global_load_ushort v119, v105, s[6:7] offset:1024
	global_load_ushort v120, v105, s[6:7] offset:2048
	global_load_ushort v121, v105, s[6:7] offset:3072
	v_add_u32_e32 v105, 0x1000, v105
	global_load_ushort v122, v105, s[6:7] offset:0
	global_load_ushort v123, v105, s[6:7] offset:1024
	global_load_ushort v124, v105, s[6:7] offset:2048
	global_load_ushort v125, v105, s[6:7] offset:3072
	v_add_u32_e32 v105, 0x1000, v105
	global_load_ushort v126, v105, s[6:7] offset:0
	global_load_ushort v127, v105, s[6:7] offset:1024
	global_load_ushort v128, v105, s[6:7] offset:2048
	global_load_ushort v129, v105, s[6:7] offset:3072
	v_add_u32_e32 v105, 0x1000, v105
.Llrua2_noload:
	ds_read_b32 v0, v109 offset:0
	ds_read_b32 v1, v109 offset:256
	ds_read_b32 v2, v109 offset:528
	ds_read_b32 v3, v109 offset:784
	ds_read_b32 v4, v109 offset:1056
	ds_read_b32 v5, v109 offset:1312
	ds_read_b32 v6, v109 offset:1584
	ds_read_b32 v7, v109 offset:1840
	s_waitcnt lgkmcnt(0)
	v_add_f32_e32 v0, v0, v13
	v_add_f32_e32 v1, v1, v14
	v_mul_f32_e32 v0, 0xbfb8aa3b, v0
	v_mul_f32_e32 v1, 0xbfb8aa3b, v1
	v_exp_f32_e32 v0, v0
	v_exp_f32_e32 v1, v1
	v_add_f32_e32 v0, 1.0, v0
	v_add_f32_e32 v1, 1.0, v1
	v_rcp_f32_e32 v0, v0
	v_rcp_f32_e32 v1, v1
	v_mul_f32_e32 v112, v0, v15
	v_exp_f32_e32 v112, v112
	v_mul_f32_e32 v147, v1, v88
	v_fma_f32 v146, -v112, v112, 1.0
	v_max_f32_e32 v146, 0, v146
	v_sqrt_f32_e32 v146, v146
	s_nop 0
	v_mul_f32_e32 v147, v146, v147
	v_fma_f32 v16, v112, v16, v147
	v_bfe_u32 v146, v16, 16, 1
	v_add3_u32 v146, v16, v146, s1
	global_store_short_d16_hi v17, v146, s[10:11] offset:0
	v_add_f32_e32 v2, v2, v13
	v_add_f32_e32 v3, v3, v14
	v_mul_f32_e32 v2, 0xbfb8aa3b, v2
	v_mul_f32_e32 v3, 0xbfb8aa3b, v3
	v_exp_f32_e32 v2, v2
	v_exp_f32_e32 v3, v3
	v_add_f32_e32 v2, 1.0, v2
	v_add_f32_e32 v3, 1.0, v3
	v_rcp_f32_e32 v2, v2
	v_rcp_f32_e32 v3, v3
	v_mul_f32_e32 v112, v2, v15
	v_exp_f32_e32 v112, v112
	v_mul_f32_e32 v147, v3, v89
	v_fma_f32 v146, -v112, v112, 1.0
	v_max_f32_e32 v146, 0, v146
	v_sqrt_f32_e32 v146, v146
	s_nop 0
	v_mul_f32_e32 v147, v146, v147
	v_fma_f32 v16, v112, v16, v147
	v_bfe_u32 v146, v16, 16, 1
	v_add3_u32 v146, v16, v146, s1
	global_store_short_d16_hi v17, v146, s[10:11] offset:1024
	v_add_f32_e32 v4, v4, v13
	v_add_f32_e32 v5, v5, v14
	v_mul_f32_e32 v4, 0xbfb8aa3b, v4
	v_mul_f32_e32 v5, 0xbfb8aa3b, v5
	v_exp_f32_e32 v4, v4
	v_exp_f32_e32 v5, v5
	v_add_f32_e32 v4, 1.0, v4
	v_add_f32_e32 v5, 1.0, v5
	v_rcp_f32_e32 v4, v4
	v_rcp_f32_e32 v5, v5
	v_mul_f32_e32 v112, v4, v15
	v_exp_f32_e32 v112, v112
	v_mul_f32_e32 v147, v5, v90
	v_fma_f32 v146, -v112, v112, 1.0
	v_max_f32_e32 v146, 0, v146
	v_sqrt_f32_e32 v146, v146
	s_nop 0
	v_mul_f32_e32 v147, v146, v147
	v_fma_f32 v16, v112, v16, v147
	v_bfe_u32 v146, v16, 16, 1
	v_add3_u32 v146, v16, v146, s1
	global_store_short_d16_hi v17, v146, s[10:11] offset:2048
	v_add_f32_e32 v6, v6, v13
	v_add_f32_e32 v7, v7, v14
	v_mul_f32_e32 v6, 0xbfb8aa3b, v6
	v_mul_f32_e32 v7, 0xbfb8aa3b, v7
	v_exp_f32_e32 v6, v6
	v_exp_f32_e32 v7, v7
	v_add_f32_e32 v6, 1.0, v6
	v_add_f32_e32 v7, 1.0, v7
	v_rcp_f32_e32 v6, v6
	v_rcp_f32_e32 v7, v7
	v_mul_f32_e32 v112, v6, v15
	v_exp_f32_e32 v112, v112
	v_mul_f32_e32 v147, v7, v91
	v_fma_f32 v146, -v112, v112, 1.0
	v_max_f32_e32 v146, 0, v146
	v_sqrt_f32_e32 v146, v146
	s_nop 0
	v_mul_f32_e32 v147, v146, v147
	v_fma_f32 v16, v112, v16, v147
	v_bfe_u32 v146, v16, 16, 1
	v_add3_u32 v146, v16, v146, s1
	global_store_short_d16_hi v17, v146, s[10:11] offset:3072
	v_add_u32_e32 v17, 0x1000, v17
	ds_read_b32 v0, v109 offset:2112
	ds_read_b32 v1, v109 offset:2368
	ds_read_b32 v2, v109 offset:2640
	ds_read_b32 v3, v109 offset:2896
	ds_read_b32 v4, v109 offset:3168
	ds_read_b32 v5, v109 offset:3424
	ds_read_b32 v6, v109 offset:3696
	ds_read_b32 v7, v109 offset:3952
	s_waitcnt lgkmcnt(0)
; DI bf16_t f2bf(float x) { unsigned u = __float_as_uint(x); u += 0x7fffu + ((u >> 16) & 1u); return (bf16_t)(u >> 16); }
; DI float sigmoidf_(float x) { return __builtin_amdgcn_rcpf(1.f + __expf(-x)); }
; template <bool PASS2>
; DI void lru_item(const Params& p, int l, int item, int lane, const bf16_t* xl, float* wxs) {
;     ...
;     const float rg = sigmoidf_(ra0 + ra1), ig = sigmoidf_(rx0 + rx1);
;     const float la = -8.f * rg * sp;
;     const float a = __expf(la);
;     const float inp = sqrtf(fmaxf(1.f - a * a, 0.f)) * (ig * xc);
;     hs = a * hs + inp;
;     if (PASS2) p.yd[(tok0 + t) * 512 + ch] = f2bf(hs);
	v_add_f32_e32 v0, v0, v13
	v_add_f32_e32 v1, v1, v14
	v_mul_f32_e32 v0, 0xbfb8aa3b, v0
	v_mul_f32_e32 v1, 0xbfb8aa3b, v1
	v_exp_f32_e32 v0, v0
	v_exp_f32_e32 v1, v1
	v_add_f32_e32 v0, 1.0, v0
	v_add_f32_e32 v1, 1.0, v1
	v_rcp_f32_e32 v0, v0
	v_rcp_f32_e32 v1, v1
	v_mul_f32_e32 v112, v0, v15
	v_exp_f32_e32 v112, v112
	v_mul_f32_e32 v147, v1, v92
	v_fma_f32 v146, -v112, v112, 1.0
	v_max_f32_e32 v146, 0, v146
	v_sqrt_f32_e32 v146, v146
	s_nop 0
	v_mul_f32_e32 v147, v146, v147
	v_fma_f32 v16, v112, v16, v147
	v_bfe_u32 v146, v16, 16, 1
	v_add3_u32 v146, v16, v146, s1
	global_store_short_d16_hi v17, v146, s[10:11] offset:0
	v_add_f32_e32 v2, v2, v13
	v_add_f32_e32 v3, v3, v14
	v_mul_f32_e32 v2, 0xbfb8aa3b, v2
	v_mul_f32_e32 v3, 0xbfb8aa3b, v3
	v_exp_f32_e32 v2, v2
	v_exp_f32_e32 v3, v3
	v_add_f32_e32 v2, 1.0, v2
	v_add_f32_e32 v3, 1.0, v3
	v_rcp_f32_e32 v2, v2
	v_rcp_f32_e32 v3, v3
	v_mul_f32_e32 v112, v2, v15
	v_exp_f32_e32 v112, v112
	v_mul_f32_e32 v147, v3, v93
	v_fma_f32 v146, -v112, v112, 1.0
	v_max_f32_e32 v146, 0, v146
	v_sqrt_f32_e32 v146, v146
	s_nop 0
	v_mul_f32_e32 v147, v146, v147
	v_fma_f32 v16, v112, v16, v147
	v_bfe_u32 v146, v16, 16, 1
	v_add3_u32 v146, v16, v146, s1
	global_store_short_d16_hi v17, v146, s[10:11] offset:1024
	v_add_f32_e32 v4, v4, v13
	v_add_f32_e32 v5, v5, v14
	v_mul_f32_e32 v4, 0xbfb8aa3b, v4
	v_mul_f32_e32 v5, 0xbfb8aa3b, v5
	v_exp_f32_e32 v4, v4
	v_exp_f32_e32 v5, v5
	v_add_f32_e32 v4, 1.0, v4
	v_add_f32_e32 v5, 1.0, v5
	v_rcp_f32_e32 v4, v4
	v_rcp_f32_e32 v5, v5
	v_mul_f32_e32 v112, v4, v15
	v_exp_f32_e32 v112, v112
	v_mul_f32_e32 v147, v5, v94
	v_fma_f32 v146, -v112, v112, 1.0
	v_max_f32_e32 v146, 0, v146
	v_sqrt_f32_e32 v146, v146
	s_nop 0
	v_mul_f32_e32 v147, v146, v147
	v_fma_f32 v16, v112, v16, v147
	v_bfe_u32 v146, v16, 16, 1
	v_add3_u32 v146, v16, v146, s1
	global_store_short_d16_hi v17, v146, s[10:11] offset:2048
	v_add_f32_e32 v6, v6, v13
	v_add_f32_e32 v7, v7, v14
	v_mul_f32_e32 v6, 0xbfb8aa3b, v6
	v_mul_f32_e32 v7, 0xbfb8aa3b, v7
	v_exp_f32_e32 v6, v6
	v_exp_f32_e32 v7, v7
	v_add_f32_e32 v6, 1.0, v6
	v_add_f32_e32 v7, 1.0, v7
	v_rcp_f32_e32 v6, v6
	v_rcp_f32_e32 v7, v7
	v_mul_f32_e32 v112, v6, v15
	v_exp_f32_e32 v112, v112
	v_mul_f32_e32 v147, v7, v95
	v_fma_f32 v146, -v112, v112, 1.0
	v_max_f32_e32 v146, 0, v146
	v_sqrt_f32_e32 v146, v146
	s_nop 0
	v_mul_f32_e32 v147, v146, v147
	v_fma_f32 v16, v112, v16, v147
	v_bfe_u32 v146, v16, 16, 1
	v_add3_u32 v146, v16, v146, s1
	global_store_short_d16_hi v17, v146, s[10:11] offset:3072
	v_add_u32_e32 v17, 0x1000, v17
	ds_read_b32 v0, v109 offset:4224
	ds_read_b32 v1, v109 offset:4480
	ds_read_b32 v2, v109 offset:4752
	ds_read_b32 v3, v109 offset:5008
	ds_read_b32 v4, v109 offset:5280
	ds_read_b32 v5, v109 offset:5536
	ds_read_b32 v6, v109 offset:5808
	ds_read_b32 v7, v109 offset:6064
	s_waitcnt lgkmcnt(0)
; DI bf16_t f2bf(float x) { unsigned u = __float_as_uint(x); u += 0x7fffu + ((u >> 16) & 1u); return (bf16_t)(u >> 16); }
; DI float sigmoidf_(float x) { return __builtin_amdgcn_rcpf(1.f + __expf(-x)); }
; template <bool PASS2>
; DI void lru_item(const Params& p, int l, int item, int lane, const bf16_t* xl, float* wxs) {
;     ...
;     const float rg = sigmoidf_(ra0 + ra1), ig = sigmoidf_(rx0 + rx1);
;     const float la = -8.f * rg * sp;
;     const float a = __expf(la);
;     const float inp = sqrtf(fmaxf(1.f - a * a, 0.f)) * (ig * xc);
;     hs = a * hs + inp;
;     if (PASS2) p.yd[(tok0 + t) * 512 + ch] = f2bf(hs);
;     else aprod *= a;
;   }
; template <int Q>
; DI void run_phase(const Params& p, int l, bf16_t* sm) {
;     ...
;     for (int it = wave * gridDim.x + blockIdx.x; it < 16 * NCHL; it += gridDim.x * 4) lru_item<true>(p, l, __builtin_amdgcn_readfirstlane(it), lane, xlbuf, (float*)sm + wave * 4096);
	v_add_f32_e32 v0, v0, v13
	v_add_f32_e32 v1, v1, v14
	v_mul_f32_e32 v0, 0xbfb8aa3b, v0
	v_mul_f32_e32 v1, 0xbfb8aa3b, v1
	v_exp_f32_e32 v0, v0
	v_exp_f32_e32 v1, v1
	v_add_f32_e32 v0, 1.0, v0
	v_add_f32_e32 v1, 1.0, v1
	v_rcp_f32_e32 v0, v0
	v_rcp_f32_e32 v1, v1
	v_mul_f32_e32 v112, v0, v15
	v_exp_f32_e32 v112, v112
	v_mul_f32_e32 v147, v1, v96
	v_fma_f32 v146, -v112, v112, 1.0
	v_max_f32_e32 v146, 0, v146
	v_sqrt_f32_e32 v146, v146
	s_nop 0
	v_mul_f32_e32 v147, v146, v147
	v_fma_f32 v16, v112, v16, v147
	v_bfe_u32 v146, v16, 16, 1
	v_add3_u32 v146, v16, v146, s1
	global_store_short_d16_hi v17, v146, s[10:11] offset:0
	v_add_f32_e32 v2, v2, v13
	v_add_f32_e32 v3, v3, v14
	v_mul_f32_e32 v2, 0xbfb8aa3b, v2
	v_mul_f32_e32 v3, 0xbfb8aa3b, v3
	v_exp_f32_e32 v2, v2
	v_exp_f32_e32 v3, v3
	v_add_f32_e32 v2, 1.0, v2
	v_add_f32_e32 v3, 1.0, v3
	v_rcp_f32_e32 v2, v2
	v_rcp_f32_e32 v3, v3
	v_mul_f32_e32 v112, v2, v15
	v_exp_f32_e32 v112, v112
	v_mul_f32_e32 v147, v3, v97
	v_fma_f32 v146, -v112, v112, 1.0
	v_max_f32_e32 v146, 0, v146
	v_sqrt_f32_e32 v146, v146
	s_nop 0
	v_mul_f32_e32 v147, v146, v147
	v_fma_f32 v16, v112, v16, v147
	v_bfe_u32 v146, v16, 16, 1
	v_add3_u32 v146, v16, v146, s1
	global_store_short_d16_hi v17, v146, s[10:11] offset:1024
	v_add_f32_e32 v4, v4, v13
	v_add_f32_e32 v5, v5, v14
	v_mul_f32_e32 v4, 0xbfb8aa3b, v4
	v_mul_f32_e32 v5, 0xbfb8aa3b, v5
	v_exp_f32_e32 v4, v4
	v_exp_f32_e32 v5, v5
	v_add_f32_e32 v4, 1.0, v4
	v_add_f32_e32 v5, 1.0, v5
	v_rcp_f32_e32 v4, v4
	v_rcp_f32_e32 v5, v5
	v_mul_f32_e32 v112, v4, v15
	v_exp_f32_e32 v112, v112
	v_mul_f32_e32 v147, v5, v98
	v_fma_f32 v146, -v112, v112, 1.0
	v_max_f32_e32 v146, 0, v146
	v_sqrt_f32_e32 v146, v146
	s_nop 0
	v_mul_f32_e32 v147, v146, v147
	v_fma_f32 v16, v112, v16, v147
	v_bfe_u32 v146, v16, 16, 1
	v_add3_u32 v146, v16, v146, s1
	global_store_short_d16_hi v17, v146, s[10:11] offset:2048
	v_add_f32_e32 v6, v6, v13
	v_add_f32_e32 v7, v7, v14
	v_mul_f32_e32 v6, 0xbfb8aa3b, v6
	v_mul_f32_e32 v7, 0xbfb8aa3b, v7
	v_exp_f32_e32 v6, v6
	v_exp_f32_e32 v7, v7
	v_add_f32_e32 v6, 1.0, v6
	v_add_f32_e32 v7, 1.0, v7
	v_rcp_f32_e32 v6, v6
	v_rcp_f32_e32 v7, v7
	v_mul_f32_e32 v112, v6, v15
	v_exp_f32_e32 v112, v112
	v_mul_f32_e32 v147, v7, v99
	v_fma_f32 v146, -v112, v112, 1.0
	v_max_f32_e32 v146, 0, v146
	v_sqrt_f32_e32 v146, v146
	s_nop 0
	v_mul_f32_e32 v147, v146, v147
	v_fma_f32 v16, v112, v16, v147
	v_bfe_u32 v146, v16, 16, 1
	v_add3_u32 v146, v16, v146, s1
	global_store_short_d16_hi v17, v146, s[10:11] offset:3072
	v_add_u32_e32 v17, 0x1000, v17
	ds_read_b32 v0, v109 offset:6336
	ds_read_b32 v1, v109 offset:6592
	ds_read_b32 v2, v109 offset:6864
	ds_read_b32 v3, v109 offset:7120
	ds_read_b32 v4, v109 offset:7392
	ds_read_b32 v5, v109 offset:7648
	ds_read_b32 v6, v109 offset:7920
	ds_read_b32 v7, v109 offset:8176
	s_waitcnt lgkmcnt(0)
	v_add_f32_e32 v0, v0, v13
	v_add_f32_e32 v1, v1, v14
	v_mul_f32_e32 v0, 0xbfb8aa3b, v0
	v_mul_f32_e32 v1, 0xbfb8aa3b, v1
	v_exp_f32_e32 v0, v0
	v_exp_f32_e32 v1, v1
	v_add_f32_e32 v0, 1.0, v0
	v_add_f32_e32 v1, 1.0, v1
	v_rcp_f32_e32 v0, v0
	v_rcp_f32_e32 v1, v1
	v_mul_f32_e32 v112, v0, v15
	v_exp_f32_e32 v112, v112
	v_mul_f32_e32 v147, v1, v100
	v_fma_f32 v146, -v112, v112, 1.0
	v_max_f32_e32 v146, 0, v146
	v_sqrt_f32_e32 v146, v146
	s_nop 0
	v_mul_f32_e32 v147, v146, v147
	v_fma_f32 v16, v112, v16, v147
	v_bfe_u32 v146, v16, 16, 1
	v_add3_u32 v146, v16, v146, s1
	global_store_short_d16_hi v17, v146, s[10:11] offset:0
	v_add_f32_e32 v2, v2, v13
	v_add_f32_e32 v3, v3, v14
	v_mul_f32_e32 v2, 0xbfb8aa3b, v2
	v_mul_f32_e32 v3, 0xbfb8aa3b, v3
	v_exp_f32_e32 v2, v2
	v_exp_f32_e32 v3, v3
	v_add_f32_e32 v2, 1.0, v2
	v_add_f32_e32 v3, 1.0, v3
	v_rcp_f32_e32 v2, v2
	v_rcp_f32_e32 v3, v3
	v_mul_f32_e32 v112, v2, v15
	v_exp_f32_e32 v112, v112
	v_mul_f32_e32 v147, v3, v101
	v_fma_f32 v146, -v112, v112, 1.0
	v_max_f32_e32 v146, 0, v146
	v_sqrt_f32_e32 v146, v146
	s_nop 0
	v_mul_f32_e32 v147, v146, v147
	v_fma_f32 v16, v112, v16, v147
	v_bfe_u32 v146, v16, 16, 1
	v_add3_u32 v146, v16, v146, s1
	global_store_short_d16_hi v17, v146, s[10:11] offset:1024
	v_add_f32_e32 v4, v4, v13
	v_add_f32_e32 v5, v5, v14
	v_mul_f32_e32 v4, 0xbfb8aa3b, v4
	v_mul_f32_e32 v5, 0xbfb8aa3b, v5
	v_exp_f32_e32 v4, v4
	v_exp_f32_e32 v5, v5
	v_add_f32_e32 v4, 1.0, v4
	v_add_f32_e32 v5, 1.0, v5
	v_rcp_f32_e32 v4, v4
	v_rcp_f32_e32 v5, v5
	v_mul_f32_e32 v112, v4, v15
	v_exp_f32_e32 v112, v112
	v_mul_f32_e32 v147, v5, v102
	v_fma_f32 v146, -v112, v112, 1.0
	v_max_f32_e32 v146, 0, v146
	v_sqrt_f32_e32 v146, v146
	s_nop 0
	v_mul_f32_e32 v147, v146, v147
	v_fma_f32 v16, v112, v16, v147
	v_bfe_u32 v146, v16, 16, 1
	v_add3_u32 v146, v16, v146, s1
	global_store_short_d16_hi v17, v146, s[10:11] offset:2048
	v_add_f32_e32 v6, v6, v13
	v_add_f32_e32 v7, v7, v14
	v_mul_f32_e32 v6, 0xbfb8aa3b, v6
	v_mul_f32_e32 v7, 0xbfb8aa3b, v7
	v_exp_f32_e32 v6, v6
	v_exp_f32_e32 v7, v7
	v_add_f32_e32 v6, 1.0, v6
	v_add_f32_e32 v7, 1.0, v7
	v_rcp_f32_e32 v6, v6
	v_rcp_f32_e32 v7, v7
	v_mul_f32_e32 v112, v6, v15
	v_exp_f32_e32 v112, v112
	v_mul_f32_e32 v147, v7, v103
	v_fma_f32 v146, -v112, v112, 1.0
	v_max_f32_e32 v146, 0, v146
	v_sqrt_f32_e32 v146, v146
	s_nop 0
	v_mul_f32_e32 v147, v146, v147
	v_fma_f32 v16, v112, v16, v147
	v_bfe_u32 v146, v16, 16, 1
	v_add3_u32 v146, v16, v146, s1
	global_store_short_d16_hi v17, v146, s[10:11] offset:3072
	v_add_u32_e32 v17, 0x1000, v17
	s_add_u32 s20, s20, 1
	s_waitcnt vmcnt(16)
	s_cmp_lt_u32 s20, 8
	s_cbranch_scc1 .Llrua2_loop
	s_waitcnt vmcnt(0)
	s_add_u32 s12, s12, s13
	s_cmpk_lt_i32 s12, 0x800
	s_cbranch_scc1 .Llrua2_item

; DI bf16_t f2bf(float x) { unsigned u = __float_as_uint(x); u += 0x7fffu + ((u >> 16) & 1u); return (bf16_t)(u >> 16); }
; template <bool PASS2>
; DI void lru_item(const Params& p, int l, int item, int lane, const bf16_t* xl, float* wxs) {
;   const int b = item / (8 * NCHL), blk = (item / NCHL) % 8, c = item % NCHL;
;   const int ch = blk * 64 + lane;
;   unsigned wpa[32], wpx[32];
;   {
;     const float* pa = p.in[I_LRU_W_A] + ((size_t)l * 8 + blk) * 4096;
;     const float* px = p.in[I_LRU_W_X] + ((size_t)l * 8 + blk) * 4096;
;     int lo_ = lane; asm volatile("" : "+v"(lo_));
; #pragma unroll
;     for (int m = 0; m < 32; m++) {
;       wpa[m] = (unsigned)f2bf(pa[(2 * m) * 64 + lo_]) | ((unsigned)f2bf(pa[(2 * m + 1) * 64 + lo_]) << 16);
;       wpx[m] = (unsigned)f2bf(px[(2 * m) * 64 + lo_]) | ((unsigned)f2bf(px[(2 * m + 1) * 64 + lo_]) << 16);
;       if ((m & 7) == 7) asm volatile("" ::: "memory");
;     }
;   }
;   const float* cw = p.in[I_LRU_CONV_W] + (size_t)l * 4 * 512;
;   const float cw0 = cw[ch], cw1 = cw[512 + ch], cw2 = cw[1024 + ch], cw3 = cw[1536 + ch];
;   const float cb = p.in[I_LRU_CONV_B][l * 512 + ch];
;   const float ba = p.in[I_LRU_B_A][l * 512 + ch], bx = p.in[I_LRU_B_X][l * 512 + ch];
; template <int Q>
; DI void run_phase(const Params& p, int l, bf16_t* sm) {
;     ...
;     for (int it = wave * gridDim.x + blockIdx.x; it < 16 * NCHL; it += gridDim.x * 4) lru_item<false>(p, l, __builtin_amdgcn_readfirstlane(it), lane, xlbuf, (float*)sm + wave * 4096);
.LBB0_2387:
	s_or_b64 exec, exec, s[0:1]
	v_mov_b32_e32 v16, v210
	s_waitcnt lgkmcnt(0)
	v_mov_b32_e32 v0, v210
	s_barrier
	v_readlane_b32 s0, v252, 1
	v_bfe_u32 v17, v0, 6, 2
	v_and_b32_e32 v81, 63, v16
	v_mul_lo_u32 v0, v17, s0
	v_readlane_b32 s0, v252, 26
	v_readlane_b32 s1, v252, 2
	s_nop 0
	v_add_u32_e32 v18, s0, v0
	s_movk_i32 s0, 0x800
	v_cmp_gt_i32_e32 vcc, s0, v18
	s_and_saveexec_b64 s[8:9], vcc
	s_cbranch_execz .LBB0_2396
	v_readlane_b32 s14, v252, 3
	v_readlane_b32 s15, v252, 4
	v_readlane_b32 s13, v252, 1
	v_readfirstlane_b32 s12, v18
	s_sub_u32 s14, s14, 0x180
	s_subb_u32 s15, s15, 0
	s_lshl_b32 s13, s13, 2
	s_load_dwordx2 s[2:3], s[14:15], 0x170
	s_waitcnt lgkmcnt(0)
	s_add_u32 s6, s2, 0x13558000
	s_addc_u32 s7, s3, 0
.Llrub1_item:
	s_bfe_u32 s16, s12, 0x30007
	v_and_b32_e32 v78, 63, v210
	v_lshl_add_u32 v78, s16, 6, v78
	v_lshlrev_b32_e32 v72, 1, v78
	v_lshlrev_b32_e32 v79, 2, v78
	v_and_b32_e32 v80, 63, v210
	v_lshrrev_b32_e32 v146, 4, v80
	v_and_b32_e32 v80, 15, v80
	v_lshlrev_b32_e32 v76, 11, v146
	v_lshl_add_u32 v76, v80, 2, v76
	v_add_u32_e32 v77, 0x2000, v76
	s_load_dwordx4 s[16:19], s[14:15], 0x100
	s_waitcnt lgkmcnt(0)
	s_add_u32 s0, s16, 0x2000
	s_addc_u32 s1, s17, 0
	global_load_dword v8, v79, s[0:1]
	global_load_dword v9, v79, s[0:1] offset:2048
	s_add_u32 s0, s0, 0x1000
	s_addc_u32 s1, s1, 0
	global_load_dword v10, v79, s[0:1]
	global_load_dword v11, v79, s[0:1] offset:2048
	s_add_u32 s0, s18, 0x800
	s_addc_u32 s1, s19, 0
	global_load_dword v12, v79, s[0:1]
	s_load_dwordx4 s[16:19], s[14:15], 0x110
	s_waitcnt lgkmcnt(0)
	s_add_u32 s0, s18, 0x800
	s_addc_u32 s1, s19, 0
	global_load_dword v13, v79, s[0:1]
	s_bfe_u32 s20, s12, 0x30007
	s_add_u32 s20, s20, 8
	s_lshl_b32 s20, s20, 14
	s_add_u32 s10, s16, s20
	s_addc_u32 s11, s17, 0
	s_load_dwordx4 s[16:19], s[14:15], 0x120
	s_mov_b32 s0, 0xffff0000
	s_movk_i32 s1, 0x7fff
	global_load_dword v20, v76, s[10:11] offset:0
	global_load_dword v21, v76, s[10:11] offset:256
	global_load_dword v22, v76, s[10:11] offset:512
	global_load_dword v23, v76, s[10:11] offset:768
	global_load_dword v24, v76, s[10:11] offset:1024
	global_load_dword v25, v76, s[10:11] offset:1280
	global_load_dword v26, v76, s[10:11] offset:1536
	global_load_dword v27, v76, s[10:11] offset:1792
	global_load_dword v28, v76, s[10:11] offset:64
	global_load_dword v29, v76, s[10:11] offset:320
	global_load_dword v30, v76, s[10:11] offset:576
	global_load_dword v31, v76, s[10:11] offset:832
	global_load_dword v32, v76, s[10:11] offset:1088
	global_load_dword v33, v76, s[10:11] offset:1344
	global_load_dword v34, v76, s[10:11] offset:1600
	global_load_dword v35, v76, s[10:11] offset:1856
	global_load_dword v36, v76, s[10:11] offset:128
	global_load_dword v37, v76, s[10:11] offset:384
	global_load_dword v38, v76, s[10:11] offset:640
	global_load_dword v39, v76, s[10:11] offset:896
	global_load_dword v40, v76, s[10:11] offset:1152
	global_load_dword v41, v76, s[10:11] offset:1408
	global_load_dword v42, v76, s[10:11] offset:1664
	global_load_dword v43, v76, s[10:11] offset:1920
	global_load_dword v44, v76, s[10:11] offset:192
	global_load_dword v45, v76, s[10:11] offset:448
	global_load_dword v46, v76, s[10:11] offset:704
	global_load_dword v47, v76, s[10:11] offset:960
	global_load_dword v48, v76, s[10:11] offset:1216
	global_load_dword v49, v76, s[10:11] offset:1472
	global_load_dword v50, v76, s[10:11] offset:1728
	global_load_dword v51, v76, s[10:11] offset:1984
	global_load_dword v52, v77, s[10:11] offset:0
	global_load_dword v53, v77, s[10:11] offset:256
	global_load_dword v54, v77, s[10:11] offset:512
	global_load_dword v55, v77, s[10:11] offset:768
	global_load_dword v56, v77, s[10:11] offset:1024
	global_load_dword v57, v77, s[10:11] offset:1280
	global_load_dword v58, v77, s[10:11] offset:1536
	global_load_dword v59, v77, s[10:11] offset:1792
	global_load_dword v60, v77, s[10:11] offset:64
	global_load_dword v61, v77, s[10:11] offset:320
	global_load_dword v62, v77, s[10:11] offset:576
	global_load_dword v63, v77, s[10:11] offset:832
	global_load_dword v64, v77, s[10:11] offset:1088
	global_load_dword v65, v77, s[10:11] offset:1344
	global_load_dword v66, v77, s[10:11] offset:1600
	global_load_dword v67, v77, s[10:11] offset:1856
	global_load_dword v0, v77, s[10:11] offset:128
	global_load_dword v1, v77, s[10:11] offset:384
	global_load_dword v2, v77, s[10:11] offset:640
	global_load_dword v3, v77, s[10:11] offset:896
	global_load_dword v4, v77, s[10:11] offset:1152
	global_load_dword v5, v77, s[10:11] offset:1408
	global_load_dword v6, v77, s[10:11] offset:1664
	global_load_dword v7, v77, s[10:11] offset:1920
	global_load_dword v19, v77, s[10:11] offset:192
	global_load_dword v68, v77, s[10:11] offset:448
	global_load_dword v69, v77, s[10:11] offset:704
	global_load_dword v70, v77, s[10:11] offset:960
	global_load_dword v71, v77, s[10:11] offset:1216
	global_load_dword v80, v77, s[10:11] offset:1472
	global_load_dword v146, v77, s[10:11] offset:1728
	global_load_dword v147, v77, s[10:11] offset:1984
	s_waitcnt vmcnt(0)
; DI bf16_t f2bf(float x) { unsigned u = __float_as_uint(x); u += 0x7fffu + ((u >> 16) & 1u); return (bf16_t)(u >> 16); }
; template <bool PASS2>
; DI void lru_item(const Params& p, int l, int item, int lane, const bf16_t* xl, float* wxs) {
;     ...
;   unsigned wpa[32], wpx[32];
;   {
;     const float* pa = p.in[I_LRU_W_A] + ((size_t)l * 8 + blk) * 4096;
;     const float* px = p.in[I_LRU_W_X] + ((size_t)l * 8 + blk) * 4096;
;     int lo_ = lane; asm volatile("" : "+v"(lo_));
; #pragma unroll
;     for (int m = 0; m < 32; m++) {
;       wpa[m] = (unsigned)f2bf(pa[(2 * m) * 64 + lo_]) | ((unsigned)f2bf(pa[(2 * m + 1) * 64 + lo_]) << 16);
;       wpx[m] = (unsigned)f2bf(px[(2 * m) * 64 + lo_]) | ((unsigned)f2bf(px[(2 * m + 1) * 64 + lo_]) << 16);
;       if ((m & 7) == 7) asm volatile("" ::: "memory");
;     }
;   }
	v_bfe_u32 v73, v20, 16, 1
	v_bfe_u32 v74, v21, 16, 1
	v_add3_u32 v20, v20, v73, s1
	v_add3_u32 v21, v21, v74, s1
	v_lshrrev_b32_e32 v20, 16, v20
	v_and_or_b32 v82, v21, s0, v20
	v_bfe_u32 v73, v22, 16, 1
	v_bfe_u32 v74, v23, 16, 1
	v_add3_u32 v22, v22, v73, s1
	v_add3_u32 v23, v23, v74, s1
	v_lshrrev_b32_e32 v22, 16, v22
	v_and_or_b32 v83, v23, s0, v22
	v_bfe_u32 v73, v24, 16, 1
	v_bfe_u32 v74, v25, 16, 1
	v_add3_u32 v24, v24, v73, s1
	v_add3_u32 v25, v25, v74, s1
	v_lshrrev_b32_e32 v24, 16, v24
	v_and_or_b32 v84, v25, s0, v24
	v_bfe_u32 v73, v26, 16, 1
	v_bfe_u32 v74, v27, 16, 1
	v_add3_u32 v26, v26, v73, s1
	v_add3_u32 v27, v27, v74, s1
	v_lshrrev_b32_e32 v26, 16, v26
	v_and_or_b32 v85, v27, s0, v26
	v_bfe_u32 v73, v28, 16, 1
	v_bfe_u32 v74, v29, 16, 1
	v_add3_u32 v28, v28, v73, s1
	v_add3_u32 v29, v29, v74, s1
	v_lshrrev_b32_e32 v28, 16, v28
	v_and_or_b32 v86, v29, s0, v28
	v_bfe_u32 v73, v30, 16, 1
	v_bfe_u32 v74, v31, 16, 1
	v_add3_u32 v30, v30, v73, s1
	v_add3_u32 v31, v31, v74, s1
	v_lshrrev_b32_e32 v30, 16, v30
	v_and_or_b32 v87, v31, s0, v30
	v_bfe_u32 v73, v32, 16, 1
	v_bfe_u32 v74, v33, 16, 1
	v_add3_u32 v32, v32, v73, s1
	v_add3_u32 v33, v33, v74, s1
	v_lshrrev_b32_e32 v32, 16, v32
	v_and_or_b32 v88, v33, s0, v32
	v_bfe_u32 v73, v34, 16, 1
	v_bfe_u32 v74, v35, 16, 1
	v_add3_u32 v34, v34, v73, s1
	v_add3_u32 v35, v35, v74, s1
	v_lshrrev_b32_e32 v34, 16, v34
	v_and_or_b32 v89, v35, s0, v34
	v_bfe_u32 v73, v36, 16, 1
	v_bfe_u32 v74, v37, 16, 1
	v_add3_u32 v36, v36, v73, s1
	v_add3_u32 v37, v37, v74, s1
	v_lshrrev_b32_e32 v36, 16, v36
	v_and_or_b32 v90, v37, s0, v36
	v_bfe_u32 v73, v38, 16, 1
	v_bfe_u32 v74, v39, 16, 1
	v_add3_u32 v38, v38, v73, s1
	v_add3_u32 v39, v39, v74, s1
	v_lshrrev_b32_e32 v38, 16, v38
	v_and_or_b32 v91, v39, s0, v38
	v_bfe_u32 v73, v40, 16, 1
	v_bfe_u32 v74, v41, 16, 1
	v_add3_u32 v40, v40, v73, s1
	v_add3_u32 v41, v41, v74, s1
	v_lshrrev_b32_e32 v40, 16, v40
	v_and_or_b32 v92, v41, s0, v40
	v_bfe_u32 v73, v42, 16, 1
	v_bfe_u32 v74, v43, 16, 1
	v_add3_u32 v42, v42, v73, s1
	v_add3_u32 v43, v43, v74, s1
	v_lshrrev_b32_e32 v42, 16, v42
	v_and_or_b32 v93, v43, s0, v42
	v_bfe_u32 v73, v44, 16, 1
	v_bfe_u32 v74, v45, 16, 1
	v_add3_u32 v44, v44, v73, s1
	v_add3_u32 v45, v45, v74, s1
	v_lshrrev_b32_e32 v44, 16, v44
	v_and_or_b32 v94, v45, s0, v44
	v_bfe_u32 v73, v46, 16, 1
	v_bfe_u32 v74, v47, 16, 1
	v_add3_u32 v46, v46, v73, s1
	v_add3_u32 v47, v47, v74, s1
	v_lshrrev_b32_e32 v46, 16, v46
	v_and_or_b32 v95, v47, s0, v46
	v_bfe_u32 v73, v48, 16, 1
	v_bfe_u32 v74, v49, 16, 1
	v_add3_u32 v48, v48, v73, s1
	v_add3_u32 v49, v49, v74, s1
	v_lshrrev_b32_e32 v48, 16, v48
	v_and_or_b32 v96, v49, s0, v48
	v_bfe_u32 v73, v50, 16, 1
	v_bfe_u32 v74, v51, 16, 1
	v_add3_u32 v50, v50, v73, s1
	v_add3_u32 v51, v51, v74, s1
	v_lshrrev_b32_e32 v50, 16, v50
	v_and_or_b32 v97, v51, s0, v50
	v_bfe_u32 v73, v52, 16, 1
	v_bfe_u32 v74, v53, 16, 1
	v_add3_u32 v52, v52, v73, s1
	v_add3_u32 v53, v53, v74, s1
	v_lshrrev_b32_e32 v52, 16, v52
	v_and_or_b32 v114, v53, s0, v52
	v_bfe_u32 v73, v54, 16, 1
	v_bfe_u32 v74, v55, 16, 1
	v_add3_u32 v54, v54, v73, s1
	v_add3_u32 v55, v55, v74, s1
	v_lshrrev_b32_e32 v54, 16, v54
	v_and_or_b32 v115, v55, s0, v54
	v_bfe_u32 v73, v56, 16, 1
	v_bfe_u32 v74, v57, 16, 1
	v_add3_u32 v56, v56, v73, s1
	v_add3_u32 v57, v57, v74, s1
	v_lshrrev_b32_e32 v56, 16, v56
	v_and_or_b32 v116, v57, s0, v56
	v_bfe_u32 v73, v58, 16, 1
	v_bfe_u32 v74, v59, 16, 1
	v_add3_u32 v58, v58, v73, s1
	v_add3_u32 v59, v59, v74, s1
	v_lshrrev_b32_e32 v58, 16, v58
	v_and_or_b32 v117, v59, s0, v58
	v_bfe_u32 v73, v60, 16, 1
	v_bfe_u32 v74, v61, 16, 1
	v_add3_u32 v60, v60, v73, s1
	v_add3_u32 v61, v61, v74, s1
	v_lshrrev_b32_e32 v60, 16, v60
	v_and_or_b32 v118, v61, s0, v60
	v_bfe_u32 v73, v62, 16, 1
	v_bfe_u32 v74, v63, 16, 1
	v_add3_u32 v62, v62, v73, s1
	v_add3_u32 v63, v63, v74, s1
	v_lshrrev_b32_e32 v62, 16, v62
	v_and_or_b32 v119, v63, s0, v62
	v_bfe_u32 v73, v64, 16, 1
	v_bfe_u32 v74, v65, 16, 1
	v_add3_u32 v64, v64, v73, s1
	v_add3_u32 v65, v65, v74, s1
	v_lshrrev_b32_e32 v64, 16, v64
	v_and_or_b32 v120, v65, s0, v64
	v_bfe_u32 v73, v66, 16, 1
	v_bfe_u32 v74, v67, 16, 1
	v_add3_u32 v66, v66, v73, s1
	v_add3_u32 v67, v67, v74, s1
	v_lshrrev_b32_e32 v66, 16, v66
	v_and_or_b32 v121, v67, s0, v66
	v_bfe_u32 v73, v0, 16, 1
	v_bfe_u32 v74, v1, 16, 1
	v_add3_u32 v0, v0, v73, s1
	v_add3_u32 v1, v1, v74, s1
	v_lshrrev_b32_e32 v0, 16, v0
	v_and_or_b32 v122, v1, s0, v0
	v_bfe_u32 v73, v2, 16, 1
	v_bfe_u32 v74, v3, 16, 1
	v_add3_u32 v2, v2, v73, s1
	v_add3_u32 v3, v3, v74, s1
	v_lshrrev_b32_e32 v2, 16, v2
	v_and_or_b32 v123, v3, s0, v2
	v_bfe_u32 v73, v4, 16, 1
	v_bfe_u32 v74, v5, 16, 1
	v_add3_u32 v4, v4, v73, s1
	v_add3_u32 v5, v5, v74, s1
	v_lshrrev_b32_e32 v4, 16, v4
	v_and_or_b32 v124, v5, s0, v4
	v_bfe_u32 v73, v6, 16, 1
	v_bfe_u32 v74, v7, 16, 1
	v_add3_u32 v6, v6, v73, s1
	v_add3_u32 v7, v7, v74, s1
	v_lshrrev_b32_e32 v6, 16, v6
	v_and_or_b32 v125, v7, s0, v6
	v_bfe_u32 v73, v19, 16, 1
	v_bfe_u32 v74, v68, 16, 1
	v_add3_u32 v19, v19, v73, s1
	v_add3_u32 v68, v68, v74, s1
	v_lshrrev_b32_e32 v19, 16, v19
	v_and_or_b32 v126, v68, s0, v19
	v_bfe_u32 v73, v69, 16, 1
	v_bfe_u32 v74, v70, 16, 1
	v_add3_u32 v69, v69, v73, s1
	v_add3_u32 v70, v70, v74, s1
	v_lshrrev_b32_e32 v69, 16, v69
	v_and_or_b32 v127, v70, s0, v69
	v_bfe_u32 v73, v71, 16, 1
	v_bfe_u32 v74, v80, 16, 1
	v_add3_u32 v71, v71, v73, s1
	v_add3_u32 v80, v80, v74, s1
	v_lshrrev_b32_e32 v71, 16, v71
	v_and_or_b32 v128, v80, s0, v71
	v_bfe_u32 v73, v146, 16, 1
	v_bfe_u32 v74, v147, 16, 1
	v_add3_u32 v146, v146, v73, s1
	v_add3_u32 v147, v147, v74, s1
	v_lshrrev_b32_e32 v146, 16, v146
	v_and_or_b32 v129, v147, s0, v146
	s_waitcnt lgkmcnt(0)
; DI bf16_t f2bf(float x) { unsigned u = __float_as_uint(x); u += 0x7fffu + ((u >> 16) & 1u); return (bf16_t)(u >> 16); }
; template <bool PASS2>
; DI void lru_item(const Params& p, int l, int item, int lane, const bf16_t* xl, float* wxs) {
;     ...
;   unsigned wpa[32], wpx[32];
;   {
;     const float* pa = p.in[I_LRU_W_A] + ((size_t)l * 8 + blk) * 4096;
;     const float* px = p.in[I_LRU_W_X] + ((size_t)l * 8 + blk) * 4096;
;     int lo_ = lane; asm volatile("" : "+v"(lo_));
; #pragma unroll
;     for (int m = 0; m < 32; m++) {
;       wpa[m] = (unsigned)f2bf(pa[(2 * m) * 64 + lo_]) | ((unsigned)f2bf(pa[(2 * m + 1) * 64 + lo_]) << 16);
;       wpx[m] = (unsigned)f2bf(px[(2 * m) * 64 + lo_]) | ((unsigned)f2bf(px[(2 * m + 1) * 64 + lo_]) << 16);
;       if ((m & 7) == 7) asm volatile("" ::: "memory");
;     }
;   }
	s_add_u32 s10, s16, s20
	s_addc_u32 s11, s17, 0
	global_load_dword v20, v76, s[10:11] offset:0
	global_load_dword v21, v76, s[10:11] offset:256
	global_load_dword v22, v76, s[10:11] offset:512
	global_load_dword v23, v76, s[10:11] offset:768
	global_load_dword v24, v76, s[10:11] offset:1024
	global_load_dword v25, v76, s[10:11] offset:1280
	global_load_dword v26, v76, s[10:11] offset:1536
	global_load_dword v27, v76, s[10:11] offset:1792
	global_load_dword v28, v76, s[10:11] offset:64
	global_load_dword v29, v76, s[10:11] offset:320
	global_load_dword v30, v76, s[10:11] offset:576
	global_load_dword v31, v76, s[10:11] offset:832
	global_load_dword v32, v76, s[10:11] offset:1088
	global_load_dword v33, v76, s[10:11] offset:1344
	global_load_dword v34, v76, s[10:11] offset:1600
	global_load_dword v35, v76, s[10:11] offset:1856
	global_load_dword v36, v76, s[10:11] offset:128
	global_load_dword v37, v76, s[10:11] offset:384
	global_load_dword v38, v76, s[10:11] offset:640
	global_load_dword v39, v76, s[10:11] offset:896
	global_load_dword v40, v76, s[10:11] offset:1152
	global_load_dword v41, v76, s[10:11] offset:1408
	global_load_dword v42, v76, s[10:11] offset:1664
	global_load_dword v43, v76, s[10:11] offset:1920
	global_load_dword v44, v76, s[10:11] offset:192
	global_load_dword v45, v76, s[10:11] offset:448
	global_load_dword v46, v76, s[10:11] offset:704
	global_load_dword v47, v76, s[10:11] offset:960
	global_load_dword v48, v76, s[10:11] offset:1216
	global_load_dword v49, v76, s[10:11] offset:1472
	global_load_dword v50, v76, s[10:11] offset:1728
	global_load_dword v51, v76, s[10:11] offset:1984
	global_load_dword v52, v77, s[10:11] offset:0
	global_load_dword v53, v77, s[10:11] offset:256
	global_load_dword v54, v77, s[10:11] offset:512
	global_load_dword v55, v77, s[10:11] offset:768
	global_load_dword v56, v77, s[10:11] offset:1024
	global_load_dword v57, v77, s[10:11] offset:1280
	global_load_dword v58, v77, s[10:11] offset:1536
	global_load_dword v59, v77, s[10:11] offset:1792
	global_load_dword v60, v77, s[10:11] offset:64
	global_load_dword v61, v77, s[10:11] offset:320
	global_load_dword v62, v77, s[10:11] offset:576
	global_load_dword v63, v77, s[10:11] offset:832
	global_load_dword v64, v77, s[10:11] offset:1088
	global_load_dword v65, v77, s[10:11] offset:1344
	global_load_dword v66, v77, s[10:11] offset:1600
	global_load_dword v67, v77, s[10:11] offset:1856
	global_load_dword v0, v77, s[10:11] offset:128
	global_load_dword v1, v77, s[10:11] offset:384
	global_load_dword v2, v77, s[10:11] offset:640
	global_load_dword v3, v77, s[10:11] offset:896
	global_load_dword v4, v77, s[10:11] offset:1152
	global_load_dword v5, v77, s[10:11] offset:1408
	global_load_dword v6, v77, s[10:11] offset:1664
	global_load_dword v7, v77, s[10:11] offset:1920
	global_load_dword v19, v77, s[10:11] offset:192
	global_load_dword v68, v77, s[10:11] offset:448
	global_load_dword v69, v77, s[10:11] offset:704
	global_load_dword v70, v77, s[10:11] offset:960
	global_load_dword v71, v77, s[10:11] offset:1216
	global_load_dword v80, v77, s[10:11] offset:1472
	global_load_dword v146, v77, s[10:11] offset:1728
	global_load_dword v147, v77, s[10:11] offset:1984
	s_waitcnt vmcnt(0)
; DI bf16_t f2bf(float x) { unsigned u = __float_as_uint(x); u += 0x7fffu + ((u >> 16) & 1u); return (bf16_t)(u >> 16); }
; DI float bf2f(bf16_t b) { return __uint_as_float(((unsigned)b) << 16); }
; DI float softplusf_(float z) { return fmaxf(z, 0.f) + __logf(1.f + __expf(-fabsf(z))); }
; template <bool PASS2>
; DI void lru_item(const Params& p, int l, int item, int lane, const bf16_t* xl, float* wxs) {
;     ...
;   unsigned wpa[32], wpx[32];
;   {
;     const float* pa = p.in[I_LRU_W_A] + ((size_t)l * 8 + blk) * 4096;
;     const float* px = p.in[I_LRU_W_X] + ((size_t)l * 8 + blk) * 4096;
;     int lo_ = lane; asm volatile("" : "+v"(lo_));
; #pragma unroll
;     for (int m = 0; m < 32; m++) {
;       wpa[m] = (unsigned)f2bf(pa[(2 * m) * 64 + lo_]) | ((unsigned)f2bf(pa[(2 * m + 1) * 64 + lo_]) << 16);
;       wpx[m] = (unsigned)f2bf(px[(2 * m) * 64 + lo_]) | ((unsigned)f2bf(px[(2 * m + 1) * 64 + lo_]) << 16);
;       if ((m & 7) == 7) asm volatile("" ::: "memory");
;     }
;   }
;   const float* cw = p.in[I_LRU_CONV_W] + (size_t)l * 4 * 512;
;   const float cw0 = cw[ch], cw1 = cw[512 + ch], cw2 = cw[1024 + ch], cw3 = cw[1536 + ch];
;   const float cb = p.in[I_LRU_CONV_B][l * 512 + ch];
;   const float ba = p.in[I_LRU_B_A][l * 512 + ch], bx = p.in[I_LRU_B_X][l * 512 + ch];
;   const float sp = softplusf_(-p.in[I_LRU_LAM][l * 512 + ch]);
;   const size_t tok0 = (size_t)b * SEQ + (size_t)c * LCL;
;   float x1 = 0.f, x2 = 0.f, x3 = 0.f;
;   if (c > 0) {
;     x1 = bf2f(xl[(tok0 - 1) * 512 + ch]); x2 = bf2f(xl[(tok0 - 2) * 512 + ch]); x3 = bf2f(xl[(tok0 - 3) * 512 + ch]);
;   }
;   float* st = p.lrust + ((size_t)(b * 512 + ch) * NCHL + c) * 2;
;   float hs = PASS2 ? st[1] : 0.f;
;   float aprod = 1.f;
;   float xn = bf2f(xl[tok0 * 512 + ch]);
	v_bfe_u32 v73, v20, 16, 1
	v_bfe_u32 v74, v21, 16, 1
	v_add3_u32 v20, v20, v73, s1
	v_add3_u32 v21, v21, v74, s1
	v_lshrrev_b32_e32 v20, 16, v20
	v_and_or_b32 v98, v21, s0, v20
	v_bfe_u32 v73, v22, 16, 1
	v_bfe_u32 v74, v23, 16, 1
	v_add3_u32 v22, v22, v73, s1
	v_add3_u32 v23, v23, v74, s1
	v_lshrrev_b32_e32 v22, 16, v22
	v_and_or_b32 v99, v23, s0, v22
	v_bfe_u32 v73, v24, 16, 1
	v_bfe_u32 v74, v25, 16, 1
	v_add3_u32 v24, v24, v73, s1
	v_add3_u32 v25, v25, v74, s1
	v_lshrrev_b32_e32 v24, 16, v24
	v_and_or_b32 v100, v25, s0, v24
	v_bfe_u32 v73, v26, 16, 1
	v_bfe_u32 v74, v27, 16, 1
	v_add3_u32 v26, v26, v73, s1
	v_add3_u32 v27, v27, v74, s1
	v_lshrrev_b32_e32 v26, 16, v26
	v_and_or_b32 v101, v27, s0, v26
	v_bfe_u32 v73, v28, 16, 1
	v_bfe_u32 v74, v29, 16, 1
	v_add3_u32 v28, v28, v73, s1
	v_add3_u32 v29, v29, v74, s1
	v_lshrrev_b32_e32 v28, 16, v28
	v_and_or_b32 v102, v29, s0, v28
	v_bfe_u32 v73, v30, 16, 1
	v_bfe_u32 v74, v31, 16, 1
	v_add3_u32 v30, v30, v73, s1
	v_add3_u32 v31, v31, v74, s1
	v_lshrrev_b32_e32 v30, 16, v30
	v_and_or_b32 v103, v31, s0, v30
	v_bfe_u32 v73, v32, 16, 1
	v_bfe_u32 v74, v33, 16, 1
	v_add3_u32 v32, v32, v73, s1
	v_add3_u32 v33, v33, v74, s1
	v_lshrrev_b32_e32 v32, 16, v32
	v_and_or_b32 v104, v33, s0, v32
	v_bfe_u32 v73, v34, 16, 1
	v_bfe_u32 v74, v35, 16, 1
	v_add3_u32 v34, v34, v73, s1
	v_add3_u32 v35, v35, v74, s1
	v_lshrrev_b32_e32 v34, 16, v34
	v_and_or_b32 v105, v35, s0, v34
	v_bfe_u32 v73, v36, 16, 1
	v_bfe_u32 v74, v37, 16, 1
	v_add3_u32 v36, v36, v73, s1
	v_add3_u32 v37, v37, v74, s1
	v_lshrrev_b32_e32 v36, 16, v36
	v_and_or_b32 v106, v37, s0, v36
	v_bfe_u32 v73, v38, 16, 1
	v_bfe_u32 v74, v39, 16, 1
	v_add3_u32 v38, v38, v73, s1
	v_add3_u32 v39, v39, v74, s1
	v_lshrrev_b32_e32 v38, 16, v38
	v_and_or_b32 v107, v39, s0, v38
	v_bfe_u32 v73, v40, 16, 1
	v_bfe_u32 v74, v41, 16, 1
	v_add3_u32 v40, v40, v73, s1
	v_add3_u32 v41, v41, v74, s1
	v_lshrrev_b32_e32 v40, 16, v40
	v_and_or_b32 v108, v41, s0, v40
	v_bfe_u32 v73, v42, 16, 1
	v_bfe_u32 v74, v43, 16, 1
	v_add3_u32 v42, v42, v73, s1
	v_add3_u32 v43, v43, v74, s1
	v_lshrrev_b32_e32 v42, 16, v42
	v_and_or_b32 v109, v43, s0, v42
	v_bfe_u32 v73, v44, 16, 1
	v_bfe_u32 v74, v45, 16, 1
	v_add3_u32 v44, v44, v73, s1
	v_add3_u32 v45, v45, v74, s1
	v_lshrrev_b32_e32 v44, 16, v44
	v_and_or_b32 v110, v45, s0, v44
	v_bfe_u32 v73, v46, 16, 1
	v_bfe_u32 v74, v47, 16, 1
	v_add3_u32 v46, v46, v73, s1
	v_add3_u32 v47, v47, v74, s1
	v_lshrrev_b32_e32 v46, 16, v46
	v_and_or_b32 v111, v47, s0, v46
	v_bfe_u32 v73, v48, 16, 1
	v_bfe_u32 v74, v49, 16, 1
	v_add3_u32 v48, v48, v73, s1
	v_add3_u32 v49, v49, v74, s1
	v_lshrrev_b32_e32 v48, 16, v48
	v_and_or_b32 v112, v49, s0, v48
	v_bfe_u32 v73, v50, 16, 1
	v_bfe_u32 v74, v51, 16, 1
	v_add3_u32 v50, v50, v73, s1
	v_add3_u32 v51, v51, v74, s1
	v_lshrrev_b32_e32 v50, 16, v50
	v_and_or_b32 v113, v51, s0, v50
	v_bfe_u32 v73, v52, 16, 1
	v_bfe_u32 v74, v53, 16, 1
	v_add3_u32 v52, v52, v73, s1
	v_add3_u32 v53, v53, v74, s1
	v_lshrrev_b32_e32 v52, 16, v52
	v_and_or_b32 v130, v53, s0, v52
	v_bfe_u32 v73, v54, 16, 1
	v_bfe_u32 v74, v55, 16, 1
	v_add3_u32 v54, v54, v73, s1
	v_add3_u32 v55, v55, v74, s1
	v_lshrrev_b32_e32 v54, 16, v54
	v_and_or_b32 v131, v55, s0, v54
	v_bfe_u32 v73, v56, 16, 1
	v_bfe_u32 v74, v57, 16, 1
	v_add3_u32 v56, v56, v73, s1
	v_add3_u32 v57, v57, v74, s1
	v_lshrrev_b32_e32 v56, 16, v56
	v_and_or_b32 v132, v57, s0, v56
	v_bfe_u32 v73, v58, 16, 1
	v_bfe_u32 v74, v59, 16, 1
	v_add3_u32 v58, v58, v73, s1
	v_add3_u32 v59, v59, v74, s1
	v_lshrrev_b32_e32 v58, 16, v58
	v_and_or_b32 v133, v59, s0, v58
	v_bfe_u32 v73, v60, 16, 1
	v_bfe_u32 v74, v61, 16, 1
	v_add3_u32 v60, v60, v73, s1
	v_add3_u32 v61, v61, v74, s1
	v_lshrrev_b32_e32 v60, 16, v60
	v_and_or_b32 v134, v61, s0, v60
	v_bfe_u32 v73, v62, 16, 1
	v_bfe_u32 v74, v63, 16, 1
	v_add3_u32 v62, v62, v73, s1
	v_add3_u32 v63, v63, v74, s1
	v_lshrrev_b32_e32 v62, 16, v62
	v_and_or_b32 v135, v63, s0, v62
	v_bfe_u32 v73, v64, 16, 1
	v_bfe_u32 v74, v65, 16, 1
	v_add3_u32 v64, v64, v73, s1
	v_add3_u32 v65, v65, v74, s1
	v_lshrrev_b32_e32 v64, 16, v64
	v_and_or_b32 v136, v65, s0, v64
	v_bfe_u32 v73, v66, 16, 1
	v_bfe_u32 v74, v67, 16, 1
	v_add3_u32 v66, v66, v73, s1
	v_add3_u32 v67, v67, v74, s1
	v_lshrrev_b32_e32 v66, 16, v66
	v_and_or_b32 v137, v67, s0, v66
	v_bfe_u32 v73, v0, 16, 1
	v_bfe_u32 v74, v1, 16, 1
	v_add3_u32 v0, v0, v73, s1
	v_add3_u32 v1, v1, v74, s1
	v_lshrrev_b32_e32 v0, 16, v0
	v_and_or_b32 v138, v1, s0, v0
	v_bfe_u32 v73, v2, 16, 1
	v_bfe_u32 v74, v3, 16, 1
	v_add3_u32 v2, v2, v73, s1
	v_add3_u32 v3, v3, v74, s1
	v_lshrrev_b32_e32 v2, 16, v2
	v_and_or_b32 v139, v3, s0, v2
	v_bfe_u32 v73, v4, 16, 1
	v_bfe_u32 v74, v5, 16, 1
	v_add3_u32 v4, v4, v73, s1
	v_add3_u32 v5, v5, v74, s1
	v_lshrrev_b32_e32 v4, 16, v4
	v_and_or_b32 v140, v5, s0, v4
	v_bfe_u32 v73, v6, 16, 1
	v_bfe_u32 v74, v7, 16, 1
	v_add3_u32 v6, v6, v73, s1
	v_add3_u32 v7, v7, v74, s1
	v_lshrrev_b32_e32 v6, 16, v6
	v_and_or_b32 v141, v7, s0, v6
	v_bfe_u32 v73, v19, 16, 1
	v_bfe_u32 v74, v68, 16, 1
	v_add3_u32 v19, v19, v73, s1
	v_add3_u32 v68, v68, v74, s1
	v_lshrrev_b32_e32 v19, 16, v19
	v_and_or_b32 v142, v68, s0, v19
	v_bfe_u32 v73, v69, 16, 1
	v_bfe_u32 v74, v70, 16, 1
	v_add3_u32 v69, v69, v73, s1
	v_add3_u32 v70, v70, v74, s1
	v_lshrrev_b32_e32 v69, 16, v69
	v_and_or_b32 v143, v70, s0, v69
	v_bfe_u32 v73, v71, 16, 1
	v_bfe_u32 v74, v80, 16, 1
	v_add3_u32 v71, v71, v73, s1
	v_add3_u32 v80, v80, v74, s1
	v_lshrrev_b32_e32 v71, 16, v71
	v_and_or_b32 v144, v80, s0, v71
	v_bfe_u32 v73, v146, 16, 1
	v_bfe_u32 v74, v147, 16, 1
	v_add3_u32 v146, v146, v73, s1
	v_add3_u32 v147, v147, v74, s1
	v_lshrrev_b32_e32 v146, 16, v146
	v_and_or_b32 v145, v147, s0, v146
	s_add_u32 s0, s18, 0x800
	s_addc_u32 s1, s19, 0
	global_load_dword v14, v79, s[0:1]
	s_load_dwordx2 s[16:17], s[14:15], 0x130
	s_waitcnt lgkmcnt(0)
	s_add_u32 s0, s16, 0x800
	s_addc_u32 s1, s17, 0
	global_load_dword v15, v79, s[0:1]
	v_and_b32_e32 v80, 63, v210
	v_lshrrev_b32_e32 v146, 6, v210
	v_and_b32_e32 v146, 3, v146
	v_mul_u32_u24_e32 v146, 0x2200, v146
	v_lshl_add_u32 v74, v80, 1, v146
	v_and_b32_e32 v147, 15, v80
	v_lshrrev_b32_e32 v79, 4, v80
	v_mul_u32_u24_e32 v75, 0x90, v147
	v_lshl_add_u32 v75, v79, 4, v75
	v_add_u32_e32 v75, v146, v75
	v_add_u32_e32 v146, 0x8800, v146
	v_mul_u32_u24_e32 v76, 0x210, v79
	v_add_u32_e32 v76, v76, v147
	v_lshl_add_u32 v76, v76, 2, v146
	v_lshl_add_u32 v77, v80, 2, v146
	s_lshr_b32 s19, s12, 10
	s_and_b32 s17, s12, 127
	s_lshl_b32 s18, s19, 14
	s_lshl_b32 s20, s17, 7
	s_add_u32 s18, s18, s20
	s_lshl_b32 s20, s18, 10
	v_add_u32_e32 v73, s20, v72
	v_mov_b32_e32 v69, 0
	v_mov_b32_e32 v70, 0
	v_mov_b32_e32 v71, 0
	v_mov_b32_e32 v19, 0
	v_mov_b32_e32 v68, 1.0
	s_cmp_eq_u32 s17, 0
	s_cbranch_scc1 .Llrub1_nohist
	global_load_ushort v69, v73, s[6:7] offset:-1024
	global_load_ushort v70, v73, s[6:7] offset:-2048
	global_load_ushort v71, v73, s[6:7] offset:-3072

; DI bf16_t f2bf(float x) { unsigned u = __float_as_uint(x); u += 0x7fffu + ((u >> 16) & 1u); return (bf16_t)(u >> 16); }
; template <bool PASS2>
; DI void lru_item(const Params& p, int l, int item, int lane, const bf16_t* xl, float* wxs) {
;   const int b = item / (8 * NCHL), blk = (item / NCHL) % 8, c = item % NCHL;
;   const int ch = blk * 64 + lane;
;   unsigned wpa[32], wpx[32];
;   {
;     const float* pa = p.in[I_LRU_W_A] + ((size_t)l * 8 + blk) * 4096;
;     const float* px = p.in[I_LRU_W_X] + ((size_t)l * 8 + blk) * 4096;
;     int lo_ = lane; asm volatile("" : "+v"(lo_));
; #pragma unroll
;     for (int m = 0; m < 32; m++) {
;       wpa[m] = (unsigned)f2bf(pa[(2 * m) * 64 + lo_]) | ((unsigned)f2bf(pa[(2 * m + 1) * 64 + lo_]) << 16);
;       wpx[m] = (unsigned)f2bf(px[(2 * m) * 64 + lo_]) | ((unsigned)f2bf(px[(2 * m + 1) * 64 + lo_]) << 16);
;       if ((m & 7) == 7) asm volatile("" ::: "memory");
;     }
;   }
;   const float* cw = p.in[I_LRU_CONV_W] + (size_t)l * 4 * 512;
;   const float cw0 = cw[ch], cw1 = cw[512 + ch], cw2 = cw[1024 + ch], cw3 = cw[1536 + ch];
;   const float cb = p.in[I_LRU_CONV_B][l * 512 + ch];
;   const float ba = p.in[I_LRU_B_A][l * 512 + ch], bx = p.in[I_LRU_B_X][l * 512 + ch];
; template <int Q>
; DI void run_phase(const Params& p, int l, bf16_t* sm) {
;     ...
;     for (int it = wave * gridDim.x + blockIdx.x; it < 16 * NCHL; it += gridDim.x * 4) lru_item<true>(p, l, __builtin_amdgcn_readfirstlane(it), lane, xlbuf, (float*)sm + wave * 4096);
.LBB0_2522:
	s_or_b64 exec, exec, s[0:1]
	v_mov_b32_e32 v21, v210
	s_waitcnt lgkmcnt(0)
	v_mov_b32_e32 v0, v210
	s_barrier
	v_readlane_b32 s0, v252, 1
	v_bfe_u32 v20, v0, 6, 2
	v_and_b32_e32 v113, 63, v21
	v_mul_lo_u32 v0, v20, s0
	v_readlane_b32 s0, v252, 26
	v_readlane_b32 s1, v252, 2
	s_nop 0
	v_add_u32_e32 v22, s0, v0
	s_movk_i32 s0, 0x800
	v_cmp_gt_i32_e32 vcc, s0, v22
	s_and_saveexec_b64 s[8:9], vcc
	s_cbranch_execz .LBB0_2532
	v_readlane_b32 s14, v252, 3
	v_readlane_b32 s15, v252, 4
	v_readlane_b32 s13, v252, 1
	v_readfirstlane_b32 s12, v22
	s_sub_u32 s14, s14, 0x180
	s_subb_u32 s15, s15, 0
	s_lshl_b32 s13, s13, 2
	s_load_dwordx2 s[2:3], s[14:15], 0x170
	s_waitcnt lgkmcnt(0)
	s_add_u32 s6, s2, 0x13558000
	s_addc_u32 s7, s3, 0
.Llrub2_item:
	s_bfe_u32 s16, s12, 0x30007
	v_and_b32_e32 v110, 63, v210
	v_lshl_add_u32 v110, s16, 6, v110
	v_lshlrev_b32_e32 v104, 1, v110
	v_lshlrev_b32_e32 v111, 2, v110
	v_and_b32_e32 v112, 63, v210
	v_lshrrev_b32_e32 v146, 4, v112
	v_and_b32_e32 v112, 15, v112
	v_lshlrev_b32_e32 v108, 11, v146
	v_lshl_add_u32 v108, v112, 2, v108
	v_add_u32_e32 v109, 0x2000, v108
	s_load_dwordx4 s[16:19], s[14:15], 0x100
	s_waitcnt lgkmcnt(0)
	s_add_u32 s0, s16, 0x2000
	s_addc_u32 s1, s17, 0
	global_load_dword v8, v111, s[0:1]
	global_load_dword v9, v111, s[0:1] offset:2048
	s_add_u32 s0, s0, 0x1000
	s_addc_u32 s1, s1, 0
	global_load_dword v10, v111, s[0:1]
	global_load_dword v11, v111, s[0:1] offset:2048
	s_add_u32 s0, s18, 0x800
	s_addc_u32 s1, s19, 0
	global_load_dword v12, v111, s[0:1]
	s_load_dwordx4 s[16:19], s[14:15], 0x110
	s_waitcnt lgkmcnt(0)
	s_add_u32 s0, s18, 0x800
	s_addc_u32 s1, s19, 0
	global_load_dword v13, v111, s[0:1]
	s_bfe_u32 s20, s12, 0x30007
	s_add_u32 s20, s20, 8
	s_lshl_b32 s20, s20, 14
	s_add_u32 s10, s16, s20
	s_addc_u32 s11, s17, 0
	s_load_dwordx4 s[16:19], s[14:15], 0x120
	s_mov_b32 s0, 0xffff0000
	s_movk_i32 s1, 0x7fff
	global_load_dword v114, v108, s[10:11] offset:0
	global_load_dword v115, v108, s[10:11] offset:256
	global_load_dword v116, v108, s[10:11] offset:512
	global_load_dword v117, v108, s[10:11] offset:768
	global_load_dword v118, v108, s[10:11] offset:1024
	global_load_dword v119, v108, s[10:11] offset:1280
	global_load_dword v120, v108, s[10:11] offset:1536
	global_load_dword v121, v108, s[10:11] offset:1792
	global_load_dword v122, v108, s[10:11] offset:64
	global_load_dword v123, v108, s[10:11] offset:320
	global_load_dword v124, v108, s[10:11] offset:576
	global_load_dword v125, v108, s[10:11] offset:832
	global_load_dword v126, v108, s[10:11] offset:1088
	global_load_dword v127, v108, s[10:11] offset:1344
	global_load_dword v128, v108, s[10:11] offset:1600
	global_load_dword v129, v108, s[10:11] offset:1856
	global_load_dword v130, v108, s[10:11] offset:128
	global_load_dword v131, v108, s[10:11] offset:384
	global_load_dword v132, v108, s[10:11] offset:640
	global_load_dword v133, v108, s[10:11] offset:896
	global_load_dword v134, v108, s[10:11] offset:1152
	global_load_dword v135, v108, s[10:11] offset:1408
	global_load_dword v136, v108, s[10:11] offset:1664
	global_load_dword v137, v108, s[10:11] offset:1920
	global_load_dword v138, v108, s[10:11] offset:192
	global_load_dword v139, v108, s[10:11] offset:448
	global_load_dword v140, v108, s[10:11] offset:704
	global_load_dword v141, v108, s[10:11] offset:960
	global_load_dword v142, v108, s[10:11] offset:1216
	global_load_dword v143, v108, s[10:11] offset:1472
	global_load_dword v144, v108, s[10:11] offset:1728
	global_load_dword v145, v108, s[10:11] offset:1984
	global_load_dword v88, v109, s[10:11] offset:0
	global_load_dword v89, v109, s[10:11] offset:256
	global_load_dword v90, v109, s[10:11] offset:512
	global_load_dword v91, v109, s[10:11] offset:768
	global_load_dword v92, v109, s[10:11] offset:1024
	global_load_dword v93, v109, s[10:11] offset:1280
	global_load_dword v94, v109, s[10:11] offset:1536
	global_load_dword v95, v109, s[10:11] offset:1792
	global_load_dword v96, v109, s[10:11] offset:64
	global_load_dword v97, v109, s[10:11] offset:320
	global_load_dword v98, v109, s[10:11] offset:576
	global_load_dword v99, v109, s[10:11] offset:832
	global_load_dword v100, v109, s[10:11] offset:1088
	global_load_dword v101, v109, s[10:11] offset:1344
	global_load_dword v102, v109, s[10:11] offset:1600
	global_load_dword v103, v109, s[10:11] offset:1856
	global_load_dword v0, v109, s[10:11] offset:128
	global_load_dword v1, v109, s[10:11] offset:384
	global_load_dword v2, v109, s[10:11] offset:640
	global_load_dword v3, v109, s[10:11] offset:896
	global_load_dword v4, v109, s[10:11] offset:1152
	global_load_dword v5, v109, s[10:11] offset:1408
	global_load_dword v6, v109, s[10:11] offset:1664
	global_load_dword v7, v109, s[10:11] offset:1920
	global_load_dword v16, v109, s[10:11] offset:192
	global_load_dword v17, v109, s[10:11] offset:448
	global_load_dword v18, v109, s[10:11] offset:704
	global_load_dword v19, v109, s[10:11] offset:960
	global_load_dword v23, v109, s[10:11] offset:1216
	global_load_dword v112, v109, s[10:11] offset:1472
	global_load_dword v146, v109, s[10:11] offset:1728
	global_load_dword v147, v109, s[10:11] offset:1984
	s_waitcnt vmcnt(0)
; DI bf16_t f2bf(float x) { unsigned u = __float_as_uint(x); u += 0x7fffu + ((u >> 16) & 1u); return (bf16_t)(u >> 16); }
; template <bool PASS2>
; DI void lru_item(const Params& p, int l, int item, int lane, const bf16_t* xl, float* wxs) {
;     ...
;   unsigned wpa[32], wpx[32];
;   {
;     const float* pa = p.in[I_LRU_W_A] + ((size_t)l * 8 + blk) * 4096;
;     const float* px = p.in[I_LRU_W_X] + ((size_t)l * 8 + blk) * 4096;
;     int lo_ = lane; asm volatile("" : "+v"(lo_));
; #pragma unroll
;     for (int m = 0; m < 32; m++) {
;       wpa[m] = (unsigned)f2bf(pa[(2 * m) * 64 + lo_]) | ((unsigned)f2bf(pa[(2 * m + 1) * 64 + lo_]) << 16);
;       wpx[m] = (unsigned)f2bf(px[(2 * m) * 64 + lo_]) | ((unsigned)f2bf(px[(2 * m + 1) * 64 + lo_]) << 16);
;       if ((m & 7) == 7) asm volatile("" ::: "memory");
;     }
;   }
	v_bfe_u32 v105, v114, 16, 1
	v_bfe_u32 v106, v115, 16, 1
	v_add3_u32 v114, v114, v105, s1
	v_add3_u32 v115, v115, v106, s1
	v_lshrrev_b32_e32 v114, 16, v114
	v_and_or_b32 v24, v115, s0, v114
	v_bfe_u32 v105, v116, 16, 1
	v_bfe_u32 v106, v117, 16, 1
	v_add3_u32 v116, v116, v105, s1
	v_add3_u32 v117, v117, v106, s1
	v_lshrrev_b32_e32 v116, 16, v116
	v_and_or_b32 v25, v117, s0, v116
	v_bfe_u32 v105, v118, 16, 1
	v_bfe_u32 v106, v119, 16, 1
	v_add3_u32 v118, v118, v105, s1
	v_add3_u32 v119, v119, v106, s1
	v_lshrrev_b32_e32 v118, 16, v118
	v_and_or_b32 v26, v119, s0, v118
	v_bfe_u32 v105, v120, 16, 1
	v_bfe_u32 v106, v121, 16, 1
	v_add3_u32 v120, v120, v105, s1
	v_add3_u32 v121, v121, v106, s1
	v_lshrrev_b32_e32 v120, 16, v120
	v_and_or_b32 v27, v121, s0, v120
	v_bfe_u32 v105, v122, 16, 1
	v_bfe_u32 v106, v123, 16, 1
	v_add3_u32 v122, v122, v105, s1
	v_add3_u32 v123, v123, v106, s1
	v_lshrrev_b32_e32 v122, 16, v122
	v_and_or_b32 v28, v123, s0, v122
	v_bfe_u32 v105, v124, 16, 1
	v_bfe_u32 v106, v125, 16, 1
	v_add3_u32 v124, v124, v105, s1
	v_add3_u32 v125, v125, v106, s1
	v_lshrrev_b32_e32 v124, 16, v124
	v_and_or_b32 v29, v125, s0, v124
	v_bfe_u32 v105, v126, 16, 1
	v_bfe_u32 v106, v127, 16, 1
	v_add3_u32 v126, v126, v105, s1
	v_add3_u32 v127, v127, v106, s1
	v_lshrrev_b32_e32 v126, 16, v126
	v_and_or_b32 v30, v127, s0, v126
	v_bfe_u32 v105, v128, 16, 1
	v_bfe_u32 v106, v129, 16, 1
	v_add3_u32 v128, v128, v105, s1
	v_add3_u32 v129, v129, v106, s1
	v_lshrrev_b32_e32 v128, 16, v128
	v_and_or_b32 v31, v129, s0, v128
	v_bfe_u32 v105, v130, 16, 1
	v_bfe_u32 v106, v131, 16, 1
	v_add3_u32 v130, v130, v105, s1
	v_add3_u32 v131, v131, v106, s1
	v_lshrrev_b32_e32 v130, 16, v130
	v_and_or_b32 v32, v131, s0, v130
	v_bfe_u32 v105, v132, 16, 1
	v_bfe_u32 v106, v133, 16, 1
	v_add3_u32 v132, v132, v105, s1
	v_add3_u32 v133, v133, v106, s1
	v_lshrrev_b32_e32 v132, 16, v132
	v_and_or_b32 v33, v133, s0, v132
	v_bfe_u32 v105, v134, 16, 1
	v_bfe_u32 v106, v135, 16, 1
	v_add3_u32 v134, v134, v105, s1
	v_add3_u32 v135, v135, v106, s1
	v_lshrrev_b32_e32 v134, 16, v134
	v_and_or_b32 v34, v135, s0, v134
	v_bfe_u32 v105, v136, 16, 1
	v_bfe_u32 v106, v137, 16, 1
	v_add3_u32 v136, v136, v105, s1
	v_add3_u32 v137, v137, v106, s1
	v_lshrrev_b32_e32 v136, 16, v136
	v_and_or_b32 v35, v137, s0, v136
	v_bfe_u32 v105, v138, 16, 1
	v_bfe_u32 v106, v139, 16, 1
	v_add3_u32 v138, v138, v105, s1
	v_add3_u32 v139, v139, v106, s1
	v_lshrrev_b32_e32 v138, 16, v138
	v_and_or_b32 v36, v139, s0, v138
	v_bfe_u32 v105, v140, 16, 1
	v_bfe_u32 v106, v141, 16, 1
	v_add3_u32 v140, v140, v105, s1
	v_add3_u32 v141, v141, v106, s1
	v_lshrrev_b32_e32 v140, 16, v140
	v_and_or_b32 v37, v141, s0, v140
	v_bfe_u32 v105, v142, 16, 1
	v_bfe_u32 v106, v143, 16, 1
	v_add3_u32 v142, v142, v105, s1
	v_add3_u32 v143, v143, v106, s1
	v_lshrrev_b32_e32 v142, 16, v142
	v_and_or_b32 v38, v143, s0, v142
	v_bfe_u32 v105, v144, 16, 1
	v_bfe_u32 v106, v145, 16, 1
	v_add3_u32 v144, v144, v105, s1
	v_add3_u32 v145, v145, v106, s1
	v_lshrrev_b32_e32 v144, 16, v144
	v_and_or_b32 v39, v145, s0, v144
	v_bfe_u32 v105, v88, 16, 1
	v_bfe_u32 v106, v89, 16, 1
	v_add3_u32 v88, v88, v105, s1
	v_add3_u32 v89, v89, v106, s1
	v_lshrrev_b32_e32 v88, 16, v88
	v_and_or_b32 v56, v89, s0, v88
	v_bfe_u32 v105, v90, 16, 1
	v_bfe_u32 v106, v91, 16, 1
	v_add3_u32 v90, v90, v105, s1
	v_add3_u32 v91, v91, v106, s1
	v_lshrrev_b32_e32 v90, 16, v90
	v_and_or_b32 v57, v91, s0, v90
	v_bfe_u32 v105, v92, 16, 1
	v_bfe_u32 v106, v93, 16, 1
	v_add3_u32 v92, v92, v105, s1
	v_add3_u32 v93, v93, v106, s1
	v_lshrrev_b32_e32 v92, 16, v92
	v_and_or_b32 v58, v93, s0, v92
	v_bfe_u32 v105, v94, 16, 1
	v_bfe_u32 v106, v95, 16, 1
	v_add3_u32 v94, v94, v105, s1
	v_add3_u32 v95, v95, v106, s1
	v_lshrrev_b32_e32 v94, 16, v94
	v_and_or_b32 v59, v95, s0, v94
	v_bfe_u32 v105, v96, 16, 1
	v_bfe_u32 v106, v97, 16, 1
	v_add3_u32 v96, v96, v105, s1
	v_add3_u32 v97, v97, v106, s1
	v_lshrrev_b32_e32 v96, 16, v96
	v_and_or_b32 v60, v97, s0, v96
	v_bfe_u32 v105, v98, 16, 1
	v_bfe_u32 v106, v99, 16, 1
	v_add3_u32 v98, v98, v105, s1
	v_add3_u32 v99, v99, v106, s1
	v_lshrrev_b32_e32 v98, 16, v98
	v_and_or_b32 v61, v99, s0, v98
	v_bfe_u32 v105, v100, 16, 1
	v_bfe_u32 v106, v101, 16, 1
	v_add3_u32 v100, v100, v105, s1
	v_add3_u32 v101, v101, v106, s1
	v_lshrrev_b32_e32 v100, 16, v100
	v_and_or_b32 v62, v101, s0, v100
	v_bfe_u32 v105, v102, 16, 1
	v_bfe_u32 v106, v103, 16, 1
	v_add3_u32 v102, v102, v105, s1
	v_add3_u32 v103, v103, v106, s1
	v_lshrrev_b32_e32 v102, 16, v102
	v_and_or_b32 v63, v103, s0, v102
	v_bfe_u32 v105, v0, 16, 1
	v_bfe_u32 v106, v1, 16, 1
	v_add3_u32 v0, v0, v105, s1
	v_add3_u32 v1, v1, v106, s1
	v_lshrrev_b32_e32 v0, 16, v0
	v_and_or_b32 v64, v1, s0, v0
	v_bfe_u32 v105, v2, 16, 1
	v_bfe_u32 v106, v3, 16, 1
	v_add3_u32 v2, v2, v105, s1
	v_add3_u32 v3, v3, v106, s1
	v_lshrrev_b32_e32 v2, 16, v2
	v_and_or_b32 v65, v3, s0, v2
	v_bfe_u32 v105, v4, 16, 1
	v_bfe_u32 v106, v5, 16, 1
	v_add3_u32 v4, v4, v105, s1
	v_add3_u32 v5, v5, v106, s1
	v_lshrrev_b32_e32 v4, 16, v4
	v_and_or_b32 v66, v5, s0, v4
	v_bfe_u32 v105, v6, 16, 1
	v_bfe_u32 v106, v7, 16, 1
	v_add3_u32 v6, v6, v105, s1
	v_add3_u32 v7, v7, v106, s1
	v_lshrrev_b32_e32 v6, 16, v6
	v_and_or_b32 v67, v7, s0, v6
	v_bfe_u32 v105, v16, 16, 1
	v_bfe_u32 v106, v17, 16, 1
	v_add3_u32 v16, v16, v105, s1
	v_add3_u32 v17, v17, v106, s1
	v_lshrrev_b32_e32 v16, 16, v16
	v_and_or_b32 v68, v17, s0, v16
	v_bfe_u32 v105, v18, 16, 1
	v_bfe_u32 v106, v19, 16, 1
	v_add3_u32 v18, v18, v105, s1
	v_add3_u32 v19, v19, v106, s1
	v_lshrrev_b32_e32 v18, 16, v18
	v_and_or_b32 v69, v19, s0, v18
	v_bfe_u32 v105, v23, 16, 1
	v_bfe_u32 v106, v112, 16, 1
	v_add3_u32 v23, v23, v105, s1
	v_add3_u32 v112, v112, v106, s1
	v_lshrrev_b32_e32 v23, 16, v23
	v_and_or_b32 v70, v112, s0, v23
	v_bfe_u32 v105, v146, 16, 1
	v_bfe_u32 v106, v147, 16, 1
	v_add3_u32 v146, v146, v105, s1
	v_add3_u32 v147, v147, v106, s1
	v_lshrrev_b32_e32 v146, 16, v146
	v_and_or_b32 v71, v147, s0, v146
	s_waitcnt lgkmcnt(0)
; DI bf16_t f2bf(float x) { unsigned u = __float_as_uint(x); u += 0x7fffu + ((u >> 16) & 1u); return (bf16_t)(u >> 16); }
; template <bool PASS2>
; DI void lru_item(const Params& p, int l, int item, int lane, const bf16_t* xl, float* wxs) {
;     ...
;   unsigned wpa[32], wpx[32];
;   {
;     const float* pa = p.in[I_LRU_W_A] + ((size_t)l * 8 + blk) * 4096;
;     const float* px = p.in[I_LRU_W_X] + ((size_t)l * 8 + blk) * 4096;
;     int lo_ = lane; asm volatile("" : "+v"(lo_));
; #pragma unroll
;     for (int m = 0; m < 32; m++) {
;       wpa[m] = (unsigned)f2bf(pa[(2 * m) * 64 + lo_]) | ((unsigned)f2bf(pa[(2 * m + 1) * 64 + lo_]) << 16);
;       wpx[m] = (unsigned)f2bf(px[(2 * m) * 64 + lo_]) | ((unsigned)f2bf(px[(2 * m + 1) * 64 + lo_]) << 16);
;       if ((m & 7) == 7) asm volatile("" ::: "memory");
;     }
;   }
	s_add_u32 s10, s16, s20
	s_addc_u32 s11, s17, 0
	global_load_dword v114, v108, s[10:11] offset:0
	global_load_dword v115, v108, s[10:11] offset:256
	global_load_dword v116, v108, s[10:11] offset:512
	global_load_dword v117, v108, s[10:11] offset:768
	global_load_dword v118, v108, s[10:11] offset:1024
	global_load_dword v119, v108, s[10:11] offset:1280
	global_load_dword v120, v108, s[10:11] offset:1536
	global_load_dword v121, v108, s[10:11] offset:1792
	global_load_dword v122, v108, s[10:11] offset:64
	global_load_dword v123, v108, s[10:11] offset:320
	global_load_dword v124, v108, s[10:11] offset:576
	global_load_dword v125, v108, s[10:11] offset:832
	global_load_dword v126, v108, s[10:11] offset:1088
	global_load_dword v127, v108, s[10:11] offset:1344
	global_load_dword v128, v108, s[10:11] offset:1600
	global_load_dword v129, v108, s[10:11] offset:1856
	global_load_dword v130, v108, s[10:11] offset:128
	global_load_dword v131, v108, s[10:11] offset:384
	global_load_dword v132, v108, s[10:11] offset:640
	global_load_dword v133, v108, s[10:11] offset:896
	global_load_dword v134, v108, s[10:11] offset:1152
	global_load_dword v135, v108, s[10:11] offset:1408
	global_load_dword v136, v108, s[10:11] offset:1664
	global_load_dword v137, v108, s[10:11] offset:1920
	global_load_dword v138, v108, s[10:11] offset:192
	global_load_dword v139, v108, s[10:11] offset:448
	global_load_dword v140, v108, s[10:11] offset:704
	global_load_dword v141, v108, s[10:11] offset:960
	global_load_dword v142, v108, s[10:11] offset:1216
	global_load_dword v143, v108, s[10:11] offset:1472
	global_load_dword v144, v108, s[10:11] offset:1728
	global_load_dword v145, v108, s[10:11] offset:1984
	global_load_dword v88, v109, s[10:11] offset:0
	global_load_dword v89, v109, s[10:11] offset:256
	global_load_dword v90, v109, s[10:11] offset:512
	global_load_dword v91, v109, s[10:11] offset:768
	global_load_dword v92, v109, s[10:11] offset:1024
	global_load_dword v93, v109, s[10:11] offset:1280
	global_load_dword v94, v109, s[10:11] offset:1536
	global_load_dword v95, v109, s[10:11] offset:1792
	global_load_dword v96, v109, s[10:11] offset:64
	global_load_dword v97, v109, s[10:11] offset:320
	global_load_dword v98, v109, s[10:11] offset:576
	global_load_dword v99, v109, s[10:11] offset:832
	global_load_dword v100, v109, s[10:11] offset:1088
	global_load_dword v101, v109, s[10:11] offset:1344
	global_load_dword v102, v109, s[10:11] offset:1600
	global_load_dword v103, v109, s[10:11] offset:1856
	global_load_dword v0, v109, s[10:11] offset:128
	global_load_dword v1, v109, s[10:11] offset:384
	global_load_dword v2, v109, s[10:11] offset:640
	global_load_dword v3, v109, s[10:11] offset:896
	global_load_dword v4, v109, s[10:11] offset:1152
	global_load_dword v5, v109, s[10:11] offset:1408
	global_load_dword v6, v109, s[10:11] offset:1664
	global_load_dword v7, v109, s[10:11] offset:1920
	global_load_dword v16, v109, s[10:11] offset:192
	global_load_dword v17, v109, s[10:11] offset:448
	global_load_dword v18, v109, s[10:11] offset:704
	global_load_dword v19, v109, s[10:11] offset:960
	global_load_dword v23, v109, s[10:11] offset:1216
	global_load_dword v112, v109, s[10:11] offset:1472
	global_load_dword v146, v109, s[10:11] offset:1728
	global_load_dword v147, v109, s[10:11] offset:1984
	s_waitcnt vmcnt(0)
	v_bfe_u32 v105, v114, 16, 1
	v_bfe_u32 v106, v115, 16, 1
	v_add3_u32 v114, v114, v105, s1
	v_add3_u32 v115, v115, v106, s1
	v_lshrrev_b32_e32 v114, 16, v114
	v_and_or_b32 v40, v115, s0, v114
	v_bfe_u32 v105, v116, 16, 1
	v_bfe_u32 v106, v117, 16, 1
	v_add3_u32 v116, v116, v105, s1
	v_add3_u32 v117, v117, v106, s1
	v_lshrrev_b32_e32 v116, 16, v116
	v_and_or_b32 v41, v117, s0, v116
	v_bfe_u32 v105, v118, 16, 1
	v_bfe_u32 v106, v119, 16, 1
	v_add3_u32 v118, v118, v105, s1
	v_add3_u32 v119, v119, v106, s1
	v_lshrrev_b32_e32 v118, 16, v118
	v_and_or_b32 v42, v119, s0, v118
	v_bfe_u32 v105, v120, 16, 1
	v_bfe_u32 v106, v121, 16, 1
	v_add3_u32 v120, v120, v105, s1
	v_add3_u32 v121, v121, v106, s1
	v_lshrrev_b32_e32 v120, 16, v120
	v_and_or_b32 v43, v121, s0, v120
	v_bfe_u32 v105, v122, 16, 1
	v_bfe_u32 v106, v123, 16, 1
	v_add3_u32 v122, v122, v105, s1
	v_add3_u32 v123, v123, v106, s1
	v_lshrrev_b32_e32 v122, 16, v122
	v_and_or_b32 v44, v123, s0, v122
	v_bfe_u32 v105, v124, 16, 1
	v_bfe_u32 v106, v125, 16, 1
	v_add3_u32 v124, v124, v105, s1
	v_add3_u32 v125, v125, v106, s1
	v_lshrrev_b32_e32 v124, 16, v124
	v_and_or_b32 v45, v125, s0, v124
	v_bfe_u32 v105, v126, 16, 1
	v_bfe_u32 v106, v127, 16, 1
	v_add3_u32 v126, v126, v105, s1
	v_add3_u32 v127, v127, v106, s1
	v_lshrrev_b32_e32 v126, 16, v126
	v_and_or_b32 v46, v127, s0, v126
	v_bfe_u32 v105, v128, 16, 1
	v_bfe_u32 v106, v129, 16, 1
	v_add3_u32 v128, v128, v105, s1
	v_add3_u32 v129, v129, v106, s1
	v_lshrrev_b32_e32 v128, 16, v128
	v_and_or_b32 v47, v129, s0, v128
	v_bfe_u32 v105, v130, 16, 1
	v_bfe_u32 v106, v131, 16, 1
	v_add3_u32 v130, v130, v105, s1
	v_add3_u32 v131, v131, v106, s1
	v_lshrrev_b32_e32 v130, 16, v130
	v_and_or_b32 v48, v131, s0, v130
	v_bfe_u32 v105, v132, 16, 1
	v_bfe_u32 v106, v133, 16, 1
	v_add3_u32 v132, v132, v105, s1
	v_add3_u32 v133, v133, v106, s1
	v_lshrrev_b32_e32 v132, 16, v132
	v_and_or_b32 v49, v133, s0, v132
	v_bfe_u32 v105, v134, 16, 1
	v_bfe_u32 v106, v135, 16, 1
	v_add3_u32 v134, v134, v105, s1
	v_add3_u32 v135, v135, v106, s1
	v_lshrrev_b32_e32 v134, 16, v134
; DI bf16_t f2bf(float x) { unsigned u = __float_as_uint(x); u += 0x7fffu + ((u >> 16) & 1u); return (bf16_t)(u >> 16); }
; DI float bf2f(bf16_t b) { return __uint_as_float(((unsigned)b) << 16); }
; DI float softplusf_(float z) { return fmaxf(z, 0.f) + __logf(1.f + __expf(-fabsf(z))); }
; template <bool PASS2>
; DI void lru_item(const Params& p, int l, int item, int lane, const bf16_t* xl, float* wxs) {
;     ...
;   unsigned wpa[32], wpx[32];
;   {
;     const float* pa = p.in[I_LRU_W_A] + ((size_t)l * 8 + blk) * 4096;
;     const float* px = p.in[I_LRU_W_X] + ((size_t)l * 8 + blk) * 4096;
;     int lo_ = lane; asm volatile("" : "+v"(lo_));
; #pragma unroll
;     for (int m = 0; m < 32; m++) {
;       wpa[m] = (unsigned)f2bf(pa[(2 * m) * 64 + lo_]) | ((unsigned)f2bf(pa[(2 * m + 1) * 64 + lo_]) << 16);
;       wpx[m] = (unsigned)f2bf(px[(2 * m) * 64 + lo_]) | ((unsigned)f2bf(px[(2 * m + 1) * 64 + lo_]) << 16);
;       if ((m & 7) == 7) asm volatile("" ::: "memory");
;     }
;   }
;   const float* cw = p.in[I_LRU_CONV_W] + (size_t)l * 4 * 512;
;   const float cw0 = cw[ch], cw1 = cw[512 + ch], cw2 = cw[1024 + ch], cw3 = cw[1536 + ch];
;   const float cb = p.in[I_LRU_CONV_B][l * 512 + ch];
;   const float ba = p.in[I_LRU_B_A][l * 512 + ch], bx = p.in[I_LRU_B_X][l * 512 + ch];
;   const float sp = softplusf_(-p.in[I_LRU_LAM][l * 512 + ch]);
;   const size_t tok0 = (size_t)b * SEQ + (size_t)c * LCL;
;   float x1 = 0.f, x2 = 0.f, x3 = 0.f;
;   if (c > 0) {
;     x1 = bf2f(xl[(tok0 - 1) * 512 + ch]); x2 = bf2f(xl[(tok0 - 2) * 512 + ch]); x3 = bf2f(xl[(tok0 - 3) * 512 + ch]);
;   }
;   float* st = p.lrust + ((size_t)(b * 512 + ch) * NCHL + c) * 2;
;   float hs = PASS2 ? st[1] : 0.f;
	v_and_or_b32 v50, v135, s0, v134
	v_bfe_u32 v105, v136, 16, 1
	v_bfe_u32 v106, v137, 16, 1
	v_add3_u32 v136, v136, v105, s1
	v_add3_u32 v137, v137, v106, s1
	v_lshrrev_b32_e32 v136, 16, v136
	v_and_or_b32 v51, v137, s0, v136
	v_bfe_u32 v105, v138, 16, 1
	v_bfe_u32 v106, v139, 16, 1
	v_add3_u32 v138, v138, v105, s1
	v_add3_u32 v139, v139, v106, s1
	v_lshrrev_b32_e32 v138, 16, v138
	v_and_or_b32 v52, v139, s0, v138
	v_bfe_u32 v105, v140, 16, 1
	v_bfe_u32 v106, v141, 16, 1
	v_add3_u32 v140, v140, v105, s1
	v_add3_u32 v141, v141, v106, s1
	v_lshrrev_b32_e32 v140, 16, v140
	v_and_or_b32 v53, v141, s0, v140
	v_bfe_u32 v105, v142, 16, 1
	v_bfe_u32 v106, v143, 16, 1
	v_add3_u32 v142, v142, v105, s1
	v_add3_u32 v143, v143, v106, s1
	v_lshrrev_b32_e32 v142, 16, v142
	v_and_or_b32 v54, v143, s0, v142
	v_bfe_u32 v105, v144, 16, 1
	v_bfe_u32 v106, v145, 16, 1
	v_add3_u32 v144, v144, v105, s1
	v_add3_u32 v145, v145, v106, s1
	v_lshrrev_b32_e32 v144, 16, v144
	v_and_or_b32 v55, v145, s0, v144
	v_bfe_u32 v105, v88, 16, 1
	v_bfe_u32 v106, v89, 16, 1
	v_add3_u32 v88, v88, v105, s1
	v_add3_u32 v89, v89, v106, s1
	v_lshrrev_b32_e32 v88, 16, v88
	v_and_or_b32 v72, v89, s0, v88
	v_bfe_u32 v105, v90, 16, 1
	v_bfe_u32 v106, v91, 16, 1
	v_add3_u32 v90, v90, v105, s1
	v_add3_u32 v91, v91, v106, s1
	v_lshrrev_b32_e32 v90, 16, v90
	v_and_or_b32 v73, v91, s0, v90
	v_bfe_u32 v105, v92, 16, 1
	v_bfe_u32 v106, v93, 16, 1
	v_add3_u32 v92, v92, v105, s1
	v_add3_u32 v93, v93, v106, s1
	v_lshrrev_b32_e32 v92, 16, v92
	v_and_or_b32 v74, v93, s0, v92
	v_bfe_u32 v105, v94, 16, 1
	v_bfe_u32 v106, v95, 16, 1
	v_add3_u32 v94, v94, v105, s1
	v_add3_u32 v95, v95, v106, s1
	v_lshrrev_b32_e32 v94, 16, v94
	v_and_or_b32 v75, v95, s0, v94
	v_bfe_u32 v105, v96, 16, 1
	v_bfe_u32 v106, v97, 16, 1
	v_add3_u32 v96, v96, v105, s1
	v_add3_u32 v97, v97, v106, s1
	v_lshrrev_b32_e32 v96, 16, v96
	v_and_or_b32 v76, v97, s0, v96
	v_bfe_u32 v105, v98, 16, 1
	v_bfe_u32 v106, v99, 16, 1
	v_add3_u32 v98, v98, v105, s1
	v_add3_u32 v99, v99, v106, s1
	v_lshrrev_b32_e32 v98, 16, v98
	v_and_or_b32 v77, v99, s0, v98
	v_bfe_u32 v105, v100, 16, 1
	v_bfe_u32 v106, v101, 16, 1
	v_add3_u32 v100, v100, v105, s1
	v_add3_u32 v101, v101, v106, s1
	v_lshrrev_b32_e32 v100, 16, v100
	v_and_or_b32 v78, v101, s0, v100
	v_bfe_u32 v105, v102, 16, 1
	v_bfe_u32 v106, v103, 16, 1
	v_add3_u32 v102, v102, v105, s1
	v_add3_u32 v103, v103, v106, s1
	v_lshrrev_b32_e32 v102, 16, v102
	v_and_or_b32 v79, v103, s0, v102
	v_bfe_u32 v105, v0, 16, 1
	v_bfe_u32 v106, v1, 16, 1
	v_add3_u32 v0, v0, v105, s1
	v_add3_u32 v1, v1, v106, s1
	v_lshrrev_b32_e32 v0, 16, v0
	v_and_or_b32 v80, v1, s0, v0
	v_bfe_u32 v105, v2, 16, 1
	v_bfe_u32 v106, v3, 16, 1
	v_add3_u32 v2, v2, v105, s1
	v_add3_u32 v3, v3, v106, s1
	v_lshrrev_b32_e32 v2, 16, v2
	v_and_or_b32 v81, v3, s0, v2
	v_bfe_u32 v105, v4, 16, 1
	v_bfe_u32 v106, v5, 16, 1
	v_add3_u32 v4, v4, v105, s1
	v_add3_u32 v5, v5, v106, s1
	v_lshrrev_b32_e32 v4, 16, v4
	v_and_or_b32 v82, v5, s0, v4
	v_bfe_u32 v105, v6, 16, 1
	v_bfe_u32 v106, v7, 16, 1
	v_add3_u32 v6, v6, v105, s1
	v_add3_u32 v7, v7, v106, s1
	v_lshrrev_b32_e32 v6, 16, v6
	v_and_or_b32 v83, v7, s0, v6
	v_bfe_u32 v105, v16, 16, 1
	v_bfe_u32 v106, v17, 16, 1
	v_add3_u32 v16, v16, v105, s1
	v_add3_u32 v17, v17, v106, s1
	v_lshrrev_b32_e32 v16, 16, v16
	v_and_or_b32 v84, v17, s0, v16
	v_bfe_u32 v105, v18, 16, 1
	v_bfe_u32 v106, v19, 16, 1
	v_add3_u32 v18, v18, v105, s1
	v_add3_u32 v19, v19, v106, s1
	v_lshrrev_b32_e32 v18, 16, v18
	v_and_or_b32 v85, v19, s0, v18
	v_bfe_u32 v105, v23, 16, 1
	v_bfe_u32 v106, v112, 16, 1
	v_add3_u32 v23, v23, v105, s1
	v_add3_u32 v112, v112, v106, s1
	v_lshrrev_b32_e32 v23, 16, v23
	v_and_or_b32 v86, v112, s0, v23
	v_bfe_u32 v105, v146, 16, 1
	v_bfe_u32 v106, v147, 16, 1
	v_add3_u32 v146, v146, v105, s1
	v_add3_u32 v147, v147, v106, s1
	v_lshrrev_b32_e32 v146, 16, v146
	v_and_or_b32 v87, v147, s0, v146
	s_add_u32 s0, s18, 0x800
	s_addc_u32 s1, s19, 0
	global_load_dword v14, v111, s[0:1]
	s_load_dwordx2 s[16:17], s[14:15], 0x130
	s_waitcnt lgkmcnt(0)
	s_add_u32 s0, s16, 0x800
	s_addc_u32 s1, s17, 0
	global_load_dword v15, v111, s[0:1]
	v_and_b32_e32 v112, 63, v210
	v_lshrrev_b32_e32 v146, 6, v210
	v_and_b32_e32 v146, 3, v146
	v_mul_u32_u24_e32 v146, 0x2200, v146
	v_lshl_add_u32 v106, v112, 1, v146
	v_and_b32_e32 v147, 15, v112
	v_lshrrev_b32_e32 v111, 4, v112
	v_mul_u32_u24_e32 v107, 0x90, v147
	v_lshl_add_u32 v107, v111, 4, v107
	v_add_u32_e32 v107, v146, v107
	v_add_u32_e32 v146, 0x8800, v146
	v_mul_u32_u24_e32 v108, 0x210, v111
	v_add_u32_e32 v108, v108, v147
	v_lshl_add_u32 v108, v108, 2, v146
	v_lshl_add_u32 v109, v112, 2, v146
	s_lshr_b32 s19, s12, 10
	s_and_b32 s17, s12, 127
	s_lshl_b32 s18, s19, 14
	s_lshl_b32 s20, s17, 7
	s_add_u32 s18, s18, s20
	s_lshl_b32 s20, s18, 10
	v_add_u32_e32 v105, s20, v104
	v_mov_b32_e32 v18, 0
	v_mov_b32_e32 v19, 0
	v_mov_b32_e32 v23, 0
	v_mov_b32_e32 v16, 0
	v_mov_b32_e32 v17, v105
	v_lshl_add_u32 v110, s19, 9, v110
	v_lshlrev_b32_e32 v110, 7, v110
	v_add_u32_e32 v110, s17, v110
	v_lshlrev_b32_e32 v110, 3, v110
	s_add_u32 s0, s2, 0x3158000
	s_addc_u32 s1, s3, 0
	global_load_dword v16, v110, s[0:1] offset:4
	s_add_u32 s10, s2, 0xf558000
	s_addc_u32 s11, s3, 0
	s_cmp_eq_u32 s17, 0
	s_cbranch_scc1 .Llrub2_nohist
	global_load_ushort v18, v105, s[6:7] offset:-1024
	global_load_ushort v19, v105, s[6:7] offset:-2048
	global_load_ushort v23, v105, s[6:7] offset:-3072
